# GEMM main loops: LDS-DMA loads use scalar base + 32-bit lane offset (no per-load 64-bit VALU add)
# baseline (speedup 1.0000x reference)
; #define PG8_STAGE(bufoff, gbase, voff) do { _Pragma("unroll") for (int _i = 0; _i < 2; ++_i) \
;         __builtin_amdgcn_global_load_lds((const unsigned*)((const char*)(gbase) + (voff)[_i]), (PG8_LAS unsigned*)(lds + (bufoff) + ldsw + _i * 8192), 16, 0, 0); } while (0)
; #define PG8_LDA(dst, b, h) do { _Pragma("unroll") for (int m = 0; m < 4; ++m) _Pragma("unroll") for (int k = 0; k < 2; ++k) dst[m][k] = *(const PG8_LAS bf16x8*)(lds + PG8_SA(b, h) + aoff + m * 2048 + k * 1024); } while (0)
; #define PG8_LDB(dst, b, h) do { _Pragma("unroll") for (int n = 0; n < 2; ++n) _Pragma("unroll") for (int k = 0; k < 2; ++k) dst[n][k] = *(const PG8_LAS bf16x8*)(lds + PG8_SB(b, h) + boff + n * 2048 + k * 1024); } while (0)
; #define PG8_MMA(ai, bj, At, Bt) do { __builtin_amdgcn_s_setprio(1); _Pragma("unroll") for (int m = 0; m < 4; ++m) _Pragma("unroll") for (int n = 0; n < 2; ++n) _Pragma("unroll") for (int k = 0; k < 2; ++k) \
;         acc[ai][bj][m][n] = __builtin_amdgcn_mfma_f32_16x16x32_bf16(Bt[n][k], At[m][k], acc[ai][bj][m][n], 0, 0, 0); __builtin_amdgcn_s_setprio(0); } while (0)
; #define PG8_WAIT_V(n) asm volatile("s_waitcnt vmcnt(" #n ")" ::: "memory")
; #define PG8_WAIT_L(n) asm volatile("s_waitcnt lgkmcnt(" #n ")" ::: "memory")
; #define PG8_BAR __builtin_amdgcn_s_barrier()
; #define PG8_SCHED __builtin_amdgcn_sched_barrier(0)
; template <class Epi, class Sched, bool ALIGN_EPI = false, bool SP2 = false>
; __device__ __forceinline__ void gemm_phase(PG8_LAS unsigned char* lds, const Gemm g, const Sched& S, const Epi& E) {
;     ...
;             const bool last = (t == nt - 2);
;             const char* a1 = cA + (size_t)(t + 1) * kstep;
;             const char* a2 = last ? nA : cA + (size_t)(t + 2) * kstep; const char* b2 = last ? nB : cB + (size_t)(t + 2) * kstep;
;             const char* a3 = a2 + kstep; const char* b3 = b2 + kstep;
;             if (last && has_next) S.a_ready(nxt);
;             if constexpr (SP2) {
;             PG8_LDB(B0, 0, 0); PG8_LDB(B1, 0, 1); PG8_SCHED; PG8_LDA(At, 0, 0); PG8_STAGE(PG8_SA(1, 1), a1 + hstep, voffA);
;             PG8_WAIT_V(8); PG8_WAIT_L(0); PG8_BAR; PG8_MMA(0, 0, At, B0); PG8_MMA(0, 1, At, B1); PG8_BAR; PG8_SCHED;
;             PG8_LDA(At, 0, 1); PG8_STAGE(PG8_SB(0, 0), b2, voffB); PG8_STAGE(PG8_SB(0, 1), b2 + hstep, voffB); PG8_STAGE(PG8_SA(0, 0), a2, voffA);
.LBB0_128:
	s_add_u32 s34, s8, 0xfff80080
	s_addc_u32 s35, s9, -1
	s_add_i32 s83, 0, 0x10000
	s_cmp_eq_u32 s82, 28
	s_cselect_b32 s41, s27, s35
	s_cselect_b32 s40, s78, s34
	v_add_u32_e32 v146, s83, v147
	s_cselect_b32 s35, s25, s81
	s_cselect_b32 s34, s79, s80
	s_add_i32 s84, 0, 0x14000
	ds_read_b128 v[142:145], v146
	ds_read_b128 v[162:165], v146 offset:1024
	ds_read_b128 v[166:169], v146 offset:2048
	ds_read_b128 v[170:173], v146 offset:3072
	v_add_u32_e32 v146, s84, v147
	ds_read_b128 v[174:177], v146
	ds_read_b128 v[178:181], v146 offset:1024
	ds_read_b128 v[182:185], v146 offset:2048
	ds_read_b128 v[186:189], v146 offset:3072
	s_add_i32 m0, s49, 0xc000
	ds_read_b128 v[190:193], v152
	ds_read_b128 v[194:197], v152 offset:1024
	ds_read_b128 v[198:201], v152 offset:2048
	ds_read_b128 v[202:205], v152 offset:3072
	ds_read_b128 v[230:233], v152 offset:4096
	ds_read_b128 v[234:237], v152 offset:5120
	ds_read_b128 v[238:241], v152 offset:6144
	ds_read_b128 v[242:245], v152 offset:7168
	global_load_lds_dwordx4 v140, s[8:9]
	s_add_i32 m0, s49, 0xe000
	s_nop 0
	global_load_lds_dwordx4 v138, s[8:9]
	s_waitcnt vmcnt(8)
	s_waitcnt lgkmcnt(0)
	s_barrier
	s_setprio 1
	s_waitcnt lgkmcnt(0)
	v_mfma_f32_16x16x32_bf16 v[130:133], v[142:145], v[190:193], v[130:133]
	v_mfma_f32_16x16x32_bf16 v[122:125], v[166:169], v[190:193], v[122:125]
	v_mfma_f32_16x16x32_bf16 v[114:117], v[142:145], v[198:201], v[114:117]
	v_mfma_f32_16x16x32_bf16 v[106:109], v[166:169], v[198:201], v[106:109]
	v_mfma_f32_16x16x32_bf16 v[98:101], v[142:145], v[230:233], v[98:101]
	v_mfma_f32_16x16x32_bf16 v[90:93], v[166:169], v[230:233], v[90:93]
	v_mfma_f32_16x16x32_bf16 v[82:85], v[142:145], v[238:241], v[82:85]
	v_mfma_f32_16x16x32_bf16 v[74:77], v[166:169], v[238:241], v[74:77]
	v_mfma_f32_16x16x32_bf16 v[130:133], v[162:165], v[194:197], v[130:133]
	v_mfma_f32_16x16x32_bf16 v[122:125], v[170:173], v[194:197], v[122:125]
	v_mfma_f32_16x16x32_bf16 v[114:117], v[162:165], v[202:205], v[114:117]
	v_mfma_f32_16x16x32_bf16 v[106:109], v[170:173], v[202:205], v[106:109]
	v_mfma_f32_16x16x32_bf16 v[98:101], v[162:165], v[234:237], v[98:101]
	v_mfma_f32_16x16x32_bf16 v[90:93], v[170:173], v[234:237], v[90:93]
	v_mfma_f32_16x16x32_bf16 v[82:85], v[162:165], v[242:245], v[82:85]
	v_mfma_f32_16x16x32_bf16 v[74:77], v[170:173], v[242:245], v[74:77]
	s_setprio 0
	s_setprio 1
	v_mfma_f32_16x16x32_bf16 v[126:129], v[174:177], v[190:193], v[126:129]
	v_mfma_f32_16x16x32_bf16 v[118:121], v[182:185], v[190:193], v[118:121]
	v_mfma_f32_16x16x32_bf16 v[110:113], v[174:177], v[198:201], v[110:113]
	v_mfma_f32_16x16x32_bf16 v[102:105], v[182:185], v[198:201], v[102:105]
	v_mfma_f32_16x16x32_bf16 v[94:97], v[174:177], v[230:233], v[94:97]
	v_mfma_f32_16x16x32_bf16 v[86:89], v[182:185], v[230:233], v[86:89]
	v_mfma_f32_16x16x32_bf16 v[78:81], v[174:177], v[238:241], v[78:81]
	v_mfma_f32_16x16x32_bf16 v[70:73], v[182:185], v[238:241], v[70:73]
	v_mfma_f32_16x16x32_bf16 v[126:129], v[178:181], v[194:197], v[126:129]
	v_mfma_f32_16x16x32_bf16 v[118:121], v[186:189], v[194:197], v[118:121]
	v_mfma_f32_16x16x32_bf16 v[110:113], v[178:181], v[202:205], v[110:113]
	v_mfma_f32_16x16x32_bf16 v[102:105], v[186:189], v[202:205], v[102:105]
	v_mfma_f32_16x16x32_bf16 v[94:97], v[178:181], v[234:237], v[94:97]
	v_mfma_f32_16x16x32_bf16 v[86:89], v[186:189], v[234:237], v[86:89]
	v_mfma_f32_16x16x32_bf16 v[78:81], v[178:181], v[242:245], v[78:81]
	v_mfma_f32_16x16x32_bf16 v[70:73], v[186:189], v[242:245], v[70:73]
	s_setprio 0
	s_barrier
	s_add_i32 s83, s83, s48
	s_mov_b32 m0, s83
	ds_read_b128 v[190:193], v152 offset:16384
	ds_read_b128 v[194:197], v152 offset:17408
	ds_read_b128 v[198:201], v152 offset:18432
	ds_read_b128 v[202:205], v152 offset:19456
	ds_read_b128 v[230:233], v152 offset:20480
	ds_read_b128 v[234:237], v152 offset:21504
	ds_read_b128 v[238:241], v152 offset:22528
	ds_read_b128 v[242:245], v152 offset:23552
	global_load_lds_dwordx4 v2, s[34:35]
	s_add_i32 m0, s83, 0x2000
	s_add_u32 s86, s34, 0x80000
	s_addc_u32 s87, s35, 0
	s_add_i32 s83, s84, s48
	global_load_lds_dwordx4 v0, s[34:35]
	s_mov_b32 m0, s83
	v_lshl_add_u64 v[250:251], s[40:41], 0, v[134:135]
	global_load_lds_dwordx4 v2, s[86:87]
	s_add_i32 m0, s83, 0x2000
	s_nop 0
	global_load_lds_dwordx4 v0, s[86:87]
	v_lshl_add_u64 v[248:249], s[40:41], 0, v[136:137]
	s_mov_b32 m0, s49
	s_nop 0
	global_load_lds_dwordx4 v136, s[40:41]
	s_mov_b32 m0, s51
	s_nop 0
	global_load_lds_dwordx4 v134, s[40:41]
	s_waitcnt vmcnt(8)
	s_waitcnt lgkmcnt(0)
	s_barrier
; #define PG8_STAGE(bufoff, gbase, voff) do { _Pragma("unroll") for (int _i = 0; _i < 2; ++_i) \
;         __builtin_amdgcn_global_load_lds((const unsigned*)((const char*)(gbase) + (voff)[_i]), (PG8_LAS unsigned*)(lds + (bufoff) + ldsw + _i * 8192), 16, 0, 0); } while (0)
; #define PG8_LDA(dst, b, h) do { _Pragma("unroll") for (int m = 0; m < 4; ++m) _Pragma("unroll") for (int k = 0; k < 2; ++k) dst[m][k] = *(const PG8_LAS bf16x8*)(lds + PG8_SA(b, h) + aoff + m * 2048 + k * 1024); } while (0)
; #define PG8_LDB(dst, b, h) do { _Pragma("unroll") for (int n = 0; n < 2; ++n) _Pragma("unroll") for (int k = 0; k < 2; ++k) dst[n][k] = *(const PG8_LAS bf16x8*)(lds + PG8_SB(b, h) + boff + n * 2048 + k * 1024); } while (0)
; #define PG8_MMA(ai, bj, At, Bt) do { __builtin_amdgcn_s_setprio(1); _Pragma("unroll") for (int m = 0; m < 4; ++m) _Pragma("unroll") for (int n = 0; n < 2; ++n) _Pragma("unroll") for (int k = 0; k < 2; ++k) \
;         acc[ai][bj][m][n] = __builtin_amdgcn_mfma_f32_16x16x32_bf16(Bt[n][k], At[m][k], acc[ai][bj][m][n], 0, 0, 0); __builtin_amdgcn_s_setprio(0); } while (0)
; #define PG8_WAIT_V(n) asm volatile("s_waitcnt vmcnt(" #n ")" ::: "memory")
; #define PG8_WAIT_L(n) asm volatile("s_waitcnt lgkmcnt(" #n ")" ::: "memory")
; #define PG8_BAR __builtin_amdgcn_s_barrier()
; #define PG8_SCHED __builtin_amdgcn_sched_barrier(0)
; template <class Epi, class Sched, bool ALIGN_EPI = false, bool SP2 = false>
; __device__ __forceinline__ void gemm_phase(PG8_LAS unsigned char* lds, const Gemm g, const Sched& S, const Epi& E) {
;     ...
;             PG8_WAIT_V(8); PG8_WAIT_L(0); PG8_BAR; PG8_MMA(1, 0, At, B0); PG8_MMA(1, 1, At, B1); PG8_BAR; PG8_SCHED;
;             PG8_LDB(B0, 1, 0); PG8_LDB(B1, 1, 1); PG8_SCHED; PG8_LDA(At, 1, 0); PG8_STAGE(PG8_SA(0, 1), a2 + hstep, voffA);
;             PG8_WAIT_V(8); PG8_WAIT_L(0); PG8_BAR; PG8_MMA(0, 0, At, B0); PG8_MMA(0, 1, At, B1); PG8_BAR; PG8_SCHED;
	s_setprio 1
	s_waitcnt lgkmcnt(0)
	v_mfma_f32_16x16x32_bf16 v[66:69], v[142:145], v[190:193], v[66:69]
	v_mfma_f32_16x16x32_bf16 v[58:61], v[166:169], v[190:193], v[58:61]
	v_mfma_f32_16x16x32_bf16 v[50:53], v[142:145], v[198:201], v[50:53]
	v_mfma_f32_16x16x32_bf16 v[42:45], v[166:169], v[198:201], v[42:45]
	v_mfma_f32_16x16x32_bf16 v[34:37], v[142:145], v[230:233], v[34:37]
	v_mfma_f32_16x16x32_bf16 v[26:29], v[166:169], v[230:233], v[26:29]
	v_mfma_f32_16x16x32_bf16 v[18:21], v[142:145], v[238:241], v[18:21]
	v_mfma_f32_16x16x32_bf16 v[10:13], v[166:169], v[238:241], v[10:13]
	v_mfma_f32_16x16x32_bf16 v[66:69], v[162:165], v[194:197], v[66:69]
	v_mfma_f32_16x16x32_bf16 v[58:61], v[170:173], v[194:197], v[58:61]
	v_mfma_f32_16x16x32_bf16 v[50:53], v[162:165], v[202:205], v[50:53]
	v_mfma_f32_16x16x32_bf16 v[42:45], v[170:173], v[202:205], v[42:45]
	v_mfma_f32_16x16x32_bf16 v[34:37], v[162:165], v[234:237], v[34:37]
	v_mfma_f32_16x16x32_bf16 v[26:29], v[170:173], v[234:237], v[26:29]
	v_mfma_f32_16x16x32_bf16 v[18:21], v[162:165], v[242:245], v[18:21]
	v_mfma_f32_16x16x32_bf16 v[10:13], v[170:173], v[242:245], v[10:13]
	s_setprio 0
	s_setprio 1
	v_mfma_f32_16x16x32_bf16 v[62:65], v[174:177], v[190:193], v[62:65]
	v_mfma_f32_16x16x32_bf16 v[54:57], v[182:185], v[190:193], v[54:57]
	v_mfma_f32_16x16x32_bf16 v[46:49], v[174:177], v[198:201], v[46:49]
	v_mfma_f32_16x16x32_bf16 v[38:41], v[182:185], v[198:201], v[38:41]
	v_mfma_f32_16x16x32_bf16 v[30:33], v[174:177], v[230:233], v[30:33]
	v_mfma_f32_16x16x32_bf16 v[22:25], v[182:185], v[230:233], v[22:25]
	v_mfma_f32_16x16x32_bf16 v[14:17], v[174:177], v[238:241], v[14:17]
	v_mfma_f32_16x16x32_bf16 v[6:9], v[182:185], v[238:241], v[6:9]
	v_mfma_f32_16x16x32_bf16 v[62:65], v[178:181], v[194:197], v[62:65]
	v_mfma_f32_16x16x32_bf16 v[54:57], v[186:189], v[194:197], v[54:57]
	v_mfma_f32_16x16x32_bf16 v[46:49], v[178:181], v[202:205], v[46:49]
	v_mfma_f32_16x16x32_bf16 v[38:41], v[186:189], v[202:205], v[38:41]
	v_mfma_f32_16x16x32_bf16 v[30:33], v[178:181], v[234:237], v[30:33]
	v_mfma_f32_16x16x32_bf16 v[22:25], v[186:189], v[234:237], v[22:25]
	v_mfma_f32_16x16x32_bf16 v[14:17], v[178:181], v[242:245], v[14:17]
	v_mfma_f32_16x16x32_bf16 v[6:9], v[186:189], v[242:245], v[6:9]
	s_setprio 0
	s_barrier
	s_add_i32 s83, 0, 0x18000
	v_add_u32_e32 v146, s83, v147
	s_add_i32 s84, 0, 0x1c000
	ds_read_b128 v[142:145], v146
	ds_read_b128 v[162:165], v146 offset:1024
	ds_read_b128 v[166:169], v146 offset:2048
	ds_read_b128 v[170:173], v146 offset:3072
	v_add_u32_e32 v146, s84, v147
	ds_read_b128 v[174:177], v146
	ds_read_b128 v[178:181], v146 offset:1024
	ds_read_b128 v[182:185], v146 offset:2048
	ds_read_b128 v[186:189], v146 offset:3072
	s_add_u32 s40, s40, 0x80000
	s_addc_u32 s41, s41, 0
	s_mov_b32 m0, s52
	ds_read_b128 v[190:193], v152 offset:32768
	ds_read_b128 v[194:197], v152 offset:33792
	ds_read_b128 v[198:201], v152 offset:34816
	ds_read_b128 v[202:205], v152 offset:35840
	ds_read_b128 v[230:233], v152 offset:36864
	ds_read_b128 v[234:237], v152 offset:37888
	ds_read_b128 v[238:241], v152 offset:38912
	ds_read_b128 v[242:245], v152 offset:39936
	global_load_lds_dwordx4 v136, s[40:41]
	s_mov_b32 m0, s53
	s_nop 0
	global_load_lds_dwordx4 v134, s[40:41]
	s_waitcnt vmcnt(8)
	s_waitcnt lgkmcnt(0)
	s_barrier
	s_setprio 1
	s_waitcnt lgkmcnt(0)
	v_mfma_f32_16x16x32_bf16 v[130:133], v[142:145], v[190:193], v[130:133]
	v_mfma_f32_16x16x32_bf16 v[122:125], v[166:169], v[190:193], v[122:125]
	v_mfma_f32_16x16x32_bf16 v[114:117], v[142:145], v[198:201], v[114:117]
	v_mfma_f32_16x16x32_bf16 v[106:109], v[166:169], v[198:201], v[106:109]
	v_mfma_f32_16x16x32_bf16 v[98:101], v[142:145], v[230:233], v[98:101]
	v_mfma_f32_16x16x32_bf16 v[90:93], v[166:169], v[230:233], v[90:93]
	v_mfma_f32_16x16x32_bf16 v[82:85], v[142:145], v[238:241], v[82:85]
	v_mfma_f32_16x16x32_bf16 v[74:77], v[166:169], v[238:241], v[74:77]
	v_mfma_f32_16x16x32_bf16 v[130:133], v[162:165], v[194:197], v[130:133]
	v_mfma_f32_16x16x32_bf16 v[122:125], v[170:173], v[194:197], v[122:125]
	v_mfma_f32_16x16x32_bf16 v[114:117], v[162:165], v[202:205], v[114:117]
	v_mfma_f32_16x16x32_bf16 v[106:109], v[170:173], v[202:205], v[106:109]
	v_mfma_f32_16x16x32_bf16 v[98:101], v[162:165], v[234:237], v[98:101]
	v_mfma_f32_16x16x32_bf16 v[90:93], v[170:173], v[234:237], v[90:93]
	v_mfma_f32_16x16x32_bf16 v[82:85], v[162:165], v[242:245], v[82:85]
	v_mfma_f32_16x16x32_bf16 v[74:77], v[170:173], v[242:245], v[74:77]
	s_setprio 0
	s_setprio 1
	v_mfma_f32_16x16x32_bf16 v[126:129], v[174:177], v[190:193], v[126:129]
	v_mfma_f32_16x16x32_bf16 v[118:121], v[182:185], v[190:193], v[118:121]
	v_mfma_f32_16x16x32_bf16 v[110:113], v[174:177], v[198:201], v[110:113]
	v_mfma_f32_16x16x32_bf16 v[102:105], v[182:185], v[198:201], v[102:105]
	v_mfma_f32_16x16x32_bf16 v[94:97], v[174:177], v[230:233], v[94:97]
	v_mfma_f32_16x16x32_bf16 v[86:89], v[182:185], v[230:233], v[86:89]
	v_mfma_f32_16x16x32_bf16 v[78:81], v[174:177], v[238:241], v[78:81]
	v_mfma_f32_16x16x32_bf16 v[70:73], v[182:185], v[238:241], v[70:73]
	v_mfma_f32_16x16x32_bf16 v[126:129], v[178:181], v[194:197], v[126:129]
	v_mfma_f32_16x16x32_bf16 v[118:121], v[186:189], v[194:197], v[118:121]
	v_mfma_f32_16x16x32_bf16 v[110:113], v[178:181], v[202:205], v[110:113]
	v_mfma_f32_16x16x32_bf16 v[102:105], v[186:189], v[202:205], v[102:105]
	v_mfma_f32_16x16x32_bf16 v[94:97], v[178:181], v[234:237], v[94:97]
	v_mfma_f32_16x16x32_bf16 v[86:89], v[186:189], v[234:237], v[86:89]
	v_mfma_f32_16x16x32_bf16 v[78:81], v[178:181], v[242:245], v[78:81]
	v_mfma_f32_16x16x32_bf16 v[70:73], v[186:189], v[242:245], v[70:73]
	s_setprio 0
	s_barrier
; #define PG8_STAGE(bufoff, gbase, voff) do { _Pragma("unroll") for (int _i = 0; _i < 2; ++_i) \
;         __builtin_amdgcn_global_load_lds((const unsigned*)((const char*)(gbase) + (voff)[_i]), (PG8_LAS unsigned*)(lds + (bufoff) + ldsw + _i * 8192), 16, 0, 0); } while (0)
; #define PG8_LDA(dst, b, h) do { _Pragma("unroll") for (int m = 0; m < 4; ++m) _Pragma("unroll") for (int k = 0; k < 2; ++k) dst[m][k] = *(const PG8_LAS bf16x8*)(lds + PG8_SA(b, h) + aoff + m * 2048 + k * 1024); } while (0)
; #define PG8_MMA(ai, bj, At, Bt) do { __builtin_amdgcn_s_setprio(1); _Pragma("unroll") for (int m = 0; m < 4; ++m) _Pragma("unroll") for (int n = 0; n < 2; ++n) _Pragma("unroll") for (int k = 0; k < 2; ++k) \
;         acc[ai][bj][m][n] = __builtin_amdgcn_mfma_f32_16x16x32_bf16(Bt[n][k], At[m][k], acc[ai][bj][m][n], 0, 0, 0); __builtin_amdgcn_s_setprio(0); } while (0)
; #define PG8_WAIT_V(n) asm volatile("s_waitcnt vmcnt(" #n ")" ::: "memory")
; #define PG8_WAIT_L(n) asm volatile("s_waitcnt lgkmcnt(" #n ")" ::: "memory")
; #define PG8_BAR __builtin_amdgcn_s_barrier()
; #define PG8_SCHED __builtin_amdgcn_sched_barrier(0)
; template <class Epi, class Sched, bool ALIGN_EPI = false, bool SP2 = false>
; __device__ __forceinline__ void gemm_phase(PG8_LAS unsigned char* lds, const Gemm g, const Sched& S, const Epi& E) {
;     ...
;         for (int t = 0; t < nt; t += 2) {
;             const bool last = (t == nt - 2);
;             const char* a1 = cA + (size_t)(t + 1) * kstep;
;             const char* a2 = last ? nA : cA + (size_t)(t + 2) * kstep; const char* b2 = last ? nB : cB + (size_t)(t + 2) * kstep;
;     ...
;             PG8_LDA(At, 1, 1); PG8_STAGE(PG8_SB(1, 0), b3, voffB); PG8_STAGE(PG8_SB(1, 1), b3 + hstep, voffB); PG8_STAGE(PG8_SA(1, 0), a3, voffA);
;             PG8_WAIT_V(8); PG8_WAIT_L(0); PG8_BAR; PG8_MMA(1, 0, At, B0); PG8_MMA(1, 1, At, B1); PG8_BAR; PG8_SCHED;
	s_add_u32 vcc_lo, s34, s2
	s_addc_u32 vcc_hi, s35, s3
	s_add_i32 s40, s83, s48
	s_mov_b32 m0, s40
	ds_read_b128 v[190:193], v152 offset:49152
	ds_read_b128 v[194:197], v152 offset:50176
	ds_read_b128 v[198:201], v152 offset:51200
	ds_read_b128 v[202:205], v152 offset:52224
	ds_read_b128 v[230:233], v152 offset:53248
	ds_read_b128 v[234:237], v152 offset:54272
	ds_read_b128 v[238:241], v152 offset:55296
	ds_read_b128 v[242:245], v152 offset:56320
	global_load_lds_dwordx4 v2, vcc
	s_add_i32 m0, s40, 0x2000
	s_add_u32 s34, s34, 0x80080
	s_addc_u32 s35, s35, 0
	s_add_i32 s40, s84, s48
	global_load_lds_dwordx4 v0, vcc
	s_mov_b32 m0, s40
	s_nop 0
	global_load_lds_dwordx4 v2, s[34:35]
	s_add_i32 m0, s40, 0x2000
	s_nop 0
	global_load_lds_dwordx4 v0, s[34:35]
	v_lshl_add_u64 v[158:159], v[248:249], 0, s[2:3]
	s_mov_b32 m0, s66
	s_nop 0
	global_load_lds_dwordx4 v[158:159], off
	v_lshl_add_u64 v[158:159], v[250:251], 0, s[2:3]
	s_mov_b32 m0, s67
	s_nop 0
	global_load_lds_dwordx4 v[158:159], off
	s_waitcnt vmcnt(8)
	s_waitcnt lgkmcnt(0)
	s_barrier
	s_setprio 1
	s_waitcnt lgkmcnt(0)
	v_mfma_f32_16x16x32_bf16 v[66:69], v[142:145], v[190:193], v[66:69]
	v_mfma_f32_16x16x32_bf16 v[58:61], v[166:169], v[190:193], v[58:61]
	v_mfma_f32_16x16x32_bf16 v[50:53], v[142:145], v[198:201], v[50:53]
	v_mfma_f32_16x16x32_bf16 v[42:45], v[166:169], v[198:201], v[42:45]
	v_mfma_f32_16x16x32_bf16 v[34:37], v[142:145], v[230:233], v[34:37]
	v_mfma_f32_16x16x32_bf16 v[26:29], v[166:169], v[230:233], v[26:29]
	v_mfma_f32_16x16x32_bf16 v[18:21], v[142:145], v[238:241], v[18:21]
	v_mfma_f32_16x16x32_bf16 v[10:13], v[166:169], v[238:241], v[10:13]
	v_mfma_f32_16x16x32_bf16 v[66:69], v[162:165], v[194:197], v[66:69]
	v_mfma_f32_16x16x32_bf16 v[58:61], v[170:173], v[194:197], v[58:61]
	v_mfma_f32_16x16x32_bf16 v[50:53], v[162:165], v[202:205], v[50:53]
	v_mfma_f32_16x16x32_bf16 v[42:45], v[170:173], v[202:205], v[42:45]
	v_mfma_f32_16x16x32_bf16 v[34:37], v[162:165], v[234:237], v[34:37]
	v_mfma_f32_16x16x32_bf16 v[26:29], v[170:173], v[234:237], v[26:29]
	v_mfma_f32_16x16x32_bf16 v[18:21], v[162:165], v[242:245], v[18:21]
	v_mfma_f32_16x16x32_bf16 v[10:13], v[170:173], v[242:245], v[10:13]
	s_setprio 0
	s_setprio 1
	v_mfma_f32_16x16x32_bf16 v[62:65], v[174:177], v[190:193], v[62:65]
	v_mfma_f32_16x16x32_bf16 v[54:57], v[182:185], v[190:193], v[54:57]
	v_mfma_f32_16x16x32_bf16 v[46:49], v[174:177], v[198:201], v[46:49]
	v_mfma_f32_16x16x32_bf16 v[38:41], v[182:185], v[198:201], v[38:41]
	v_mfma_f32_16x16x32_bf16 v[30:33], v[174:177], v[230:233], v[30:33]
	v_mfma_f32_16x16x32_bf16 v[22:25], v[182:185], v[230:233], v[22:25]
	v_mfma_f32_16x16x32_bf16 v[14:17], v[174:177], v[238:241], v[14:17]
	v_mfma_f32_16x16x32_bf16 v[6:9], v[182:185], v[238:241], v[6:9]
	v_mfma_f32_16x16x32_bf16 v[62:65], v[178:181], v[194:197], v[62:65]
	v_mfma_f32_16x16x32_bf16 v[54:57], v[186:189], v[194:197], v[54:57]
	v_mfma_f32_16x16x32_bf16 v[46:49], v[178:181], v[202:205], v[46:49]
	v_mfma_f32_16x16x32_bf16 v[38:41], v[186:189], v[202:205], v[38:41]
	v_mfma_f32_16x16x32_bf16 v[30:33], v[178:181], v[234:237], v[30:33]
	v_mfma_f32_16x16x32_bf16 v[22:25], v[186:189], v[234:237], v[22:25]
	v_mfma_f32_16x16x32_bf16 v[14:17], v[178:181], v[242:245], v[14:17]
	v_mfma_f32_16x16x32_bf16 v[6:9], v[186:189], v[242:245], v[6:9]
	s_setprio 0
	s_barrier
	s_add_i32 s82, s82, 2
	s_add_u32 s80, s80, 0x100
	s_addc_u32 s81, s81, 0
	s_add_u32 s8, s8, 0x100
	s_addc_u32 s9, s9, 0
	s_cmp_gt_u32 s82, 29
	s_cbranch_scc0 .LBB0_128
	s_and_b64 vcc, exec, s[22:23]
	s_cbranch_vccz .LBB0_131
	s_barrier

; #define PG8_STAGE(bufoff, gbase, voff) do { _Pragma("unroll") for (int _i = 0; _i < 2; ++_i) \
;         __builtin_amdgcn_global_load_lds((const unsigned*)((const char*)(gbase) + (voff)[_i]), (PG8_LAS unsigned*)(lds + (bufoff) + ldsw + _i * 8192), 16, 0, 0); } while (0)
; #define PG8_LDA(dst, b, h) do { _Pragma("unroll") for (int m = 0; m < 4; ++m) _Pragma("unroll") for (int k = 0; k < 2; ++k) dst[m][k] = *(const PG8_LAS bf16x8*)(lds + PG8_SA(b, h) + aoff + m * 2048 + k * 1024); } while (0)
; #define PG8_LDB(dst, b, h) do { _Pragma("unroll") for (int n = 0; n < 2; ++n) _Pragma("unroll") for (int k = 0; k < 2; ++k) dst[n][k] = *(const PG8_LAS bf16x8*)(lds + PG8_SB(b, h) + boff + n * 2048 + k * 1024); } while (0)
; #define PG8_MMA(ai, bj, At, Bt) do { __builtin_amdgcn_s_setprio(1); _Pragma("unroll") for (int m = 0; m < 4; ++m) _Pragma("unroll") for (int n = 0; n < 2; ++n) _Pragma("unroll") for (int k = 0; k < 2; ++k) \
;         acc[ai][bj][m][n] = __builtin_amdgcn_mfma_f32_16x16x32_bf16(Bt[n][k], At[m][k], acc[ai][bj][m][n], 0, 0, 0); __builtin_amdgcn_s_setprio(0); } while (0)
; #define PG8_WAIT_V(n) asm volatile("s_waitcnt vmcnt(" #n ")" ::: "memory")
; #define PG8_WAIT_L(n) asm volatile("s_waitcnt lgkmcnt(" #n ")" ::: "memory")
; #define PG8_BAR __builtin_amdgcn_s_barrier()
; #define PG8_SCHED __builtin_amdgcn_sched_barrier(0)
; template <class Epi, class Sched, bool ALIGN_EPI = false, bool SP2 = false>
; __device__ __forceinline__ void gemm_phase(PG8_LAS unsigned char* lds, const Gemm g, const Sched& S, const Epi& E) {
;     ...
;             const bool last = (t == nt - 2);
;             const char* a1 = cA + (size_t)(t + 1) * kstep;
;             const char* a2 = last ? nA : cA + (size_t)(t + 2) * kstep; const char* b2 = last ? nB : cB + (size_t)(t + 2) * kstep;
;             const char* a3 = a2 + kstep; const char* b3 = b2 + kstep;
;             if (last && has_next) S.a_ready(nxt);
;             if constexpr (SP2) {
;             PG8_LDB(B0, 0, 0); PG8_LDB(B1, 0, 1); PG8_SCHED; PG8_LDA(At, 0, 0); PG8_STAGE(PG8_SA(1, 1), a1 + hstep, voffA);
;             PG8_WAIT_V(8); PG8_WAIT_L(0); PG8_BAR; PG8_MMA(0, 0, At, B0); PG8_MMA(0, 1, At, B1); PG8_BAR; PG8_SCHED;
;             PG8_LDA(At, 0, 1); PG8_STAGE(PG8_SB(0, 0), b2, voffB); PG8_STAGE(PG8_SB(0, 1), b2 + hstep, voffB); PG8_STAGE(PG8_SA(0, 0), a2, voffA);
.LBB0_235:
	s_add_u32 s10, s30, 0x100
	s_addc_u32 s11, s31, 0
	s_add_i32 s84, 0, 0x10000
	s_cmpk_eq_i32 s83, 0x54
	s_cselect_b32 s41, s29, s11
	s_cselect_b32 s40, s28, s10
	s_cselect_b32 s35, s1, s82
	s_cselect_b32 s34, s0, s81
	s_add_i32 s86, 0, 0x14000
	v_add_u32_e32 v62, s84, v152
	v_add_u32_e32 v158, s86, v152
	ds_read_b128 v[50:53], v62
	ds_read_b128 v[54:57], v62 offset:1024
	ds_read_b128 v[58:61], v62 offset:2048
	ds_read_b128 v[62:65], v62 offset:3072
	ds_read_b128 v[166:169], v158
	ds_read_b128 v[170:173], v158 offset:1024
	ds_read_b128 v[178:181], v158 offset:2048
	ds_read_b128 v[182:185], v158 offset:3072
	s_add_i32 m0, s51, 0xc000
	ds_read_b128 v[186:189], v177
	ds_read_b128 v[190:193], v177 offset:1024
	ds_read_b128 v[194:197], v177 offset:2048
	ds_read_b128 v[198:201], v177 offset:3072
	ds_read_b128 v[202:205], v177 offset:4096
	ds_read_b128 v[230:233], v177 offset:5120
	ds_read_b128 v[234:237], v177 offset:6144
	ds_read_b128 v[238:241], v177 offset:7168
	global_load_lds_dwordx4 v164, s[30:31]
	s_add_i32 m0, s51, 0xe000
	s_nop 0
	global_load_lds_dwordx4 v162, s[30:31]
	s_waitcnt vmcnt(8)
	s_waitcnt lgkmcnt(0)
	s_barrier
	s_setprio 1
	s_waitcnt lgkmcnt(0)
	v_mfma_f32_16x16x32_bf16 v[146:149], v[50:53], v[186:189], v[146:149]
	v_mfma_f32_16x16x32_bf16 v[142:145], v[58:61], v[186:189], v[142:145]
	v_mfma_f32_16x16x32_bf16 v[130:133], v[50:53], v[194:197], v[130:133]
	v_mfma_f32_16x16x32_bf16 v[126:129], v[58:61], v[194:197], v[126:129]
	v_mfma_f32_16x16x32_bf16 v[114:117], v[50:53], v[202:205], v[114:117]
	v_mfma_f32_16x16x32_bf16 v[110:113], v[58:61], v[202:205], v[110:113]
	v_mfma_f32_16x16x32_bf16 v[98:101], v[50:53], v[234:237], v[98:101]
	v_mfma_f32_16x16x32_bf16 v[94:97], v[58:61], v[234:237], v[94:97]
	v_mfma_f32_16x16x32_bf16 v[146:149], v[54:57], v[190:193], v[146:149]
	v_mfma_f32_16x16x32_bf16 v[142:145], v[62:65], v[190:193], v[142:145]
	v_mfma_f32_16x16x32_bf16 v[130:133], v[54:57], v[198:201], v[130:133]
	v_mfma_f32_16x16x32_bf16 v[126:129], v[62:65], v[198:201], v[126:129]
	v_mfma_f32_16x16x32_bf16 v[114:117], v[54:57], v[230:233], v[114:117]
	v_mfma_f32_16x16x32_bf16 v[110:113], v[62:65], v[230:233], v[110:113]
	v_mfma_f32_16x16x32_bf16 v[98:101], v[54:57], v[238:241], v[98:101]
	v_mfma_f32_16x16x32_bf16 v[94:97], v[62:65], v[238:241], v[94:97]
	s_setprio 0
	s_setprio 1
	v_mfma_f32_16x16x32_bf16 v[138:141], v[166:169], v[186:189], v[138:141]
	v_mfma_f32_16x16x32_bf16 v[134:137], v[178:181], v[186:189], v[134:137]
	v_mfma_f32_16x16x32_bf16 v[122:125], v[166:169], v[194:197], v[122:125]
	v_mfma_f32_16x16x32_bf16 v[118:121], v[178:181], v[194:197], v[118:121]
	v_mfma_f32_16x16x32_bf16 v[106:109], v[166:169], v[202:205], v[106:109]
	v_mfma_f32_16x16x32_bf16 v[102:105], v[178:181], v[202:205], v[102:105]
	v_mfma_f32_16x16x32_bf16 v[90:93], v[166:169], v[234:237], v[90:93]
	v_mfma_f32_16x16x32_bf16 v[86:89], v[178:181], v[234:237], v[86:89]
	v_mfma_f32_16x16x32_bf16 v[138:141], v[170:173], v[190:193], v[138:141]
	v_mfma_f32_16x16x32_bf16 v[134:137], v[182:185], v[190:193], v[134:137]
	v_mfma_f32_16x16x32_bf16 v[122:125], v[170:173], v[198:201], v[122:125]
	v_mfma_f32_16x16x32_bf16 v[118:121], v[182:185], v[198:201], v[118:121]
	v_mfma_f32_16x16x32_bf16 v[106:109], v[170:173], v[230:233], v[106:109]
	v_mfma_f32_16x16x32_bf16 v[102:105], v[182:185], v[230:233], v[102:105]
	v_mfma_f32_16x16x32_bf16 v[90:93], v[170:173], v[238:241], v[90:93]
	v_mfma_f32_16x16x32_bf16 v[86:89], v[182:185], v[238:241], v[86:89]
	s_setprio 0
	s_barrier
	s_add_i32 s30, s84, s49
	s_mov_b32 m0, s30
	ds_read_b128 v[186:189], v177 offset:16384
	ds_read_b128 v[190:193], v177 offset:17408
	ds_read_b128 v[194:197], v177 offset:18432
	ds_read_b128 v[198:201], v177 offset:19456
	ds_read_b128 v[202:205], v177 offset:20480
	ds_read_b128 v[230:233], v177 offset:21504
	ds_read_b128 v[234:237], v177 offset:22528
	ds_read_b128 v[238:241], v177 offset:23552
	global_load_lds_dwordx4 v2, s[34:35]
	s_add_i32 m0, s30, 0x2000
	s_add_u32 s30, s34, 0x160000
	s_addc_u32 s31, s35, 0
	s_add_i32 s84, s86, s49
	global_load_lds_dwordx4 v0, s[34:35]
	s_mov_b32 m0, s84
	s_nop 0
	global_load_lds_dwordx4 v2, s[30:31]
	s_add_i32 m0, s84, 0x2000
	s_nop 0
	global_load_lds_dwordx4 v0, s[30:31]
	s_mov_b32 m0, s51
	s_nop 0
	global_load_lds_dwordx4 v2, s[40:41]
	s_mov_b32 m0, s52
	s_nop 0
	global_load_lds_dwordx4 v0, s[40:41]
	s_waitcnt vmcnt(8)
	s_waitcnt lgkmcnt(0)
	s_barrier
	s_setprio 1
	s_waitcnt lgkmcnt(0)
	v_mfma_f32_16x16x32_bf16 v[82:85], v[50:53], v[186:189], v[82:85]
	v_mfma_f32_16x16x32_bf16 v[78:81], v[58:61], v[186:189], v[78:81]
	v_mfma_f32_16x16x32_bf16 v[66:69], v[50:53], v[194:197], v[66:69]
	v_mfma_f32_16x16x32_bf16 v[46:49], v[58:61], v[194:197], v[46:49]
	v_mfma_f32_16x16x32_bf16 v[34:37], v[50:53], v[202:205], v[34:37]
	v_mfma_f32_16x16x32_bf16 v[30:33], v[58:61], v[202:205], v[30:33]
	v_mfma_f32_16x16x32_bf16 v[18:21], v[50:53], v[234:237], v[18:21]
	v_mfma_f32_16x16x32_bf16 v[14:17], v[58:61], v[234:237], v[14:17]
	v_mfma_f32_16x16x32_bf16 v[82:85], v[54:57], v[190:193], v[82:85]
	v_mfma_f32_16x16x32_bf16 v[78:81], v[62:65], v[190:193], v[78:81]
	v_mfma_f32_16x16x32_bf16 v[66:69], v[54:57], v[198:201], v[66:69]
	v_mfma_f32_16x16x32_bf16 v[46:49], v[62:65], v[198:201], v[46:49]
	v_mfma_f32_16x16x32_bf16 v[34:37], v[54:57], v[230:233], v[34:37]
	v_mfma_f32_16x16x32_bf16 v[30:33], v[62:65], v[230:233], v[30:33]
	v_mfma_f32_16x16x32_bf16 v[18:21], v[54:57], v[238:241], v[18:21]
	v_mfma_f32_16x16x32_bf16 v[14:17], v[62:65], v[238:241], v[14:17]
	s_setprio 0
	s_setprio 1
	v_mfma_f32_16x16x32_bf16 v[42:45], v[166:169], v[194:197], v[42:45]
	v_mfma_f32_16x16x32_bf16 v[38:41], v[178:181], v[194:197], v[38:41]
	v_mfma_f32_16x16x32_bf16 v[26:29], v[166:169], v[202:205], v[26:29]
	v_mfma_f32_16x16x32_bf16 v[22:25], v[178:181], v[202:205], v[22:25]
	v_mfma_f32_16x16x32_bf16 v[10:13], v[166:169], v[234:237], v[10:13]
	v_mfma_f32_16x16x32_bf16 v[6:9], v[178:181], v[234:237], v[6:9]
	v_mfma_f32_16x16x32_bf16 v[50:53], v[166:169], v[186:189], v[74:77]
	v_mfma_f32_16x16x32_bf16 v[54:57], v[178:181], v[186:189], v[70:73]
	v_mfma_f32_16x16x32_bf16 v[42:45], v[170:173], v[198:201], v[42:45]
	v_mfma_f32_16x16x32_bf16 v[38:41], v[182:185], v[198:201], v[38:41]
	v_mfma_f32_16x16x32_bf16 v[26:29], v[170:173], v[230:233], v[26:29]
	v_mfma_f32_16x16x32_bf16 v[22:25], v[182:185], v[230:233], v[22:25]
	v_mfma_f32_16x16x32_bf16 v[10:13], v[170:173], v[238:241], v[10:13]
	v_mfma_f32_16x16x32_bf16 v[6:9], v[182:185], v[238:241], v[6:9]
	v_mfma_f32_16x16x32_bf16 v[50:53], v[170:173], v[190:193], v[50:53]
	v_mfma_f32_16x16x32_bf16 v[54:57], v[182:185], v[190:193], v[54:57]
	s_setprio 0
	s_barrier
; #define PG8_STAGE(bufoff, gbase, voff) do { _Pragma("unroll") for (int _i = 0; _i < 2; ++_i) \
;         __builtin_amdgcn_global_load_lds((const unsigned*)((const char*)(gbase) + (voff)[_i]), (PG8_LAS unsigned*)(lds + (bufoff) + ldsw + _i * 8192), 16, 0, 0); } while (0)
; #define PG8_LDA(dst, b, h) do { _Pragma("unroll") for (int m = 0; m < 4; ++m) _Pragma("unroll") for (int k = 0; k < 2; ++k) dst[m][k] = *(const PG8_LAS bf16x8*)(lds + PG8_SA(b, h) + aoff + m * 2048 + k * 1024); } while (0)
; #define PG8_LDB(dst, b, h) do { _Pragma("unroll") for (int n = 0; n < 2; ++n) _Pragma("unroll") for (int k = 0; k < 2; ++k) dst[n][k] = *(const PG8_LAS bf16x8*)(lds + PG8_SB(b, h) + boff + n * 2048 + k * 1024); } while (0)
; #define PG8_MMA(ai, bj, At, Bt) do { __builtin_amdgcn_s_setprio(1); _Pragma("unroll") for (int m = 0; m < 4; ++m) _Pragma("unroll") for (int n = 0; n < 2; ++n) _Pragma("unroll") for (int k = 0; k < 2; ++k) \
;         acc[ai][bj][m][n] = __builtin_amdgcn_mfma_f32_16x16x32_bf16(Bt[n][k], At[m][k], acc[ai][bj][m][n], 0, 0, 0); __builtin_amdgcn_s_setprio(0); } while (0)
; #define PG8_WAIT_V(n) asm volatile("s_waitcnt vmcnt(" #n ")" ::: "memory")
; #define PG8_WAIT_L(n) asm volatile("s_waitcnt lgkmcnt(" #n ")" ::: "memory")
; #define PG8_BAR __builtin_amdgcn_s_barrier()
; #define PG8_SCHED __builtin_amdgcn_sched_barrier(0)
; template <class Epi, class Sched, bool ALIGN_EPI = false, bool SP2 = false>
; __device__ __forceinline__ void gemm_phase(PG8_LAS unsigned char* lds, const Gemm g, const Sched& S, const Epi& E) {
;     ...
;             PG8_LDB(B0, 1, 0); PG8_LDB(B1, 1, 1); PG8_SCHED; PG8_LDA(At, 1, 0); PG8_STAGE(PG8_SA(0, 1), a2 + hstep, voffA);
;             PG8_WAIT_V(8); PG8_WAIT_L(0); PG8_BAR; PG8_MMA(0, 0, At, B0); PG8_MMA(0, 1, At, B1); PG8_BAR; PG8_SCHED;
	s_add_i32 s84, 0, 0x18000
	s_add_i32 s86, 0, 0x1c000
	v_add_u32_e32 v74, s84, v152
	v_add_u32_e32 v160, s86, v152
	ds_read_b128 v[58:61], v74
	ds_read_b128 v[62:65], v74 offset:1024
	ds_read_b128 v[70:73], v74 offset:2048
	ds_read_b128 v[74:77], v74 offset:3072
	ds_read_b128 v[166:169], v160
	ds_read_b128 v[170:173], v160 offset:1024
	ds_read_b128 v[178:181], v160 offset:2048
	ds_read_b128 v[182:185], v160 offset:3072
	s_add_u32 s30, s40, 0x160000
	s_addc_u32 s31, s41, 0
	s_mov_b32 m0, s53
	ds_read_b128 v[186:189], v177 offset:32768
	ds_read_b128 v[190:193], v177 offset:33792
	ds_read_b128 v[194:197], v177 offset:34816
	ds_read_b128 v[198:201], v177 offset:35840
	ds_read_b128 v[202:205], v177 offset:36864
	ds_read_b128 v[230:233], v177 offset:37888
	ds_read_b128 v[234:237], v177 offset:38912
	ds_read_b128 v[238:241], v177 offset:39936
	global_load_lds_dwordx4 v2, s[30:31]
	s_mov_b32 m0, s66
	s_nop 0
	global_load_lds_dwordx4 v0, s[30:31]
	s_waitcnt vmcnt(8)
	s_waitcnt lgkmcnt(0)
	s_barrier
	s_setprio 1
	s_waitcnt lgkmcnt(0)
	v_mfma_f32_16x16x32_bf16 v[146:149], v[58:61], v[186:189], v[146:149]
	v_mfma_f32_16x16x32_bf16 v[142:145], v[70:73], v[186:189], v[142:145]
	v_mfma_f32_16x16x32_bf16 v[130:133], v[58:61], v[194:197], v[130:133]
	v_mfma_f32_16x16x32_bf16 v[126:129], v[70:73], v[194:197], v[126:129]
	v_mfma_f32_16x16x32_bf16 v[114:117], v[58:61], v[202:205], v[114:117]
	v_mfma_f32_16x16x32_bf16 v[110:113], v[70:73], v[202:205], v[110:113]
	v_mfma_f32_16x16x32_bf16 v[98:101], v[58:61], v[234:237], v[98:101]
	v_mfma_f32_16x16x32_bf16 v[94:97], v[70:73], v[234:237], v[94:97]
	v_mfma_f32_16x16x32_bf16 v[146:149], v[62:65], v[190:193], v[146:149]
	v_mfma_f32_16x16x32_bf16 v[142:145], v[74:77], v[190:193], v[142:145]
	v_mfma_f32_16x16x32_bf16 v[130:133], v[62:65], v[198:201], v[130:133]
	v_mfma_f32_16x16x32_bf16 v[126:129], v[74:77], v[198:201], v[126:129]
	v_mfma_f32_16x16x32_bf16 v[114:117], v[62:65], v[230:233], v[114:117]
	v_mfma_f32_16x16x32_bf16 v[110:113], v[74:77], v[230:233], v[110:113]
	v_mfma_f32_16x16x32_bf16 v[98:101], v[62:65], v[238:241], v[98:101]
	v_mfma_f32_16x16x32_bf16 v[94:97], v[74:77], v[238:241], v[94:97]
	s_setprio 0
	s_setprio 1
	v_mfma_f32_16x16x32_bf16 v[138:141], v[166:169], v[186:189], v[138:141]
	v_mfma_f32_16x16x32_bf16 v[134:137], v[178:181], v[186:189], v[134:137]
	v_mfma_f32_16x16x32_bf16 v[122:125], v[166:169], v[194:197], v[122:125]
	v_mfma_f32_16x16x32_bf16 v[118:121], v[178:181], v[194:197], v[118:121]
	v_mfma_f32_16x16x32_bf16 v[106:109], v[166:169], v[202:205], v[106:109]
	v_mfma_f32_16x16x32_bf16 v[102:105], v[178:181], v[202:205], v[102:105]
	v_mfma_f32_16x16x32_bf16 v[90:93], v[166:169], v[234:237], v[90:93]
	v_mfma_f32_16x16x32_bf16 v[86:89], v[178:181], v[234:237], v[86:89]
	v_mfma_f32_16x16x32_bf16 v[138:141], v[170:173], v[190:193], v[138:141]
	v_mfma_f32_16x16x32_bf16 v[134:137], v[182:185], v[190:193], v[134:137]
	v_mfma_f32_16x16x32_bf16 v[122:125], v[170:173], v[198:201], v[122:125]
	v_mfma_f32_16x16x32_bf16 v[118:121], v[182:185], v[198:201], v[118:121]
	v_mfma_f32_16x16x32_bf16 v[106:109], v[170:173], v[230:233], v[106:109]
	v_mfma_f32_16x16x32_bf16 v[102:105], v[182:185], v[230:233], v[102:105]
	v_mfma_f32_16x16x32_bf16 v[90:93], v[170:173], v[238:241], v[90:93]
	v_mfma_f32_16x16x32_bf16 v[86:89], v[182:185], v[238:241], v[86:89]
	s_setprio 0
	s_barrier
; #define PG8_STAGE(bufoff, gbase, voff) do { _Pragma("unroll") for (int _i = 0; _i < 2; ++_i) \
;         __builtin_amdgcn_global_load_lds((const unsigned*)((const char*)(gbase) + (voff)[_i]), (PG8_LAS unsigned*)(lds + (bufoff) + ldsw + _i * 8192), 16, 0, 0); } while (0)
; #define PG8_LDA(dst, b, h) do { _Pragma("unroll") for (int m = 0; m < 4; ++m) _Pragma("unroll") for (int k = 0; k < 2; ++k) dst[m][k] = *(const PG8_LAS bf16x8*)(lds + PG8_SA(b, h) + aoff + m * 2048 + k * 1024); } while (0)
; #define PG8_MMA(ai, bj, At, Bt) do { __builtin_amdgcn_s_setprio(1); _Pragma("unroll") for (int m = 0; m < 4; ++m) _Pragma("unroll") for (int n = 0; n < 2; ++n) _Pragma("unroll") for (int k = 0; k < 2; ++k) \
;         acc[ai][bj][m][n] = __builtin_amdgcn_mfma_f32_16x16x32_bf16(Bt[n][k], At[m][k], acc[ai][bj][m][n], 0, 0, 0); __builtin_amdgcn_s_setprio(0); } while (0)
; #define PG8_WAIT_V(n) asm volatile("s_waitcnt vmcnt(" #n ")" ::: "memory")
; #define PG8_WAIT_L(n) asm volatile("s_waitcnt lgkmcnt(" #n ")" ::: "memory")
; #define PG8_BAR __builtin_amdgcn_s_barrier()
; #define PG8_SCHED __builtin_amdgcn_sched_barrier(0)
;     __device__ __forceinline__ void operator()(const f32x4 (&acc)[2][2][4][2], const Unit& u, int wr, int wc, int fr, int fq) const {
;         const int row0 = u.pm * BM + wr * 64 + fr; const int col0 = u.pn * BM + wc * 32 + 4 * fq;
;         f32x4 gv[2][2];
; #pragma unroll
;         for (int bj = 0; bj < 2; ++bj)
; #pragma unroll
;             for (int n = 0; n < 2; ++n) gv[bj][n] = xg ? *(const f32x4*)(gn + col0 + bj * HALF + n * 16) : (f32x4){0.f, 0.f, 0.f, 0.f};
; template <class Epi, class Sched, bool ALIGN_EPI = false, bool SP2 = false>
; __device__ __forceinline__ void gemm_phase(PG8_LAS unsigned char* lds, const Gemm g, const Sched& S, const Epi& E) {
;     ...
;             PG8_LDA(At, 1, 1); PG8_STAGE(PG8_SB(1, 0), b3, voffB); PG8_STAGE(PG8_SB(1, 1), b3 + hstep, voffB); PG8_STAGE(PG8_SA(1, 0), a3, voffA);
;             PG8_WAIT_V(8); PG8_WAIT_L(0); PG8_BAR; PG8_MMA(1, 0, At, B0); PG8_MMA(1, 1, At, B1); PG8_BAR; PG8_SCHED;
	s_add_u32 vcc_lo, s34, s2
	s_addc_u32 vcc_hi, s35, s3
	s_add_i32 s30, s84, s49
	s_mov_b32 m0, s30
	ds_read_b128 v[186:189], v177 offset:49152
	ds_read_b128 v[190:193], v177 offset:50176
	ds_read_b128 v[194:197], v177 offset:51200
	ds_read_b128 v[198:201], v177 offset:52224
	ds_read_b128 v[202:205], v177 offset:53248
	ds_read_b128 v[230:233], v177 offset:54272
	ds_read_b128 v[234:237], v177 offset:55296
	ds_read_b128 v[238:241], v177 offset:56320
	global_load_lds_dwordx4 v2, vcc
	s_add_i32 m0, s30, 0x2000
	s_add_u32 s30, s34, 0x160080
	s_addc_u32 s31, s35, 0
	s_add_i32 s34, s86, s49
	global_load_lds_dwordx4 v0, vcc
	s_mov_b32 m0, s34
	s_nop 0
	global_load_lds_dwordx4 v2, s[30:31]
	s_add_i32 m0, s34, 0x2000
	s_nop 0
	global_load_lds_dwordx4 v0, s[30:31]
	s_add_u32 vcc_lo, s40, s2
	s_addc_u32 vcc_hi, s41, s3
	s_mov_b32 m0, s67
	s_nop 0
	global_load_lds_dwordx4 v2, vcc
	s_mov_b32 m0, s69
	s_nop 0
	global_load_lds_dwordx4 v0, vcc
	s_waitcnt vmcnt(8)
	s_waitcnt lgkmcnt(0)
	s_barrier
	s_setprio 1
	s_waitcnt lgkmcnt(0)
	v_mfma_f32_16x16x32_bf16 v[82:85], v[58:61], v[186:189], v[82:85]
	v_mfma_f32_16x16x32_bf16 v[78:81], v[70:73], v[186:189], v[78:81]
	v_mfma_f32_16x16x32_bf16 v[66:69], v[58:61], v[194:197], v[66:69]
	v_mfma_f32_16x16x32_bf16 v[46:49], v[70:73], v[194:197], v[46:49]
	v_mfma_f32_16x16x32_bf16 v[34:37], v[58:61], v[202:205], v[34:37]
	v_mfma_f32_16x16x32_bf16 v[30:33], v[70:73], v[202:205], v[30:33]
	v_mfma_f32_16x16x32_bf16 v[18:21], v[58:61], v[234:237], v[18:21]
	v_mfma_f32_16x16x32_bf16 v[14:17], v[70:73], v[234:237], v[14:17]
	v_mfma_f32_16x16x32_bf16 v[82:85], v[62:65], v[190:193], v[82:85]
	v_mfma_f32_16x16x32_bf16 v[78:81], v[74:77], v[190:193], v[78:81]
	v_mfma_f32_16x16x32_bf16 v[66:69], v[62:65], v[198:201], v[66:69]
	v_mfma_f32_16x16x32_bf16 v[46:49], v[74:77], v[198:201], v[46:49]
	v_mfma_f32_16x16x32_bf16 v[34:37], v[62:65], v[230:233], v[34:37]
	v_mfma_f32_16x16x32_bf16 v[30:33], v[74:77], v[230:233], v[30:33]
	v_mfma_f32_16x16x32_bf16 v[18:21], v[62:65], v[238:241], v[18:21]
	v_mfma_f32_16x16x32_bf16 v[14:17], v[74:77], v[238:241], v[14:17]
	s_setprio 0
	s_setprio 1
	v_mfma_f32_16x16x32_bf16 v[50:53], v[166:169], v[186:189], v[50:53]
	v_mfma_f32_16x16x32_bf16 v[74:77], v[170:173], v[190:193], v[50:53]
	v_mfma_f32_16x16x32_bf16 v[50:53], v[178:181], v[186:189], v[54:57]
	v_mfma_f32_16x16x32_bf16 v[42:45], v[166:169], v[194:197], v[42:45]
	v_mfma_f32_16x16x32_bf16 v[38:41], v[178:181], v[194:197], v[38:41]
	v_mfma_f32_16x16x32_bf16 v[26:29], v[166:169], v[202:205], v[26:29]
	v_mfma_f32_16x16x32_bf16 v[22:25], v[178:181], v[202:205], v[22:25]
	v_mfma_f32_16x16x32_bf16 v[10:13], v[166:169], v[234:237], v[10:13]
	v_mfma_f32_16x16x32_bf16 v[6:9], v[178:181], v[234:237], v[6:9]
	v_mfma_f32_16x16x32_bf16 v[70:73], v[182:185], v[190:193], v[50:53]
	v_mfma_f32_16x16x32_bf16 v[42:45], v[170:173], v[198:201], v[42:45]
	v_mfma_f32_16x16x32_bf16 v[38:41], v[182:185], v[198:201], v[38:41]
	v_mfma_f32_16x16x32_bf16 v[26:29], v[170:173], v[230:233], v[26:29]
	v_mfma_f32_16x16x32_bf16 v[22:25], v[182:185], v[230:233], v[22:25]
	v_mfma_f32_16x16x32_bf16 v[10:13], v[170:173], v[238:241], v[10:13]
	v_mfma_f32_16x16x32_bf16 v[6:9], v[182:185], v[238:241], v[6:9]
	s_setprio 0
	s_barrier
	s_add_i32 s83, s83, 2
	s_add_u32 s81, s81, 0x100
	s_addc_u32 s82, s82, 0
	s_cmpk_gt_u32 s83, 0x55
	s_mov_b64 s[30:31], s[10:11]
	s_cbranch_scc0 .LBB0_235
	v_lshl_or_b32 v170, s80, 8, v176
	v_ashrrev_i32_e32 v171, 31, v170
	v_mov_b32_e32 v54, 0
	v_cndmask_b32_e64 v50, 0, 1, s[20:21]
	v_lshl_add_u64 v[166:167], v[170:171], 2, s[24:25]
	v_cmp_ne_u32_e64 s[10:11], 1, v50
	s_andn2_b64 vcc, exec, s[20:21]
	v_mov_b32_e32 v62, 0
	v_mov_b32_e32 v63, v54
	v_mov_b32_e32 v64, 0
	v_mov_b32_e32 v65, 0
	s_cbranch_vccnz .LBB0_238
	global_load_dwordx4 v[62:65], v[166:167], off

; #define PG8_STAGE(bufoff, gbase, voff) do { _Pragma("unroll") for (int _i = 0; _i < 2; ++_i) \
;         __builtin_amdgcn_global_load_lds((const unsigned*)((const char*)(gbase) + (voff)[_i]), (PG8_LAS unsigned*)(lds + (bufoff) + ldsw + _i * 8192), 16, 0, 0); } while (0)
; #define PG8_LDA(dst, b, h) do { _Pragma("unroll") for (int m = 0; m < 4; ++m) _Pragma("unroll") for (int k = 0; k < 2; ++k) dst[m][k] = *(const PG8_LAS bf16x8*)(lds + PG8_SA(b, h) + aoff + m * 2048 + k * 1024); } while (0)
; #define PG8_LDB(dst, b, h) do { _Pragma("unroll") for (int n = 0; n < 2; ++n) _Pragma("unroll") for (int k = 0; k < 2; ++k) dst[n][k] = *(const PG8_LAS bf16x8*)(lds + PG8_SB(b, h) + boff + n * 2048 + k * 1024); } while (0)
; #define PG8_MMA(ai, bj, At, Bt) do { __builtin_amdgcn_s_setprio(1); _Pragma("unroll") for (int m = 0; m < 4; ++m) _Pragma("unroll") for (int n = 0; n < 2; ++n) _Pragma("unroll") for (int k = 0; k < 2; ++k) \
;         acc[ai][bj][m][n] = __builtin_amdgcn_mfma_f32_16x16x32_bf16(Bt[n][k], At[m][k], acc[ai][bj][m][n], 0, 0, 0); __builtin_amdgcn_s_setprio(0); } while (0)
; #define PG8_WAIT_V(n) asm volatile("s_waitcnt vmcnt(" #n ")" ::: "memory")
; #define PG8_WAIT_L(n) asm volatile("s_waitcnt lgkmcnt(" #n ")" ::: "memory")
; #define PG8_BAR __builtin_amdgcn_s_barrier()
; #define PG8_SCHED __builtin_amdgcn_sched_barrier(0)
; template <class Epi, class Sched, bool ALIGN_EPI = false, bool SP2 = false>
; __device__ __forceinline__ void gemm_phase(PG8_LAS unsigned char* lds, const Gemm g, const Sched& S, const Epi& E) {
;     ...
;             const bool last = (t == nt - 2);
;             const char* a1 = cA + (size_t)(t + 1) * kstep;
;             const char* a2 = last ? nA : cA + (size_t)(t + 2) * kstep; const char* b2 = last ? nB : cB + (size_t)(t + 2) * kstep;
;             const char* a3 = a2 + kstep; const char* b3 = b2 + kstep;
;             if (last && has_next) S.a_ready(nxt);
;             if constexpr (SP2) {
;             PG8_LDB(B0, 0, 0); PG8_LDB(B1, 0, 1); PG8_SCHED; PG8_LDA(At, 0, 0); PG8_STAGE(PG8_SA(1, 1), a1 + hstep, voffA);
;             PG8_WAIT_V(8); PG8_WAIT_L(0); PG8_BAR; PG8_MMA(0, 0, At, B0); PG8_MMA(0, 1, At, B1); PG8_BAR; PG8_SCHED;
;             PG8_LDA(At, 0, 1); PG8_STAGE(PG8_SB(0, 0), b2, voffB); PG8_STAGE(PG8_SB(0, 1), b2 + hstep, voffB); PG8_STAGE(PG8_SA(0, 0), a2, voffA);
.LBB0_396:
	s_add_u32 s30, s10, 0xfff80080
	s_addc_u32 s31, s11, -1
	s_add_i32 s78, 0, 0x10000
	s_cmp_eq_u32 s71, 28
	s_cselect_b32 s35, s23, s31
	s_cselect_b32 s34, s66, s30
	v_add_u32_e32 v2, s78, v141
	s_cselect_b32 s31, s21, s70
	s_cselect_b32 s30, s67, s69
	s_add_i32 s80, 0, 0x14000
	ds_read_b128 v[146:149], v2
	ds_read_b128 v[162:165], v2 offset:1024
	ds_read_b128 v[166:169], v2 offset:2048
	ds_read_b128 v[172:175], v2 offset:3072
	v_add_u32_e32 v2, s80, v141
	ds_read_b128 v[176:179], v2
	ds_read_b128 v[180:183], v2 offset:1024
	ds_read_b128 v[184:187], v2 offset:2048
	ds_read_b128 v[188:191], v2 offset:3072
	s_add_i32 m0, s45, 0xc000
	ds_read_b128 v[192:195], v170
	ds_read_b128 v[196:199], v170 offset:1024
	ds_read_b128 v[200:203], v170 offset:2048
	ds_read_b128 v[204:207], v170 offset:3072
	ds_read_b128 v[230:233], v170 offset:4096
	ds_read_b128 v[234:237], v170 offset:5120
	ds_read_b128 v[238:241], v170 offset:6144
	ds_read_b128 v[242:245], v170 offset:7168
	global_load_lds_dwordx4 v144, s[10:11]
	s_add_i32 m0, s45, 0xe000
	s_nop 0
	global_load_lds_dwordx4 v142, s[10:11]
	s_waitcnt vmcnt(8)
	s_waitcnt lgkmcnt(0)
	s_barrier
	s_setprio 1
	s_waitcnt lgkmcnt(0)
	v_mfma_f32_16x16x32_bf16 v[130:133], v[146:149], v[192:195], v[130:133]
	v_mfma_f32_16x16x32_bf16 v[126:129], v[166:169], v[192:195], v[126:129]
	v_mfma_f32_16x16x32_bf16 v[114:117], v[146:149], v[200:203], v[114:117]
	v_mfma_f32_16x16x32_bf16 v[110:113], v[166:169], v[200:203], v[110:113]
	v_mfma_f32_16x16x32_bf16 v[98:101], v[146:149], v[230:233], v[98:101]
	v_mfma_f32_16x16x32_bf16 v[94:97], v[166:169], v[230:233], v[94:97]
	v_mfma_f32_16x16x32_bf16 v[82:85], v[146:149], v[238:241], v[82:85]
	v_mfma_f32_16x16x32_bf16 v[78:81], v[166:169], v[238:241], v[78:81]
	v_mfma_f32_16x16x32_bf16 v[130:133], v[162:165], v[196:199], v[130:133]
	v_mfma_f32_16x16x32_bf16 v[126:129], v[172:175], v[196:199], v[126:129]
	v_mfma_f32_16x16x32_bf16 v[114:117], v[162:165], v[204:207], v[114:117]
	v_mfma_f32_16x16x32_bf16 v[110:113], v[172:175], v[204:207], v[110:113]
	v_mfma_f32_16x16x32_bf16 v[98:101], v[162:165], v[234:237], v[98:101]
	v_mfma_f32_16x16x32_bf16 v[94:97], v[172:175], v[234:237], v[94:97]
	v_mfma_f32_16x16x32_bf16 v[82:85], v[162:165], v[242:245], v[82:85]
	v_mfma_f32_16x16x32_bf16 v[78:81], v[172:175], v[242:245], v[78:81]
	s_setprio 0
	s_setprio 1
	v_mfma_f32_16x16x32_bf16 v[122:125], v[176:179], v[192:195], v[122:125]
	v_mfma_f32_16x16x32_bf16 v[118:121], v[184:187], v[192:195], v[118:121]
	v_mfma_f32_16x16x32_bf16 v[106:109], v[176:179], v[200:203], v[106:109]
	v_mfma_f32_16x16x32_bf16 v[102:105], v[184:187], v[200:203], v[102:105]
	v_mfma_f32_16x16x32_bf16 v[90:93], v[176:179], v[230:233], v[90:93]
	v_mfma_f32_16x16x32_bf16 v[86:89], v[184:187], v[230:233], v[86:89]
	v_mfma_f32_16x16x32_bf16 v[74:77], v[176:179], v[238:241], v[74:77]
	v_mfma_f32_16x16x32_bf16 v[70:73], v[184:187], v[238:241], v[70:73]
	v_mfma_f32_16x16x32_bf16 v[122:125], v[180:183], v[196:199], v[122:125]
	v_mfma_f32_16x16x32_bf16 v[118:121], v[188:191], v[196:199], v[118:121]
	v_mfma_f32_16x16x32_bf16 v[106:109], v[180:183], v[204:207], v[106:109]
	v_mfma_f32_16x16x32_bf16 v[102:105], v[188:191], v[204:207], v[102:105]
	v_mfma_f32_16x16x32_bf16 v[90:93], v[180:183], v[234:237], v[90:93]
	v_mfma_f32_16x16x32_bf16 v[86:89], v[188:191], v[234:237], v[86:89]
	v_mfma_f32_16x16x32_bf16 v[74:77], v[180:183], v[242:245], v[74:77]
	v_mfma_f32_16x16x32_bf16 v[70:73], v[188:191], v[242:245], v[70:73]
	s_setprio 0
	s_barrier
	s_add_i32 s78, s78, s40
	s_mov_b32 m0, s78
	ds_read_b128 v[192:195], v170 offset:16384
	ds_read_b128 v[196:199], v170 offset:17408
	ds_read_b128 v[200:203], v170 offset:18432
	ds_read_b128 v[204:207], v170 offset:19456
	ds_read_b128 v[230:233], v170 offset:20480
	ds_read_b128 v[234:237], v170 offset:21504
	ds_read_b128 v[238:241], v170 offset:22528
	ds_read_b128 v[242:245], v170 offset:23552
	global_load_lds_dwordx4 v136, s[30:31]
	s_add_i32 m0, s78, 0x2000
	s_add_u32 s78, s30, 0x80000
	s_addc_u32 s79, s31, 0
	s_add_i32 s80, s80, s40
	global_load_lds_dwordx4 v0, s[30:31]
	s_mov_b32 m0, s80
	v_lshl_add_u64 v[250:251], s[34:35], 0, v[134:135]
	global_load_lds_dwordx4 v136, s[78:79]
	s_add_i32 m0, s80, 0x2000
	s_nop 0
	global_load_lds_dwordx4 v0, s[78:79]
	v_lshl_add_u64 v[248:249], s[34:35], 0, v[138:139]
	s_mov_b32 m0, s45
	s_nop 0
	global_load_lds_dwordx4 v138, s[34:35]
	s_mov_b32 m0, s46
	s_nop 0
	global_load_lds_dwordx4 v134, s[34:35]
	s_waitcnt vmcnt(8)
	s_waitcnt lgkmcnt(0)
	s_barrier
; #define PG8_STAGE(bufoff, gbase, voff) do { _Pragma("unroll") for (int _i = 0; _i < 2; ++_i) \
;         __builtin_amdgcn_global_load_lds((const unsigned*)((const char*)(gbase) + (voff)[_i]), (PG8_LAS unsigned*)(lds + (bufoff) + ldsw + _i * 8192), 16, 0, 0); } while (0)
; #define PG8_LDA(dst, b, h) do { _Pragma("unroll") for (int m = 0; m < 4; ++m) _Pragma("unroll") for (int k = 0; k < 2; ++k) dst[m][k] = *(const PG8_LAS bf16x8*)(lds + PG8_SA(b, h) + aoff + m * 2048 + k * 1024); } while (0)
; #define PG8_LDB(dst, b, h) do { _Pragma("unroll") for (int n = 0; n < 2; ++n) _Pragma("unroll") for (int k = 0; k < 2; ++k) dst[n][k] = *(const PG8_LAS bf16x8*)(lds + PG8_SB(b, h) + boff + n * 2048 + k * 1024); } while (0)
; #define PG8_MMA(ai, bj, At, Bt) do { __builtin_amdgcn_s_setprio(1); _Pragma("unroll") for (int m = 0; m < 4; ++m) _Pragma("unroll") for (int n = 0; n < 2; ++n) _Pragma("unroll") for (int k = 0; k < 2; ++k) \
;         acc[ai][bj][m][n] = __builtin_amdgcn_mfma_f32_16x16x32_bf16(Bt[n][k], At[m][k], acc[ai][bj][m][n], 0, 0, 0); __builtin_amdgcn_s_setprio(0); } while (0)
; #define PG8_WAIT_V(n) asm volatile("s_waitcnt vmcnt(" #n ")" ::: "memory")
; #define PG8_WAIT_L(n) asm volatile("s_waitcnt lgkmcnt(" #n ")" ::: "memory")
; #define PG8_BAR __builtin_amdgcn_s_barrier()
; #define PG8_SCHED __builtin_amdgcn_sched_barrier(0)
; template <class Epi, class Sched, bool ALIGN_EPI = false, bool SP2 = false>
; __device__ __forceinline__ void gemm_phase(PG8_LAS unsigned char* lds, const Gemm g, const Sched& S, const Epi& E) {
;     ...
;             PG8_WAIT_V(8); PG8_WAIT_L(0); PG8_BAR; PG8_MMA(1, 0, At, B0); PG8_MMA(1, 1, At, B1); PG8_BAR; PG8_SCHED;
;             PG8_LDB(B0, 1, 0); PG8_LDB(B1, 1, 1); PG8_SCHED; PG8_LDA(At, 1, 0); PG8_STAGE(PG8_SA(0, 1), a2 + hstep, voffA);
;             PG8_WAIT_V(8); PG8_WAIT_L(0); PG8_BAR; PG8_MMA(0, 0, At, B0); PG8_MMA(0, 1, At, B1); PG8_BAR; PG8_SCHED;
	s_setprio 1
	s_waitcnt lgkmcnt(0)
	v_mfma_f32_16x16x32_bf16 v[66:69], v[146:149], v[192:195], v[66:69]
	v_mfma_f32_16x16x32_bf16 v[62:65], v[166:169], v[192:195], v[62:65]
	v_mfma_f32_16x16x32_bf16 v[50:53], v[146:149], v[200:203], v[50:53]
	v_mfma_f32_16x16x32_bf16 v[46:49], v[166:169], v[200:203], v[46:49]
	v_mfma_f32_16x16x32_bf16 v[34:37], v[146:149], v[230:233], v[34:37]
	v_mfma_f32_16x16x32_bf16 v[30:33], v[166:169], v[230:233], v[30:33]
	v_mfma_f32_16x16x32_bf16 v[18:21], v[146:149], v[238:241], v[18:21]
	v_mfma_f32_16x16x32_bf16 v[14:17], v[166:169], v[238:241], v[14:17]
	v_mfma_f32_16x16x32_bf16 v[66:69], v[162:165], v[196:199], v[66:69]
	v_mfma_f32_16x16x32_bf16 v[62:65], v[172:175], v[196:199], v[62:65]
	v_mfma_f32_16x16x32_bf16 v[50:53], v[162:165], v[204:207], v[50:53]
	v_mfma_f32_16x16x32_bf16 v[46:49], v[172:175], v[204:207], v[46:49]
	v_mfma_f32_16x16x32_bf16 v[34:37], v[162:165], v[234:237], v[34:37]
	v_mfma_f32_16x16x32_bf16 v[30:33], v[172:175], v[234:237], v[30:33]
	v_mfma_f32_16x16x32_bf16 v[18:21], v[162:165], v[242:245], v[18:21]
	v_mfma_f32_16x16x32_bf16 v[14:17], v[172:175], v[242:245], v[14:17]
	s_setprio 0
	s_setprio 1
	v_mfma_f32_16x16x32_bf16 v[58:61], v[176:179], v[192:195], v[58:61]
	v_mfma_f32_16x16x32_bf16 v[54:57], v[184:187], v[192:195], v[54:57]
	v_mfma_f32_16x16x32_bf16 v[42:45], v[176:179], v[200:203], v[42:45]
	v_mfma_f32_16x16x32_bf16 v[38:41], v[184:187], v[200:203], v[38:41]
	v_mfma_f32_16x16x32_bf16 v[26:29], v[176:179], v[230:233], v[26:29]
	v_mfma_f32_16x16x32_bf16 v[22:25], v[184:187], v[230:233], v[22:25]
	v_mfma_f32_16x16x32_bf16 v[10:13], v[176:179], v[238:241], v[10:13]
	v_mfma_f32_16x16x32_bf16 v[6:9], v[184:187], v[238:241], v[6:9]
	v_mfma_f32_16x16x32_bf16 v[58:61], v[180:183], v[196:199], v[58:61]
	v_mfma_f32_16x16x32_bf16 v[54:57], v[188:191], v[196:199], v[54:57]
	v_mfma_f32_16x16x32_bf16 v[42:45], v[180:183], v[204:207], v[42:45]
	v_mfma_f32_16x16x32_bf16 v[38:41], v[188:191], v[204:207], v[38:41]
	v_mfma_f32_16x16x32_bf16 v[26:29], v[180:183], v[234:237], v[26:29]
	v_mfma_f32_16x16x32_bf16 v[22:25], v[188:191], v[234:237], v[22:25]
	v_mfma_f32_16x16x32_bf16 v[10:13], v[180:183], v[242:245], v[10:13]
	v_mfma_f32_16x16x32_bf16 v[6:9], v[188:191], v[242:245], v[6:9]
	s_setprio 0
	s_barrier
	s_add_i32 s78, 0, 0x18000
	v_add_u32_e32 v2, s78, v141
	s_add_i32 s79, 0, 0x1c000
	ds_read_b128 v[146:149], v2
	ds_read_b128 v[162:165], v2 offset:1024
	ds_read_b128 v[166:169], v2 offset:2048
	ds_read_b128 v[172:175], v2 offset:3072
	v_add_u32_e32 v2, s79, v141
	ds_read_b128 v[176:179], v2
	ds_read_b128 v[180:183], v2 offset:1024
	ds_read_b128 v[184:187], v2 offset:2048
	ds_read_b128 v[188:191], v2 offset:3072
	s_add_u32 s34, s34, 0x80000
	s_addc_u32 s35, s35, 0
	s_mov_b32 m0, s47
	ds_read_b128 v[192:195], v170 offset:32768
	ds_read_b128 v[196:199], v170 offset:33792
	ds_read_b128 v[200:203], v170 offset:34816
	ds_read_b128 v[204:207], v170 offset:35840
	ds_read_b128 v[230:233], v170 offset:36864
	ds_read_b128 v[234:237], v170 offset:37888
	ds_read_b128 v[238:241], v170 offset:38912
	ds_read_b128 v[242:245], v170 offset:39936
	global_load_lds_dwordx4 v138, s[34:35]
	s_mov_b32 m0, s48
	s_nop 0
	global_load_lds_dwordx4 v134, s[34:35]
	s_waitcnt vmcnt(8)
	s_waitcnt lgkmcnt(0)
	s_barrier
	s_setprio 1
	s_waitcnt lgkmcnt(0)
	v_mfma_f32_16x16x32_bf16 v[130:133], v[146:149], v[192:195], v[130:133]
	v_mfma_f32_16x16x32_bf16 v[126:129], v[166:169], v[192:195], v[126:129]
	v_mfma_f32_16x16x32_bf16 v[114:117], v[146:149], v[200:203], v[114:117]
	v_mfma_f32_16x16x32_bf16 v[110:113], v[166:169], v[200:203], v[110:113]
	v_mfma_f32_16x16x32_bf16 v[98:101], v[146:149], v[230:233], v[98:101]
	v_mfma_f32_16x16x32_bf16 v[94:97], v[166:169], v[230:233], v[94:97]
	v_mfma_f32_16x16x32_bf16 v[82:85], v[146:149], v[238:241], v[82:85]
	v_mfma_f32_16x16x32_bf16 v[78:81], v[166:169], v[238:241], v[78:81]
	v_mfma_f32_16x16x32_bf16 v[130:133], v[162:165], v[196:199], v[130:133]
	v_mfma_f32_16x16x32_bf16 v[126:129], v[172:175], v[196:199], v[126:129]
	v_mfma_f32_16x16x32_bf16 v[114:117], v[162:165], v[204:207], v[114:117]
	v_mfma_f32_16x16x32_bf16 v[110:113], v[172:175], v[204:207], v[110:113]
	v_mfma_f32_16x16x32_bf16 v[98:101], v[162:165], v[234:237], v[98:101]
	v_mfma_f32_16x16x32_bf16 v[94:97], v[172:175], v[234:237], v[94:97]
	v_mfma_f32_16x16x32_bf16 v[82:85], v[162:165], v[242:245], v[82:85]
	v_mfma_f32_16x16x32_bf16 v[78:81], v[172:175], v[242:245], v[78:81]
	s_setprio 0
	s_setprio 1
	v_mfma_f32_16x16x32_bf16 v[122:125], v[176:179], v[192:195], v[122:125]
	v_mfma_f32_16x16x32_bf16 v[118:121], v[184:187], v[192:195], v[118:121]
	v_mfma_f32_16x16x32_bf16 v[106:109], v[176:179], v[200:203], v[106:109]
	v_mfma_f32_16x16x32_bf16 v[102:105], v[184:187], v[200:203], v[102:105]
	v_mfma_f32_16x16x32_bf16 v[90:93], v[176:179], v[230:233], v[90:93]
	v_mfma_f32_16x16x32_bf16 v[86:89], v[184:187], v[230:233], v[86:89]
	v_mfma_f32_16x16x32_bf16 v[74:77], v[176:179], v[238:241], v[74:77]
	v_mfma_f32_16x16x32_bf16 v[70:73], v[184:187], v[238:241], v[70:73]
	v_mfma_f32_16x16x32_bf16 v[122:125], v[180:183], v[196:199], v[122:125]
	v_mfma_f32_16x16x32_bf16 v[118:121], v[188:191], v[196:199], v[118:121]
	v_mfma_f32_16x16x32_bf16 v[106:109], v[180:183], v[204:207], v[106:109]
	v_mfma_f32_16x16x32_bf16 v[102:105], v[188:191], v[204:207], v[102:105]
	v_mfma_f32_16x16x32_bf16 v[90:93], v[180:183], v[234:237], v[90:93]
	v_mfma_f32_16x16x32_bf16 v[86:89], v[188:191], v[234:237], v[86:89]
	v_mfma_f32_16x16x32_bf16 v[74:77], v[180:183], v[242:245], v[74:77]
	v_mfma_f32_16x16x32_bf16 v[70:73], v[188:191], v[242:245], v[70:73]
	s_setprio 0
	s_barrier
; #define PG8_STAGE(bufoff, gbase, voff) do { _Pragma("unroll") for (int _i = 0; _i < 2; ++_i) \
;         __builtin_amdgcn_global_load_lds((const unsigned*)((const char*)(gbase) + (voff)[_i]), (PG8_LAS unsigned*)(lds + (bufoff) + ldsw + _i * 8192), 16, 0, 0); } while (0)
; #define PG8_LDA(dst, b, h) do { _Pragma("unroll") for (int m = 0; m < 4; ++m) _Pragma("unroll") for (int k = 0; k < 2; ++k) dst[m][k] = *(const PG8_LAS bf16x8*)(lds + PG8_SA(b, h) + aoff + m * 2048 + k * 1024); } while (0)
; #define PG8_MMA(ai, bj, At, Bt) do { __builtin_amdgcn_s_setprio(1); _Pragma("unroll") for (int m = 0; m < 4; ++m) _Pragma("unroll") for (int n = 0; n < 2; ++n) _Pragma("unroll") for (int k = 0; k < 2; ++k) \
;         acc[ai][bj][m][n] = __builtin_amdgcn_mfma_f32_16x16x32_bf16(Bt[n][k], At[m][k], acc[ai][bj][m][n], 0, 0, 0); __builtin_amdgcn_s_setprio(0); } while (0)
; #define PG8_WAIT_V(n) asm volatile("s_waitcnt vmcnt(" #n ")" ::: "memory")
; #define PG8_WAIT_L(n) asm volatile("s_waitcnt lgkmcnt(" #n ")" ::: "memory")
; #define PG8_BAR __builtin_amdgcn_s_barrier()
; #define PG8_SCHED __builtin_amdgcn_sched_barrier(0)
; template <class Epi, class Sched, bool ALIGN_EPI = false, bool SP2 = false>
; __device__ __forceinline__ void gemm_phase(PG8_LAS unsigned char* lds, const Gemm g, const Sched& S, const Epi& E) {
;     ...
;         for (int t = 0; t < nt; t += 2) {
;             const bool last = (t == nt - 2);
;             const char* a1 = cA + (size_t)(t + 1) * kstep;
;             const char* a2 = last ? nA : cA + (size_t)(t + 2) * kstep; const char* b2 = last ? nB : cB + (size_t)(t + 2) * kstep;
;     ...
;             PG8_LDA(At, 1, 1); PG8_STAGE(PG8_SB(1, 0), b3, voffB); PG8_STAGE(PG8_SB(1, 1), b3 + hstep, voffB); PG8_STAGE(PG8_SA(1, 0), a3, voffA);
;             PG8_WAIT_V(8); PG8_WAIT_L(0); PG8_BAR; PG8_MMA(1, 0, At, B0); PG8_MMA(1, 1, At, B1); PG8_BAR; PG8_SCHED;
	s_add_u32 vcc_lo, s30, s2
	s_addc_u32 vcc_hi, s31, s3
	s_add_i32 s34, s78, s40
	s_mov_b32 m0, s34
	ds_read_b128 v[192:195], v170 offset:49152
	ds_read_b128 v[196:199], v170 offset:50176
	ds_read_b128 v[200:203], v170 offset:51200
	ds_read_b128 v[204:207], v170 offset:52224
	ds_read_b128 v[230:233], v170 offset:53248
	ds_read_b128 v[234:237], v170 offset:54272
	ds_read_b128 v[238:241], v170 offset:55296
	ds_read_b128 v[242:245], v170 offset:56320
	global_load_lds_dwordx4 v136, vcc
	s_add_i32 m0, s34, 0x2000
	s_add_u32 s30, s30, 0x80080
	s_addc_u32 s31, s31, 0
	s_add_i32 s34, s79, s40
	global_load_lds_dwordx4 v0, vcc
	s_mov_b32 m0, s34
	s_nop 0
	global_load_lds_dwordx4 v136, s[30:31]
	s_add_i32 m0, s34, 0x2000
	s_nop 0
	global_load_lds_dwordx4 v0, s[30:31]
	v_lshl_add_u64 v[158:159], v[248:249], 0, s[2:3]
	s_mov_b32 m0, s49
	s_nop 0
	global_load_lds_dwordx4 v[158:159], off
	v_lshl_add_u64 v[158:159], v[250:251], 0, s[2:3]
	s_mov_b32 m0, s50
	s_nop 0
	global_load_lds_dwordx4 v[158:159], off
	s_waitcnt vmcnt(8)
	s_waitcnt lgkmcnt(0)
	s_barrier
	s_setprio 1
	s_waitcnt lgkmcnt(0)
	v_mfma_f32_16x16x32_bf16 v[66:69], v[146:149], v[192:195], v[66:69]
	v_mfma_f32_16x16x32_bf16 v[62:65], v[166:169], v[192:195], v[62:65]
	v_mfma_f32_16x16x32_bf16 v[50:53], v[146:149], v[200:203], v[50:53]
	v_mfma_f32_16x16x32_bf16 v[46:49], v[166:169], v[200:203], v[46:49]
	v_mfma_f32_16x16x32_bf16 v[34:37], v[146:149], v[230:233], v[34:37]
	v_mfma_f32_16x16x32_bf16 v[30:33], v[166:169], v[230:233], v[30:33]
	v_mfma_f32_16x16x32_bf16 v[18:21], v[146:149], v[238:241], v[18:21]
	v_mfma_f32_16x16x32_bf16 v[14:17], v[166:169], v[238:241], v[14:17]
	v_mfma_f32_16x16x32_bf16 v[66:69], v[162:165], v[196:199], v[66:69]
	v_mfma_f32_16x16x32_bf16 v[62:65], v[172:175], v[196:199], v[62:65]
	v_mfma_f32_16x16x32_bf16 v[50:53], v[162:165], v[204:207], v[50:53]
	v_mfma_f32_16x16x32_bf16 v[46:49], v[172:175], v[204:207], v[46:49]
	v_mfma_f32_16x16x32_bf16 v[34:37], v[162:165], v[234:237], v[34:37]
	v_mfma_f32_16x16x32_bf16 v[30:33], v[172:175], v[234:237], v[30:33]
	v_mfma_f32_16x16x32_bf16 v[18:21], v[162:165], v[242:245], v[18:21]
	v_mfma_f32_16x16x32_bf16 v[14:17], v[172:175], v[242:245], v[14:17]
	s_setprio 0
	s_setprio 1
	v_mfma_f32_16x16x32_bf16 v[58:61], v[176:179], v[192:195], v[58:61]
	v_mfma_f32_16x16x32_bf16 v[54:57], v[184:187], v[192:195], v[54:57]
	v_mfma_f32_16x16x32_bf16 v[42:45], v[176:179], v[200:203], v[42:45]
	v_mfma_f32_16x16x32_bf16 v[38:41], v[184:187], v[200:203], v[38:41]
	v_mfma_f32_16x16x32_bf16 v[26:29], v[176:179], v[230:233], v[26:29]
	v_mfma_f32_16x16x32_bf16 v[22:25], v[184:187], v[230:233], v[22:25]
	v_mfma_f32_16x16x32_bf16 v[10:13], v[176:179], v[238:241], v[10:13]
	v_mfma_f32_16x16x32_bf16 v[6:9], v[184:187], v[238:241], v[6:9]
	v_mfma_f32_16x16x32_bf16 v[58:61], v[180:183], v[196:199], v[58:61]
	v_mfma_f32_16x16x32_bf16 v[54:57], v[188:191], v[196:199], v[54:57]
	v_mfma_f32_16x16x32_bf16 v[42:45], v[180:183], v[204:207], v[42:45]
	v_mfma_f32_16x16x32_bf16 v[38:41], v[188:191], v[204:207], v[38:41]
	v_mfma_f32_16x16x32_bf16 v[26:29], v[180:183], v[234:237], v[26:29]
	v_mfma_f32_16x16x32_bf16 v[22:25], v[188:191], v[234:237], v[22:25]
	v_mfma_f32_16x16x32_bf16 v[10:13], v[180:183], v[242:245], v[10:13]
	v_mfma_f32_16x16x32_bf16 v[6:9], v[188:191], v[242:245], v[6:9]
	s_setprio 0
	s_barrier
	s_add_i32 s71, s71, 2
	s_add_u32 s69, s69, 0x100
	s_addc_u32 s70, s70, 0
	s_add_u32 s10, s10, 0x100
	s_addc_u32 s11, s11, 0
	s_cmp_gt_u32 s71, 29
	s_cbranch_scc0 .LBB0_396
	s_and_b64 vcc, exec, s[18:19]
	s_cbranch_vccz .LBB0_399
	s_barrier

; #define PG8_STAGE(bufoff, gbase, voff) do { _Pragma("unroll") for (int _i = 0; _i < 2; ++_i) \
;         __builtin_amdgcn_global_load_lds((const unsigned*)((const char*)(gbase) + (voff)[_i]), (PG8_LAS unsigned*)(lds + (bufoff) + ldsw + _i * 8192), 16, 0, 0); } while (0)
; #define PG8_LDA(dst, b, h) do { _Pragma("unroll") for (int m = 0; m < 4; ++m) _Pragma("unroll") for (int k = 0; k < 2; ++k) dst[m][k] = *(const PG8_LAS bf16x8*)(lds + PG8_SA(b, h) + aoff + m * 2048 + k * 1024); } while (0)
; #define PG8_LDB(dst, b, h) do { _Pragma("unroll") for (int n = 0; n < 2; ++n) _Pragma("unroll") for (int k = 0; k < 2; ++k) dst[n][k] = *(const PG8_LAS bf16x8*)(lds + PG8_SB(b, h) + boff + n * 2048 + k * 1024); } while (0)
; #define PG8_MMA(ai, bj, At, Bt) do { __builtin_amdgcn_s_setprio(1); _Pragma("unroll") for (int m = 0; m < 4; ++m) _Pragma("unroll") for (int n = 0; n < 2; ++n) _Pragma("unroll") for (int k = 0; k < 2; ++k) \
;         acc[ai][bj][m][n] = __builtin_amdgcn_mfma_f32_16x16x32_bf16(Bt[n][k], At[m][k], acc[ai][bj][m][n], 0, 0, 0); __builtin_amdgcn_s_setprio(0); } while (0)
; #define PG8_WAIT_V(n) asm volatile("s_waitcnt vmcnt(" #n ")" ::: "memory")
; #define PG8_WAIT_L(n) asm volatile("s_waitcnt lgkmcnt(" #n ")" ::: "memory")
; #define PG8_BAR __builtin_amdgcn_s_barrier()
; #define PG8_SCHED __builtin_amdgcn_sched_barrier(0)
; template <class Epi, class Sched, bool ALIGN_EPI = false, bool SP2 = false>
; __device__ __forceinline__ void gemm_phase(PG8_LAS unsigned char* lds, const Gemm g, const Sched& S, const Epi& E) {
;     ...
;             const bool last = (t == nt - 2);
;             const char* a1 = cA + (size_t)(t + 1) * kstep;
;             const char* a2 = last ? nA : cA + (size_t)(t + 2) * kstep; const char* b2 = last ? nB : cB + (size_t)(t + 2) * kstep;
;             const char* a3 = a2 + kstep; const char* b3 = b2 + kstep;
;             if (last && has_next) S.a_ready(nxt);
;             if constexpr (SP2) {
;             PG8_LDB(B0, 0, 0); PG8_LDB(B1, 0, 1); PG8_SCHED; PG8_LDA(At, 0, 0); PG8_STAGE(PG8_SA(1, 1), a1 + hstep, voffA);
;             PG8_WAIT_V(8); PG8_WAIT_L(0); PG8_BAR; PG8_MMA(0, 0, At, B0); PG8_MMA(0, 1, At, B1); PG8_BAR; PG8_SCHED;
;             PG8_LDA(At, 0, 1); PG8_STAGE(PG8_SB(0, 0), b2, voffB); PG8_STAGE(PG8_SB(0, 1), b2 + hstep, voffB); PG8_STAGE(PG8_SA(0, 0), a2, voffA);
.LBB0_818:
	s_add_u32 s30, s26, 0xfffc0080
	s_addc_u32 s31, s27, -1
	s_add_i32 s78, 0, 0x10000
	s_cmp_eq_u32 s71, 12
	s_cselect_b32 s35, s21, s31
	s_cselect_b32 s34, s66, s30
	v_add_u32_e32 v149, s78, v146
	s_cselect_b32 s31, s19, s70
	s_cselect_b32 s30, s67, s69
	s_add_i32 s80, 0, 0x14000
	ds_read_b128 v[142:145], v149
	ds_read_b128 v[162:165], v149 offset:1024
	ds_read_b128 v[166:169], v149 offset:2048
	ds_read_b128 v[170:173], v149 offset:3072
	v_add_u32_e32 v149, s80, v146
	ds_read_b128 v[174:177], v149
	ds_read_b128 v[178:181], v149 offset:1024
	ds_read_b128 v[182:185], v149 offset:2048
	ds_read_b128 v[186:189], v149 offset:3072
	s_add_i32 m0, s44, 0xc000
	ds_read_b128 v[190:193], v148
	ds_read_b128 v[194:197], v148 offset:1024
	ds_read_b128 v[198:201], v148 offset:2048
	ds_read_b128 v[202:205], v148 offset:3072
	ds_read_b128 v[230:233], v148 offset:4096
	ds_read_b128 v[234:237], v148 offset:5120
	ds_read_b128 v[238:241], v148 offset:6144
	ds_read_b128 v[242:245], v148 offset:7168
	global_load_lds_dwordx4 v140, s[26:27]
	s_add_i32 m0, s44, 0xe000
	s_nop 0
	global_load_lds_dwordx4 v138, s[26:27]
	s_waitcnt vmcnt(8)
	s_waitcnt lgkmcnt(0)
	s_barrier
	s_setprio 1
	s_waitcnt lgkmcnt(0)
	v_mfma_f32_16x16x32_bf16 v[130:133], v[142:145], v[190:193], v[130:133]
	v_mfma_f32_16x16x32_bf16 v[126:129], v[166:169], v[190:193], v[126:129]
	v_mfma_f32_16x16x32_bf16 v[118:121], v[142:145], v[198:201], v[118:121]
	v_mfma_f32_16x16x32_bf16 v[110:113], v[166:169], v[198:201], v[110:113]
	v_mfma_f32_16x16x32_bf16 v[98:101], v[142:145], v[230:233], v[98:101]
	v_mfma_f32_16x16x32_bf16 v[94:97], v[166:169], v[230:233], v[94:97]
	v_mfma_f32_16x16x32_bf16 v[82:85], v[142:145], v[238:241], v[82:85]
	v_mfma_f32_16x16x32_bf16 v[78:81], v[166:169], v[238:241], v[78:81]
	v_mfma_f32_16x16x32_bf16 v[130:133], v[162:165], v[194:197], v[130:133]
	v_mfma_f32_16x16x32_bf16 v[126:129], v[170:173], v[194:197], v[126:129]
	v_mfma_f32_16x16x32_bf16 v[118:121], v[162:165], v[202:205], v[118:121]
	v_mfma_f32_16x16x32_bf16 v[110:113], v[170:173], v[202:205], v[110:113]
	v_mfma_f32_16x16x32_bf16 v[98:101], v[162:165], v[234:237], v[98:101]
	v_mfma_f32_16x16x32_bf16 v[94:97], v[170:173], v[234:237], v[94:97]
	v_mfma_f32_16x16x32_bf16 v[82:85], v[162:165], v[242:245], v[82:85]
	v_mfma_f32_16x16x32_bf16 v[78:81], v[170:173], v[242:245], v[78:81]
	s_setprio 0
	s_setprio 1
	v_mfma_f32_16x16x32_bf16 v[122:125], v[174:177], v[190:193], v[122:125]
	v_mfma_f32_16x16x32_bf16 v[114:117], v[182:185], v[190:193], v[114:117]
	v_mfma_f32_16x16x32_bf16 v[106:109], v[174:177], v[198:201], v[106:109]
	v_mfma_f32_16x16x32_bf16 v[102:105], v[182:185], v[198:201], v[102:105]
	v_mfma_f32_16x16x32_bf16 v[90:93], v[174:177], v[230:233], v[90:93]
	v_mfma_f32_16x16x32_bf16 v[86:89], v[182:185], v[230:233], v[86:89]
	v_mfma_f32_16x16x32_bf16 v[74:77], v[174:177], v[238:241], v[74:77]
	v_mfma_f32_16x16x32_bf16 v[70:73], v[182:185], v[238:241], v[70:73]
	v_mfma_f32_16x16x32_bf16 v[122:125], v[178:181], v[194:197], v[122:125]
	v_mfma_f32_16x16x32_bf16 v[114:117], v[186:189], v[194:197], v[114:117]
	v_mfma_f32_16x16x32_bf16 v[106:109], v[178:181], v[202:205], v[106:109]
	v_mfma_f32_16x16x32_bf16 v[102:105], v[186:189], v[202:205], v[102:105]
	v_mfma_f32_16x16x32_bf16 v[90:93], v[178:181], v[234:237], v[90:93]
	v_mfma_f32_16x16x32_bf16 v[86:89], v[186:189], v[234:237], v[86:89]
	v_mfma_f32_16x16x32_bf16 v[74:77], v[178:181], v[242:245], v[74:77]
	v_mfma_f32_16x16x32_bf16 v[70:73], v[186:189], v[242:245], v[70:73]
	s_setprio 0
	s_barrier
	s_add_i32 s78, s78, s41
	s_mov_b32 m0, s78
	ds_read_b128 v[190:193], v148 offset:16384
	ds_read_b128 v[194:197], v148 offset:17408
	ds_read_b128 v[198:201], v148 offset:18432
	ds_read_b128 v[202:205], v148 offset:19456
	ds_read_b128 v[230:233], v148 offset:20480
	ds_read_b128 v[234:237], v148 offset:21504
	ds_read_b128 v[238:241], v148 offset:22528
	ds_read_b128 v[242:245], v148 offset:23552
	global_load_lds_dwordx4 v2, s[30:31]
	s_add_i32 m0, s78, 0x2000
	s_add_u32 s78, s30, 0x40000
	s_addc_u32 s79, s31, 0
	s_add_i32 s80, s80, s41
	global_load_lds_dwordx4 v0, s[30:31]
	s_mov_b32 m0, s80
	v_lshl_add_u64 v[246:247], s[34:35], 0, v[134:135]
	global_load_lds_dwordx4 v2, s[78:79]
	s_add_i32 m0, s80, 0x2000
	s_nop 0
	global_load_lds_dwordx4 v0, s[78:79]
	v_lshl_add_u64 v[206:207], s[34:35], 0, v[136:137]
	s_mov_b32 m0, s44
	s_nop 0
	global_load_lds_dwordx4 v136, s[34:35]
	s_mov_b32 m0, s45
	s_nop 0
	global_load_lds_dwordx4 v134, s[34:35]
	s_waitcnt vmcnt(8)
	s_waitcnt lgkmcnt(0)
	s_barrier
; #define PG8_STAGE(bufoff, gbase, voff) do { _Pragma("unroll") for (int _i = 0; _i < 2; ++_i) \
;         __builtin_amdgcn_global_load_lds((const unsigned*)((const char*)(gbase) + (voff)[_i]), (PG8_LAS unsigned*)(lds + (bufoff) + ldsw + _i * 8192), 16, 0, 0); } while (0)
; #define PG8_LDA(dst, b, h) do { _Pragma("unroll") for (int m = 0; m < 4; ++m) _Pragma("unroll") for (int k = 0; k < 2; ++k) dst[m][k] = *(const PG8_LAS bf16x8*)(lds + PG8_SA(b, h) + aoff + m * 2048 + k * 1024); } while (0)
; #define PG8_LDB(dst, b, h) do { _Pragma("unroll") for (int n = 0; n < 2; ++n) _Pragma("unroll") for (int k = 0; k < 2; ++k) dst[n][k] = *(const PG8_LAS bf16x8*)(lds + PG8_SB(b, h) + boff + n * 2048 + k * 1024); } while (0)
; #define PG8_MMA(ai, bj, At, Bt) do { __builtin_amdgcn_s_setprio(1); _Pragma("unroll") for (int m = 0; m < 4; ++m) _Pragma("unroll") for (int n = 0; n < 2; ++n) _Pragma("unroll") for (int k = 0; k < 2; ++k) \
;         acc[ai][bj][m][n] = __builtin_amdgcn_mfma_f32_16x16x32_bf16(Bt[n][k], At[m][k], acc[ai][bj][m][n], 0, 0, 0); __builtin_amdgcn_s_setprio(0); } while (0)
; #define PG8_WAIT_V(n) asm volatile("s_waitcnt vmcnt(" #n ")" ::: "memory")
; #define PG8_WAIT_L(n) asm volatile("s_waitcnt lgkmcnt(" #n ")" ::: "memory")
; #define PG8_BAR __builtin_amdgcn_s_barrier()
; #define PG8_SCHED __builtin_amdgcn_sched_barrier(0)
; template <class Epi, class Sched, bool ALIGN_EPI = false, bool SP2 = false>
; __device__ __forceinline__ void gemm_phase(PG8_LAS unsigned char* lds, const Gemm g, const Sched& S, const Epi& E) {
;     ...
;             PG8_WAIT_V(8); PG8_WAIT_L(0); PG8_BAR; PG8_MMA(1, 0, At, B0); PG8_MMA(1, 1, At, B1); PG8_BAR; PG8_SCHED;
;             PG8_LDB(B0, 1, 0); PG8_LDB(B1, 1, 1); PG8_SCHED; PG8_LDA(At, 1, 0); PG8_STAGE(PG8_SA(0, 1), a2 + hstep, voffA);
;             PG8_WAIT_V(8); PG8_WAIT_L(0); PG8_BAR; PG8_MMA(0, 0, At, B0); PG8_MMA(0, 1, At, B1); PG8_BAR; PG8_SCHED;
	s_setprio 1
	s_waitcnt lgkmcnt(0)
	v_mfma_f32_16x16x32_bf16 v[66:69], v[142:145], v[190:193], v[66:69]
	v_mfma_f32_16x16x32_bf16 v[62:65], v[166:169], v[190:193], v[62:65]
	v_mfma_f32_16x16x32_bf16 v[50:53], v[142:145], v[198:201], v[50:53]
	v_mfma_f32_16x16x32_bf16 v[46:49], v[166:169], v[198:201], v[46:49]
	v_mfma_f32_16x16x32_bf16 v[34:37], v[142:145], v[230:233], v[34:37]
	v_mfma_f32_16x16x32_bf16 v[30:33], v[166:169], v[230:233], v[30:33]
	v_mfma_f32_16x16x32_bf16 v[18:21], v[142:145], v[238:241], v[18:21]
	v_mfma_f32_16x16x32_bf16 v[14:17], v[166:169], v[238:241], v[14:17]
	v_mfma_f32_16x16x32_bf16 v[66:69], v[162:165], v[194:197], v[66:69]
	v_mfma_f32_16x16x32_bf16 v[62:65], v[170:173], v[194:197], v[62:65]
	v_mfma_f32_16x16x32_bf16 v[50:53], v[162:165], v[202:205], v[50:53]
	v_mfma_f32_16x16x32_bf16 v[46:49], v[170:173], v[202:205], v[46:49]
	v_mfma_f32_16x16x32_bf16 v[34:37], v[162:165], v[234:237], v[34:37]
	v_mfma_f32_16x16x32_bf16 v[30:33], v[170:173], v[234:237], v[30:33]
	v_mfma_f32_16x16x32_bf16 v[18:21], v[162:165], v[242:245], v[18:21]
	v_mfma_f32_16x16x32_bf16 v[14:17], v[170:173], v[242:245], v[14:17]
	s_setprio 0
	s_setprio 1
	v_mfma_f32_16x16x32_bf16 v[58:61], v[174:177], v[190:193], v[58:61]
	v_mfma_f32_16x16x32_bf16 v[54:57], v[182:185], v[190:193], v[54:57]
	v_mfma_f32_16x16x32_bf16 v[42:45], v[174:177], v[198:201], v[42:45]
	v_mfma_f32_16x16x32_bf16 v[38:41], v[182:185], v[198:201], v[38:41]
	v_mfma_f32_16x16x32_bf16 v[26:29], v[174:177], v[230:233], v[26:29]
	v_mfma_f32_16x16x32_bf16 v[22:25], v[182:185], v[230:233], v[22:25]
	v_mfma_f32_16x16x32_bf16 v[10:13], v[174:177], v[238:241], v[10:13]
	v_mfma_f32_16x16x32_bf16 v[6:9], v[182:185], v[238:241], v[6:9]
	v_mfma_f32_16x16x32_bf16 v[58:61], v[178:181], v[194:197], v[58:61]
	v_mfma_f32_16x16x32_bf16 v[54:57], v[186:189], v[194:197], v[54:57]
	v_mfma_f32_16x16x32_bf16 v[42:45], v[178:181], v[202:205], v[42:45]
	v_mfma_f32_16x16x32_bf16 v[38:41], v[186:189], v[202:205], v[38:41]
	v_mfma_f32_16x16x32_bf16 v[26:29], v[178:181], v[234:237], v[26:29]
	v_mfma_f32_16x16x32_bf16 v[22:25], v[186:189], v[234:237], v[22:25]
	v_mfma_f32_16x16x32_bf16 v[10:13], v[178:181], v[242:245], v[10:13]
	v_mfma_f32_16x16x32_bf16 v[6:9], v[186:189], v[242:245], v[6:9]
	s_setprio 0
	s_barrier
	s_add_i32 s78, 0, 0x18000
	v_add_u32_e32 v149, s78, v146
	s_add_i32 s79, 0, 0x1c000
	ds_read_b128 v[142:145], v149
	ds_read_b128 v[162:165], v149 offset:1024
	ds_read_b128 v[166:169], v149 offset:2048
	ds_read_b128 v[170:173], v149 offset:3072
	v_add_u32_e32 v149, s79, v146
	ds_read_b128 v[174:177], v149
	ds_read_b128 v[178:181], v149 offset:1024
	ds_read_b128 v[182:185], v149 offset:2048
	ds_read_b128 v[186:189], v149 offset:3072
	s_add_u32 s34, s34, 0x40000
	s_addc_u32 s35, s35, 0
	s_mov_b32 m0, s46
	ds_read_b128 v[190:193], v148 offset:32768
	ds_read_b128 v[194:197], v148 offset:33792
	ds_read_b128 v[198:201], v148 offset:34816
	ds_read_b128 v[202:205], v148 offset:35840
	ds_read_b128 v[230:233], v148 offset:36864
	ds_read_b128 v[234:237], v148 offset:37888
	ds_read_b128 v[238:241], v148 offset:38912
	ds_read_b128 v[242:245], v148 offset:39936
	global_load_lds_dwordx4 v136, s[34:35]
	s_mov_b32 m0, s47
	s_nop 0
	global_load_lds_dwordx4 v134, s[34:35]
	s_waitcnt vmcnt(8)
	s_waitcnt lgkmcnt(0)
	s_barrier
	s_setprio 1
	s_waitcnt lgkmcnt(0)
	v_mfma_f32_16x16x32_bf16 v[130:133], v[142:145], v[190:193], v[130:133]
	v_mfma_f32_16x16x32_bf16 v[126:129], v[166:169], v[190:193], v[126:129]
	v_mfma_f32_16x16x32_bf16 v[118:121], v[142:145], v[198:201], v[118:121]
	v_mfma_f32_16x16x32_bf16 v[110:113], v[166:169], v[198:201], v[110:113]
	v_mfma_f32_16x16x32_bf16 v[98:101], v[142:145], v[230:233], v[98:101]
	v_mfma_f32_16x16x32_bf16 v[94:97], v[166:169], v[230:233], v[94:97]
	v_mfma_f32_16x16x32_bf16 v[82:85], v[142:145], v[238:241], v[82:85]
	v_mfma_f32_16x16x32_bf16 v[78:81], v[166:169], v[238:241], v[78:81]
	v_mfma_f32_16x16x32_bf16 v[130:133], v[162:165], v[194:197], v[130:133]
	v_mfma_f32_16x16x32_bf16 v[126:129], v[170:173], v[194:197], v[126:129]
	v_mfma_f32_16x16x32_bf16 v[118:121], v[162:165], v[202:205], v[118:121]
	v_mfma_f32_16x16x32_bf16 v[110:113], v[170:173], v[202:205], v[110:113]
	v_mfma_f32_16x16x32_bf16 v[98:101], v[162:165], v[234:237], v[98:101]
	v_mfma_f32_16x16x32_bf16 v[94:97], v[170:173], v[234:237], v[94:97]
	v_mfma_f32_16x16x32_bf16 v[82:85], v[162:165], v[242:245], v[82:85]
	v_mfma_f32_16x16x32_bf16 v[78:81], v[170:173], v[242:245], v[78:81]
	s_setprio 0
	s_setprio 1
	v_mfma_f32_16x16x32_bf16 v[122:125], v[174:177], v[190:193], v[122:125]
	v_mfma_f32_16x16x32_bf16 v[114:117], v[182:185], v[190:193], v[114:117]
	v_mfma_f32_16x16x32_bf16 v[106:109], v[174:177], v[198:201], v[106:109]
	v_mfma_f32_16x16x32_bf16 v[102:105], v[182:185], v[198:201], v[102:105]
	v_mfma_f32_16x16x32_bf16 v[90:93], v[174:177], v[230:233], v[90:93]
	v_mfma_f32_16x16x32_bf16 v[86:89], v[182:185], v[230:233], v[86:89]
	v_mfma_f32_16x16x32_bf16 v[74:77], v[174:177], v[238:241], v[74:77]
	v_mfma_f32_16x16x32_bf16 v[70:73], v[182:185], v[238:241], v[70:73]
	v_mfma_f32_16x16x32_bf16 v[122:125], v[178:181], v[194:197], v[122:125]
	v_mfma_f32_16x16x32_bf16 v[114:117], v[186:189], v[194:197], v[114:117]
	v_mfma_f32_16x16x32_bf16 v[106:109], v[178:181], v[202:205], v[106:109]
	v_mfma_f32_16x16x32_bf16 v[102:105], v[186:189], v[202:205], v[102:105]
	v_mfma_f32_16x16x32_bf16 v[90:93], v[178:181], v[234:237], v[90:93]
	v_mfma_f32_16x16x32_bf16 v[86:89], v[186:189], v[234:237], v[86:89]
	v_mfma_f32_16x16x32_bf16 v[74:77], v[178:181], v[242:245], v[74:77]
	v_mfma_f32_16x16x32_bf16 v[70:73], v[186:189], v[242:245], v[70:73]
	s_setprio 0
	s_barrier
; #define PG8_STAGE(bufoff, gbase, voff) do { _Pragma("unroll") for (int _i = 0; _i < 2; ++_i) \
;         __builtin_amdgcn_global_load_lds((const unsigned*)((const char*)(gbase) + (voff)[_i]), (PG8_LAS unsigned*)(lds + (bufoff) + ldsw + _i * 8192), 16, 0, 0); } while (0)
; #define PG8_LDA(dst, b, h) do { _Pragma("unroll") for (int m = 0; m < 4; ++m) _Pragma("unroll") for (int k = 0; k < 2; ++k) dst[m][k] = *(const PG8_LAS bf16x8*)(lds + PG8_SA(b, h) + aoff + m * 2048 + k * 1024); } while (0)
; #define PG8_MMA(ai, bj, At, Bt) do { __builtin_amdgcn_s_setprio(1); _Pragma("unroll") for (int m = 0; m < 4; ++m) _Pragma("unroll") for (int n = 0; n < 2; ++n) _Pragma("unroll") for (int k = 0; k < 2; ++k) \
;         acc[ai][bj][m][n] = __builtin_amdgcn_mfma_f32_16x16x32_bf16(Bt[n][k], At[m][k], acc[ai][bj][m][n], 0, 0, 0); __builtin_amdgcn_s_setprio(0); } while (0)
; #define PG8_WAIT_V(n) asm volatile("s_waitcnt vmcnt(" #n ")" ::: "memory")
; #define PG8_WAIT_L(n) asm volatile("s_waitcnt lgkmcnt(" #n ")" ::: "memory")
; #define PG8_BAR __builtin_amdgcn_s_barrier()
; #define PG8_SCHED __builtin_amdgcn_sched_barrier(0)
; template <class Epi, class Sched, bool ALIGN_EPI = false, bool SP2 = false>
; __device__ __forceinline__ void gemm_phase(PG8_LAS unsigned char* lds, const Gemm g, const Sched& S, const Epi& E) {
;     ...
;         for (int t = 0; t < nt; t += 2) {
;             const bool last = (t == nt - 2);
;             const char* a1 = cA + (size_t)(t + 1) * kstep;
;             const char* a2 = last ? nA : cA + (size_t)(t + 2) * kstep; const char* b2 = last ? nB : cB + (size_t)(t + 2) * kstep;
;     ...
;             PG8_LDA(At, 1, 1); PG8_STAGE(PG8_SB(1, 0), b3, voffB); PG8_STAGE(PG8_SB(1, 1), b3 + hstep, voffB); PG8_STAGE(PG8_SA(1, 0), a3, voffA);
;             PG8_WAIT_V(8); PG8_WAIT_L(0); PG8_BAR; PG8_MMA(1, 0, At, B0); PG8_MMA(1, 1, At, B1); PG8_BAR; PG8_SCHED;
	s_add_u32 vcc_lo, s30, s2
	s_addc_u32 vcc_hi, s31, s3
	s_add_i32 s34, s78, s41
	s_mov_b32 m0, s34
	ds_read_b128 v[190:193], v148 offset:49152
	ds_read_b128 v[194:197], v148 offset:50176
	ds_read_b128 v[198:201], v148 offset:51200
	ds_read_b128 v[202:205], v148 offset:52224
	ds_read_b128 v[230:233], v148 offset:53248
	ds_read_b128 v[234:237], v148 offset:54272
	ds_read_b128 v[238:241], v148 offset:55296
	ds_read_b128 v[242:245], v148 offset:56320
	global_load_lds_dwordx4 v2, vcc
	s_add_i32 m0, s34, 0x2000
	s_add_u32 s30, s30, 0x40080
	s_addc_u32 s31, s31, 0
	s_add_i32 s34, s79, s41
	global_load_lds_dwordx4 v0, vcc
	s_mov_b32 m0, s34
	s_nop 0
	global_load_lds_dwordx4 v2, s[30:31]
	s_add_i32 m0, s34, 0x2000
	s_nop 0
	global_load_lds_dwordx4 v0, s[30:31]
	v_lshl_add_u64 v[158:159], v[206:207], 0, s[2:3]
	s_mov_b32 m0, s48
	s_nop 0
	global_load_lds_dwordx4 v[158:159], off
	v_lshl_add_u64 v[158:159], v[246:247], 0, s[2:3]
	s_mov_b32 m0, s49
	s_nop 0
	global_load_lds_dwordx4 v[158:159], off
	s_waitcnt vmcnt(8)
	s_waitcnt lgkmcnt(0)
	s_barrier
	s_setprio 1
	s_waitcnt lgkmcnt(0)
	v_mfma_f32_16x16x32_bf16 v[66:69], v[142:145], v[190:193], v[66:69]
	v_mfma_f32_16x16x32_bf16 v[62:65], v[166:169], v[190:193], v[62:65]
	v_mfma_f32_16x16x32_bf16 v[50:53], v[142:145], v[198:201], v[50:53]
	v_mfma_f32_16x16x32_bf16 v[46:49], v[166:169], v[198:201], v[46:49]
	v_mfma_f32_16x16x32_bf16 v[34:37], v[142:145], v[230:233], v[34:37]
	v_mfma_f32_16x16x32_bf16 v[30:33], v[166:169], v[230:233], v[30:33]
	v_mfma_f32_16x16x32_bf16 v[18:21], v[142:145], v[238:241], v[18:21]
	v_mfma_f32_16x16x32_bf16 v[14:17], v[166:169], v[238:241], v[14:17]
	v_mfma_f32_16x16x32_bf16 v[66:69], v[162:165], v[194:197], v[66:69]
	v_mfma_f32_16x16x32_bf16 v[62:65], v[170:173], v[194:197], v[62:65]
	v_mfma_f32_16x16x32_bf16 v[50:53], v[162:165], v[202:205], v[50:53]
	v_mfma_f32_16x16x32_bf16 v[46:49], v[170:173], v[202:205], v[46:49]
	v_mfma_f32_16x16x32_bf16 v[34:37], v[162:165], v[234:237], v[34:37]
	v_mfma_f32_16x16x32_bf16 v[30:33], v[170:173], v[234:237], v[30:33]
	v_mfma_f32_16x16x32_bf16 v[18:21], v[162:165], v[242:245], v[18:21]
	v_mfma_f32_16x16x32_bf16 v[14:17], v[170:173], v[242:245], v[14:17]
	s_setprio 0
	s_setprio 1
	v_mfma_f32_16x16x32_bf16 v[58:61], v[174:177], v[190:193], v[58:61]
	v_mfma_f32_16x16x32_bf16 v[54:57], v[182:185], v[190:193], v[54:57]
	v_mfma_f32_16x16x32_bf16 v[42:45], v[174:177], v[198:201], v[42:45]
	v_mfma_f32_16x16x32_bf16 v[38:41], v[182:185], v[198:201], v[38:41]
	v_mfma_f32_16x16x32_bf16 v[26:29], v[174:177], v[230:233], v[26:29]
	v_mfma_f32_16x16x32_bf16 v[22:25], v[182:185], v[230:233], v[22:25]
	v_mfma_f32_16x16x32_bf16 v[10:13], v[174:177], v[238:241], v[10:13]
	v_mfma_f32_16x16x32_bf16 v[6:9], v[182:185], v[238:241], v[6:9]
	v_mfma_f32_16x16x32_bf16 v[58:61], v[178:181], v[194:197], v[58:61]
	v_mfma_f32_16x16x32_bf16 v[54:57], v[186:189], v[194:197], v[54:57]
	v_mfma_f32_16x16x32_bf16 v[42:45], v[178:181], v[202:205], v[42:45]
	v_mfma_f32_16x16x32_bf16 v[38:41], v[186:189], v[202:205], v[38:41]
	v_mfma_f32_16x16x32_bf16 v[26:29], v[178:181], v[234:237], v[26:29]
	v_mfma_f32_16x16x32_bf16 v[22:25], v[186:189], v[234:237], v[22:25]
	v_mfma_f32_16x16x32_bf16 v[10:13], v[178:181], v[242:245], v[10:13]
	v_mfma_f32_16x16x32_bf16 v[6:9], v[186:189], v[242:245], v[6:9]
	s_setprio 0
	s_barrier
	s_add_i32 s71, s71, 2
	s_add_u32 s69, s69, 0x100
	s_addc_u32 s70, s70, 0
	s_add_u32 s26, s26, 0x100
	s_addc_u32 s27, s27, 0
	s_cmp_gt_u32 s71, 13
	s_cbranch_scc0 .LBB0_818
	s_and_b64 vcc, exec, s[16:17]
	s_cbranch_vccz .LBB0_821
	s_barrier

; #define PG8_STAGE(bufoff, gbase, voff) do { _Pragma("unroll") for (int _i = 0; _i < 2; ++_i) \
;         __builtin_amdgcn_global_load_lds((const unsigned*)((const char*)(gbase) + (voff)[_i]), (PG8_LAS unsigned*)(lds + (bufoff) + ldsw + _i * 8192), 16, 0, 0); } while (0)
; #define PG8_LDA(dst, b, h) do { _Pragma("unroll") for (int m = 0; m < 4; ++m) _Pragma("unroll") for (int k = 0; k < 2; ++k) dst[m][k] = *(const PG8_LAS bf16x8*)(lds + PG8_SA(b, h) + aoff + m * 2048 + k * 1024); } while (0)
; #define PG8_LDB(dst, b, h) do { _Pragma("unroll") for (int n = 0; n < 2; ++n) _Pragma("unroll") for (int k = 0; k < 2; ++k) dst[n][k] = *(const PG8_LAS bf16x8*)(lds + PG8_SB(b, h) + boff + n * 2048 + k * 1024); } while (0)
; #define PG8_MMA(ai, bj, At, Bt) do { __builtin_amdgcn_s_setprio(1); _Pragma("unroll") for (int m = 0; m < 4; ++m) _Pragma("unroll") for (int n = 0; n < 2; ++n) _Pragma("unroll") for (int k = 0; k < 2; ++k) \
;         acc[ai][bj][m][n] = __builtin_amdgcn_mfma_f32_16x16x32_bf16(Bt[n][k], At[m][k], acc[ai][bj][m][n], 0, 0, 0); __builtin_amdgcn_s_setprio(0); } while (0)
; #define PG8_WAIT_V(n) asm volatile("s_waitcnt vmcnt(" #n ")" ::: "memory")
; #define PG8_WAIT_L(n) asm volatile("s_waitcnt lgkmcnt(" #n ")" ::: "memory")
; #define PG8_BAR __builtin_amdgcn_s_barrier()
; #define PG8_SCHED __builtin_amdgcn_sched_barrier(0)
; template <class Epi, class Sched, bool ALIGN_EPI = false, bool SP2 = false>
; __device__ __forceinline__ void gemm_phase(PG8_LAS unsigned char* lds, const Gemm g, const Sched& S, const Epi& E) {
;     ...
;             const bool last = (t == nt - 2);
;             const char* a1 = cA + (size_t)(t + 1) * kstep;
;             const char* a2 = last ? nA : cA + (size_t)(t + 2) * kstep; const char* b2 = last ? nB : cB + (size_t)(t + 2) * kstep;
;             const char* a3 = a2 + kstep; const char* b3 = b2 + kstep;
;             if (last && has_next) S.a_ready(nxt);
;             if constexpr (SP2) {
;             PG8_LDB(B0, 0, 0); PG8_LDB(B1, 0, 1); PG8_SCHED; PG8_LDA(At, 0, 0); PG8_STAGE(PG8_SA(1, 1), a1 + hstep, voffA);
;             PG8_WAIT_V(8); PG8_WAIT_L(0); PG8_BAR; PG8_MMA(0, 0, At, B0); PG8_MMA(0, 1, At, B1); PG8_BAR; PG8_SCHED;
;             PG8_LDA(At, 0, 1); PG8_STAGE(PG8_SB(0, 0), b2, voffB); PG8_STAGE(PG8_SB(0, 1), b2 + hstep, voffB); PG8_STAGE(PG8_SA(0, 0), a2, voffA);
.LBB0_905:
	s_add_u32 s30, s26, 0x100
	s_addc_u32 s31, s27, 0
	s_add_i32 s83, 0, 0x10000
	s_cmp_eq_u32 s82, 28
	s_cselect_b32 s41, s21, s31
	s_cselect_b32 s40, s78, s30
	s_cselect_b32 s35, s19, s81
	s_cselect_b32 s34, s79, s80
	s_add_i32 s84, 0, 0x14000
	v_add_u32_e32 v98, s83, v152
	v_add_u32_e32 v158, s84, v152
	ds_read_b128 v[78:81], v98
	ds_read_b128 v[86:89], v98 offset:1024
	ds_read_b128 v[94:97], v98 offset:2048
	ds_read_b128 v[98:101], v98 offset:3072
	ds_read_b128 v[166:169], v158
	ds_read_b128 v[174:177], v158 offset:1024
	ds_read_b128 v[178:181], v158 offset:2048
	ds_read_b128 v[182:185], v158 offset:3072
	s_add_i32 m0, s49, 0xc000
	ds_read_b128 v[186:189], v173
	ds_read_b128 v[190:193], v173 offset:1024
	ds_read_b128 v[194:197], v173 offset:2048
	ds_read_b128 v[198:201], v173 offset:3072
	ds_read_b128 v[202:205], v173 offset:4096
	ds_read_b128 v[230:233], v173 offset:5120
	ds_read_b128 v[234:237], v173 offset:6144
	ds_read_b128 v[238:241], v173 offset:7168
	global_load_lds_dwordx4 v164, s[26:27]
	s_add_i32 m0, s49, 0xe000
	s_nop 0
	global_load_lds_dwordx4 v162, s[26:27]
	s_waitcnt vmcnt(8)
	s_waitcnt lgkmcnt(0)
	s_barrier
	s_setprio 1
	s_waitcnt lgkmcnt(0)
	v_mfma_f32_16x16x32_bf16 v[146:149], v[78:81], v[186:189], v[146:149]
	v_mfma_f32_16x16x32_bf16 v[142:145], v[94:97], v[186:189], v[142:145]
	v_mfma_f32_16x16x32_bf16 v[130:133], v[78:81], v[194:197], v[130:133]
	v_mfma_f32_16x16x32_bf16 v[126:129], v[94:97], v[194:197], v[126:129]
	v_mfma_f32_16x16x32_bf16 v[114:117], v[78:81], v[202:205], v[114:117]
	v_mfma_f32_16x16x32_bf16 v[110:113], v[94:97], v[202:205], v[110:113]
	v_mfma_f32_16x16x32_bf16 v[90:93], v[78:81], v[234:237], v[90:93]
	v_mfma_f32_16x16x32_bf16 v[82:85], v[94:97], v[234:237], v[82:85]
	v_mfma_f32_16x16x32_bf16 v[146:149], v[86:89], v[190:193], v[146:149]
	v_mfma_f32_16x16x32_bf16 v[142:145], v[98:101], v[190:193], v[142:145]
	v_mfma_f32_16x16x32_bf16 v[130:133], v[86:89], v[198:201], v[130:133]
	v_mfma_f32_16x16x32_bf16 v[126:129], v[98:101], v[198:201], v[126:129]
	v_mfma_f32_16x16x32_bf16 v[114:117], v[86:89], v[230:233], v[114:117]
	v_mfma_f32_16x16x32_bf16 v[110:113], v[98:101], v[230:233], v[110:113]
	v_mfma_f32_16x16x32_bf16 v[90:93], v[86:89], v[238:241], v[90:93]
	v_mfma_f32_16x16x32_bf16 v[82:85], v[98:101], v[238:241], v[82:85]
	s_setprio 0
	s_setprio 1
	v_mfma_f32_16x16x32_bf16 v[138:141], v[166:169], v[186:189], v[138:141]
	v_mfma_f32_16x16x32_bf16 v[134:137], v[178:181], v[186:189], v[134:137]
	v_mfma_f32_16x16x32_bf16 v[122:125], v[166:169], v[194:197], v[122:125]
	v_mfma_f32_16x16x32_bf16 v[118:121], v[178:181], v[194:197], v[118:121]
	v_mfma_f32_16x16x32_bf16 v[106:109], v[166:169], v[202:205], v[106:109]
	v_mfma_f32_16x16x32_bf16 v[102:105], v[178:181], v[202:205], v[102:105]
	v_mfma_f32_16x16x32_bf16 v[74:77], v[166:169], v[234:237], v[74:77]
	v_mfma_f32_16x16x32_bf16 v[70:73], v[178:181], v[234:237], v[70:73]
	v_mfma_f32_16x16x32_bf16 v[138:141], v[174:177], v[190:193], v[138:141]
	v_mfma_f32_16x16x32_bf16 v[134:137], v[182:185], v[190:193], v[134:137]
	v_mfma_f32_16x16x32_bf16 v[122:125], v[174:177], v[198:201], v[122:125]
	v_mfma_f32_16x16x32_bf16 v[118:121], v[182:185], v[198:201], v[118:121]
	v_mfma_f32_16x16x32_bf16 v[106:109], v[174:177], v[230:233], v[106:109]
	v_mfma_f32_16x16x32_bf16 v[102:105], v[182:185], v[230:233], v[102:105]
	v_mfma_f32_16x16x32_bf16 v[74:77], v[174:177], v[238:241], v[74:77]
	v_mfma_f32_16x16x32_bf16 v[70:73], v[182:185], v[238:241], v[70:73]
	s_setprio 0
	s_barrier
	s_add_i32 s26, s83, s48
	s_mov_b32 m0, s26
	ds_read_b128 v[186:189], v173 offset:16384
	ds_read_b128 v[190:193], v173 offset:17408
	ds_read_b128 v[194:197], v173 offset:18432
	ds_read_b128 v[198:201], v173 offset:19456
	ds_read_b128 v[202:205], v173 offset:20480
	ds_read_b128 v[230:233], v173 offset:21504
	ds_read_b128 v[234:237], v173 offset:22528
	ds_read_b128 v[238:241], v173 offset:23552
	global_load_lds_dwordx4 v2, s[34:35]
	s_add_i32 m0, s26, 0x2000
	s_add_u32 s26, s34, 0x80000
	s_addc_u32 s27, s35, 0
	s_add_i32 s83, s84, s48
	global_load_lds_dwordx4 v0, s[34:35]
	s_mov_b32 m0, s83
	s_nop 0
	global_load_lds_dwordx4 v2, s[26:27]
	s_add_i32 m0, s83, 0x2000
	s_nop 0
	global_load_lds_dwordx4 v0, s[26:27]
	s_mov_b32 m0, s49
	s_nop 0
	global_load_lds_dwordx4 v2, s[40:41]
	s_mov_b32 m0, s51
	s_nop 0
	global_load_lds_dwordx4 v0, s[40:41]
	s_waitcnt vmcnt(8)
	s_waitcnt lgkmcnt(0)
	s_barrier
	s_setprio 1
	s_waitcnt lgkmcnt(0)
	v_mfma_f32_16x16x32_bf16 v[66:69], v[78:81], v[186:189], v[66:69]
	v_mfma_f32_16x16x32_bf16 v[62:65], v[94:97], v[186:189], v[62:65]
	v_mfma_f32_16x16x32_bf16 v[50:53], v[78:81], v[194:197], v[50:53]
	v_mfma_f32_16x16x32_bf16 v[46:49], v[94:97], v[194:197], v[46:49]
	v_mfma_f32_16x16x32_bf16 v[34:37], v[78:81], v[202:205], v[34:37]
	v_mfma_f32_16x16x32_bf16 v[30:33], v[94:97], v[202:205], v[30:33]
	v_mfma_f32_16x16x32_bf16 v[18:21], v[78:81], v[234:237], v[18:21]
	v_mfma_f32_16x16x32_bf16 v[14:17], v[94:97], v[234:237], v[14:17]
	v_mfma_f32_16x16x32_bf16 v[66:69], v[86:89], v[190:193], v[66:69]
	v_mfma_f32_16x16x32_bf16 v[62:65], v[98:101], v[190:193], v[62:65]
	v_mfma_f32_16x16x32_bf16 v[50:53], v[86:89], v[198:201], v[50:53]
	v_mfma_f32_16x16x32_bf16 v[46:49], v[98:101], v[198:201], v[46:49]
	v_mfma_f32_16x16x32_bf16 v[34:37], v[86:89], v[230:233], v[34:37]
	v_mfma_f32_16x16x32_bf16 v[30:33], v[98:101], v[230:233], v[30:33]
	v_mfma_f32_16x16x32_bf16 v[18:21], v[86:89], v[238:241], v[18:21]
	v_mfma_f32_16x16x32_bf16 v[14:17], v[98:101], v[238:241], v[14:17]
	s_setprio 0
	s_setprio 1
	v_mfma_f32_16x16x32_bf16 v[58:61], v[166:169], v[186:189], v[58:61]
	v_mfma_f32_16x16x32_bf16 v[54:57], v[178:181], v[186:189], v[54:57]
	v_mfma_f32_16x16x32_bf16 v[42:45], v[166:169], v[194:197], v[42:45]
	v_mfma_f32_16x16x32_bf16 v[38:41], v[178:181], v[194:197], v[38:41]
	v_mfma_f32_16x16x32_bf16 v[26:29], v[166:169], v[202:205], v[26:29]
	v_mfma_f32_16x16x32_bf16 v[22:25], v[178:181], v[202:205], v[22:25]
	v_mfma_f32_16x16x32_bf16 v[10:13], v[166:169], v[234:237], v[10:13]
	v_mfma_f32_16x16x32_bf16 v[6:9], v[178:181], v[234:237], v[6:9]
	v_mfma_f32_16x16x32_bf16 v[58:61], v[174:177], v[190:193], v[58:61]
	v_mfma_f32_16x16x32_bf16 v[54:57], v[182:185], v[190:193], v[54:57]
	v_mfma_f32_16x16x32_bf16 v[42:45], v[174:177], v[198:201], v[42:45]
	v_mfma_f32_16x16x32_bf16 v[38:41], v[182:185], v[198:201], v[38:41]
	v_mfma_f32_16x16x32_bf16 v[26:29], v[174:177], v[230:233], v[26:29]
	v_mfma_f32_16x16x32_bf16 v[22:25], v[182:185], v[230:233], v[22:25]
	v_mfma_f32_16x16x32_bf16 v[10:13], v[174:177], v[238:241], v[10:13]
	v_mfma_f32_16x16x32_bf16 v[6:9], v[182:185], v[238:241], v[6:9]
	s_setprio 0
	s_barrier
; #define PG8_STAGE(bufoff, gbase, voff) do { _Pragma("unroll") for (int _i = 0; _i < 2; ++_i) \
;         __builtin_amdgcn_global_load_lds((const unsigned*)((const char*)(gbase) + (voff)[_i]), (PG8_LAS unsigned*)(lds + (bufoff) + ldsw + _i * 8192), 16, 0, 0); } while (0)
; #define PG8_LDA(dst, b, h) do { _Pragma("unroll") for (int m = 0; m < 4; ++m) _Pragma("unroll") for (int k = 0; k < 2; ++k) dst[m][k] = *(const PG8_LAS bf16x8*)(lds + PG8_SA(b, h) + aoff + m * 2048 + k * 1024); } while (0)
; #define PG8_LDB(dst, b, h) do { _Pragma("unroll") for (int n = 0; n < 2; ++n) _Pragma("unroll") for (int k = 0; k < 2; ++k) dst[n][k] = *(const PG8_LAS bf16x8*)(lds + PG8_SB(b, h) + boff + n * 2048 + k * 1024); } while (0)
; #define PG8_MMA(ai, bj, At, Bt) do { __builtin_amdgcn_s_setprio(1); _Pragma("unroll") for (int m = 0; m < 4; ++m) _Pragma("unroll") for (int n = 0; n < 2; ++n) _Pragma("unroll") for (int k = 0; k < 2; ++k) \
;         acc[ai][bj][m][n] = __builtin_amdgcn_mfma_f32_16x16x32_bf16(Bt[n][k], At[m][k], acc[ai][bj][m][n], 0, 0, 0); __builtin_amdgcn_s_setprio(0); } while (0)
; #define PG8_WAIT_V(n) asm volatile("s_waitcnt vmcnt(" #n ")" ::: "memory")
; #define PG8_WAIT_L(n) asm volatile("s_waitcnt lgkmcnt(" #n ")" ::: "memory")
; #define PG8_BAR __builtin_amdgcn_s_barrier()
; #define PG8_SCHED __builtin_amdgcn_sched_barrier(0)
; template <class Epi, class Sched, bool ALIGN_EPI = false, bool SP2 = false>
; __device__ __forceinline__ void gemm_phase(PG8_LAS unsigned char* lds, const Gemm g, const Sched& S, const Epi& E) {
;     ...
;             PG8_LDB(B0, 1, 0); PG8_LDB(B1, 1, 1); PG8_SCHED; PG8_LDA(At, 1, 0); PG8_STAGE(PG8_SA(0, 1), a2 + hstep, voffA);
;             PG8_WAIT_V(8); PG8_WAIT_L(0); PG8_BAR; PG8_MMA(0, 0, At, B0); PG8_MMA(0, 1, At, B1); PG8_BAR; PG8_SCHED;
;             PG8_LDA(At, 1, 1); PG8_STAGE(PG8_SB(1, 0), b3, voffB); PG8_STAGE(PG8_SB(1, 1), b3 + hstep, voffB); PG8_STAGE(PG8_SA(1, 0), a3, voffA);
;             PG8_WAIT_V(8); PG8_WAIT_L(0); PG8_BAR; PG8_MMA(1, 0, At, B0); PG8_MMA(1, 1, At, B1); PG8_BAR; PG8_SCHED;
	s_add_i32 s83, 0, 0x18000
	s_add_i32 s84, 0, 0x1c000
	v_add_u32_e32 v98, s83, v152
	v_add_u32_e32 v182, s84, v152
	ds_read_b128 v[78:81], v98
	ds_read_b128 v[86:89], v98 offset:1024
	ds_read_b128 v[94:97], v98 offset:2048
	ds_read_b128 v[98:101], v98 offset:3072
	ds_read_b128 v[166:169], v182
	ds_read_b128 v[174:177], v182 offset:1024
	ds_read_b128 v[178:181], v182 offset:2048
	ds_read_b128 v[182:185], v182 offset:3072
	s_add_u32 s26, s40, 0x80000
	s_addc_u32 s27, s41, 0
	s_mov_b32 m0, s52
	ds_read_b128 v[186:189], v173 offset:32768
	ds_read_b128 v[190:193], v173 offset:33792
	ds_read_b128 v[194:197], v173 offset:34816
	ds_read_b128 v[198:201], v173 offset:35840
	ds_read_b128 v[202:205], v173 offset:36864
	ds_read_b128 v[230:233], v173 offset:37888
	ds_read_b128 v[234:237], v173 offset:38912
	ds_read_b128 v[238:241], v173 offset:39936
	global_load_lds_dwordx4 v2, s[26:27]
	s_mov_b32 m0, s53
	s_nop 0
	global_load_lds_dwordx4 v0, s[26:27]
	s_waitcnt vmcnt(8)
	s_waitcnt lgkmcnt(0)
	s_barrier
	s_setprio 1
	s_waitcnt lgkmcnt(0)
	v_mfma_f32_16x16x32_bf16 v[146:149], v[78:81], v[186:189], v[146:149]
	v_mfma_f32_16x16x32_bf16 v[142:145], v[94:97], v[186:189], v[142:145]
	v_mfma_f32_16x16x32_bf16 v[130:133], v[78:81], v[194:197], v[130:133]
	v_mfma_f32_16x16x32_bf16 v[126:129], v[94:97], v[194:197], v[126:129]
	v_mfma_f32_16x16x32_bf16 v[114:117], v[78:81], v[202:205], v[114:117]
	v_mfma_f32_16x16x32_bf16 v[110:113], v[94:97], v[202:205], v[110:113]
	v_mfma_f32_16x16x32_bf16 v[90:93], v[78:81], v[234:237], v[90:93]
	v_mfma_f32_16x16x32_bf16 v[82:85], v[94:97], v[234:237], v[82:85]
	v_mfma_f32_16x16x32_bf16 v[146:149], v[86:89], v[190:193], v[146:149]
	v_mfma_f32_16x16x32_bf16 v[142:145], v[98:101], v[190:193], v[142:145]
	v_mfma_f32_16x16x32_bf16 v[130:133], v[86:89], v[198:201], v[130:133]
	v_mfma_f32_16x16x32_bf16 v[126:129], v[98:101], v[198:201], v[126:129]
	v_mfma_f32_16x16x32_bf16 v[114:117], v[86:89], v[230:233], v[114:117]
	v_mfma_f32_16x16x32_bf16 v[110:113], v[98:101], v[230:233], v[110:113]
	v_mfma_f32_16x16x32_bf16 v[90:93], v[86:89], v[238:241], v[90:93]
	v_mfma_f32_16x16x32_bf16 v[82:85], v[98:101], v[238:241], v[82:85]
	s_setprio 0
	s_setprio 1
	v_mfma_f32_16x16x32_bf16 v[138:141], v[166:169], v[186:189], v[138:141]
	v_mfma_f32_16x16x32_bf16 v[134:137], v[178:181], v[186:189], v[134:137]
	v_mfma_f32_16x16x32_bf16 v[122:125], v[166:169], v[194:197], v[122:125]
	v_mfma_f32_16x16x32_bf16 v[118:121], v[178:181], v[194:197], v[118:121]
	v_mfma_f32_16x16x32_bf16 v[106:109], v[166:169], v[202:205], v[106:109]
	v_mfma_f32_16x16x32_bf16 v[102:105], v[178:181], v[202:205], v[102:105]
	v_mfma_f32_16x16x32_bf16 v[74:77], v[166:169], v[234:237], v[74:77]
	v_mfma_f32_16x16x32_bf16 v[70:73], v[178:181], v[234:237], v[70:73]
	v_mfma_f32_16x16x32_bf16 v[138:141], v[174:177], v[190:193], v[138:141]
	v_mfma_f32_16x16x32_bf16 v[134:137], v[182:185], v[190:193], v[134:137]
	v_mfma_f32_16x16x32_bf16 v[122:125], v[174:177], v[198:201], v[122:125]
	v_mfma_f32_16x16x32_bf16 v[118:121], v[182:185], v[198:201], v[118:121]
	v_mfma_f32_16x16x32_bf16 v[106:109], v[174:177], v[230:233], v[106:109]
	v_mfma_f32_16x16x32_bf16 v[102:105], v[182:185], v[230:233], v[102:105]
	v_mfma_f32_16x16x32_bf16 v[74:77], v[174:177], v[238:241], v[74:77]
	v_mfma_f32_16x16x32_bf16 v[70:73], v[182:185], v[238:241], v[70:73]
	s_setprio 0
	s_barrier
	s_add_u32 vcc_lo, s34, s2
	s_addc_u32 vcc_hi, s35, s3
	s_add_i32 s26, s83, s48
	s_mov_b32 m0, s26
	ds_read_b128 v[186:189], v173 offset:49152
	ds_read_b128 v[190:193], v173 offset:50176
	ds_read_b128 v[194:197], v173 offset:51200
	ds_read_b128 v[198:201], v173 offset:52224
	ds_read_b128 v[202:205], v173 offset:53248
	ds_read_b128 v[230:233], v173 offset:54272
	ds_read_b128 v[234:237], v173 offset:55296
	ds_read_b128 v[238:241], v173 offset:56320
	global_load_lds_dwordx4 v2, vcc
	s_add_i32 m0, s26, 0x2000
	s_add_u32 s26, s34, 0x80080
	s_addc_u32 s27, s35, 0
	s_add_i32 s34, s84, s48
	global_load_lds_dwordx4 v0, vcc
	s_mov_b32 m0, s34
	s_nop 0
	global_load_lds_dwordx4 v2, s[26:27]
	s_add_i32 m0, s34, 0x2000
	s_nop 0
	global_load_lds_dwordx4 v0, s[26:27]
	s_add_u32 vcc_lo, s40, s2
	s_addc_u32 vcc_hi, s41, s3
	s_mov_b32 m0, s66
	s_nop 0
	global_load_lds_dwordx4 v2, vcc
	s_mov_b32 m0, s67
	s_nop 0
	global_load_lds_dwordx4 v0, vcc
	s_waitcnt vmcnt(8)
	s_waitcnt lgkmcnt(0)
	s_barrier
	s_setprio 1
	s_waitcnt lgkmcnt(0)
	v_mfma_f32_16x16x32_bf16 v[66:69], v[78:81], v[186:189], v[66:69]
	v_mfma_f32_16x16x32_bf16 v[62:65], v[94:97], v[186:189], v[62:65]
	v_mfma_f32_16x16x32_bf16 v[50:53], v[78:81], v[194:197], v[50:53]
	v_mfma_f32_16x16x32_bf16 v[46:49], v[94:97], v[194:197], v[46:49]
	v_mfma_f32_16x16x32_bf16 v[34:37], v[78:81], v[202:205], v[34:37]
	v_mfma_f32_16x16x32_bf16 v[30:33], v[94:97], v[202:205], v[30:33]
	v_mfma_f32_16x16x32_bf16 v[18:21], v[78:81], v[234:237], v[18:21]
	v_mfma_f32_16x16x32_bf16 v[14:17], v[94:97], v[234:237], v[14:17]
	v_mfma_f32_16x16x32_bf16 v[66:69], v[86:89], v[190:193], v[66:69]
	v_mfma_f32_16x16x32_bf16 v[62:65], v[98:101], v[190:193], v[62:65]
	v_mfma_f32_16x16x32_bf16 v[50:53], v[86:89], v[198:201], v[50:53]
	v_mfma_f32_16x16x32_bf16 v[46:49], v[98:101], v[198:201], v[46:49]
	v_mfma_f32_16x16x32_bf16 v[34:37], v[86:89], v[230:233], v[34:37]
	v_mfma_f32_16x16x32_bf16 v[30:33], v[98:101], v[230:233], v[30:33]
	v_mfma_f32_16x16x32_bf16 v[18:21], v[86:89], v[238:241], v[18:21]
	v_mfma_f32_16x16x32_bf16 v[14:17], v[98:101], v[238:241], v[14:17]
	s_setprio 0
	s_setprio 1
	v_mfma_f32_16x16x32_bf16 v[58:61], v[166:169], v[186:189], v[58:61]
	v_mfma_f32_16x16x32_bf16 v[54:57], v[178:181], v[186:189], v[54:57]
	v_mfma_f32_16x16x32_bf16 v[42:45], v[166:169], v[194:197], v[42:45]
	v_mfma_f32_16x16x32_bf16 v[38:41], v[178:181], v[194:197], v[38:41]
	v_mfma_f32_16x16x32_bf16 v[26:29], v[166:169], v[202:205], v[26:29]
	v_mfma_f32_16x16x32_bf16 v[22:25], v[178:181], v[202:205], v[22:25]
	v_mfma_f32_16x16x32_bf16 v[10:13], v[166:169], v[234:237], v[10:13]
	v_mfma_f32_16x16x32_bf16 v[6:9], v[178:181], v[234:237], v[6:9]
	v_mfma_f32_16x16x32_bf16 v[58:61], v[174:177], v[190:193], v[58:61]
	v_mfma_f32_16x16x32_bf16 v[54:57], v[182:185], v[190:193], v[54:57]
	v_mfma_f32_16x16x32_bf16 v[42:45], v[174:177], v[198:201], v[42:45]
	v_mfma_f32_16x16x32_bf16 v[38:41], v[182:185], v[198:201], v[38:41]
	v_mfma_f32_16x16x32_bf16 v[26:29], v[174:177], v[230:233], v[26:29]
	v_mfma_f32_16x16x32_bf16 v[22:25], v[182:185], v[230:233], v[22:25]
	v_mfma_f32_16x16x32_bf16 v[10:13], v[174:177], v[238:241], v[10:13]
	v_mfma_f32_16x16x32_bf16 v[6:9], v[182:185], v[238:241], v[6:9]
	s_setprio 0
	s_barrier
;     __device__ __forceinline__ void operator()(const f32x4 (&acc)[2][2][4][2], const Unit& u, int wr, int wc, int fr, int fq) const {
;         const int row0 = u.pm * BM + wr * 64 + fr; const int col0 = u.pn * BM + wc * 32 + 4 * fq;
;         f32x4 gv[2][2];
; #pragma unroll
;         for (int bj = 0; bj < 2; ++bj)
; #pragma unroll
;             for (int n = 0; n < 2; ++n) gv[bj][n] = xg ? *(const f32x4*)(gn + col0 + bj * HALF + n * 16) : (f32x4){0.f, 0.f, 0.f, 0.f};
; #pragma unroll
;         for (int ai = 0; ai < 2; ++ai)
; #pragma unroll
;             for (int m = 0; m < 4; ++m) { const size_t off = (size_t)(row0 + ai * HALF + m * 16) * ldc + col0; float ss = 0.f;
; #pragma unroll
;                 for (int bj = 0; bj < 2; ++bj)
; #pragma unroll
;                     for (int n = 0; n < 2; ++n) { const f32x4 bs = *(const f32x4*)(base + off + bj * HALF + n * 16); const f32x4 o = bs + acc[ai][bj][m][n] * scale;
;                         *(f32x4*)(out + off + bj * HALF + n * 16) = o;
;                         if (xg) { ss += (o[0] * o[0] + o[1] * o[1]) + (o[2] * o[2] + o[3] * o[3]); const f32x4 og = o * gv[bj][n];
;                             typedef unsigned u32x2v __attribute__((ext_vector_type(2))); u32x2v w; w.x = cvt_pk_bf16(og[0], og[1]); w.y = cvt_pk_bf16(og[2], og[3]); *(u32x2v*)(xg + off + bj * HALF + n * 16) = w; } }
;                 if (xg) { ss += __shfl_xor(ss, 16); ss += __shfl_xor(ss, 32); if (fq == 0) atomicAdd(rowss + row0 + ai * HALF + m * 16, (rowss_t)(ss * 16777216.0f)); } }
	s_add_i32 s82, s82, 2
	s_add_u32 s80, s80, 0x100
	s_addc_u32 s81, s81, 0
	s_cmp_gt_u32 s82, 29
	s_mov_b64 s[26:27], s[30:31]
	s_cbranch_scc0 .LBB0_905
	v_lshl_add_u32 v170, s70, 8, v5
	v_lshl_or_b32 v168, s71, 8, v172
	v_ashrrev_i32_e32 v171, 31, v170
	v_ashrrev_i32_e32 v169, 31, v168
	v_readlane_b32 s6, v252, 59
	v_lshlrev_b64 v[158:159], 11, v[170:171]
	v_readlane_b32 s7, v252, 60
	v_lshl_add_u64 v[166:167], v[158:159], 0, v[168:169]
	v_lshl_add_u64 v[158:159], v[166:167], 2, s[12:13]
	v_lshl_add_u64 v[78:79], v[168:169], 2, s[6:7]
	global_load_dwordx4 v[98:101], v[78:79], off
	global_load_dwordx4 v[94:97], v[78:79], off offset:64
	global_load_dwordx4 v[86:89], v[78:79], off offset:512
	s_nop 0
	global_load_dwordx4 v[78:81], v[78:79], off offset:576
	s_nop 0
	global_load_dwordx4 v[174:177], v[158:159], off
	global_load_dwordx4 v[182:185], v[158:159], off offset:64
	global_load_dwordx4 v[186:189], v[158:159], off offset:512
	global_load_dwordx4 v[190:193], v[158:159], off offset:576
	s_waitcnt vmcnt(3) lgkmcnt(0)
	v_pk_add_f32 v[148:149], v[148:149], v[176:177]
	v_pk_add_f32 v[146:147], v[146:147], v[174:175]
	v_mul_f32_e32 v161, v149, v149
	v_mul_f32_e32 v160, v147, v147
	global_store_dwordx4 v[158:159], v[146:149], off
	v_fmac_f32_e32 v160, v146, v146
	v_fmac_f32_e32 v161, v148, v148
	v_pk_mul_f32 v[148:149], v[100:101], v[148:149]
	v_pk_mul_f32 v[146:147], v[98:99], v[146:147]
	v_add_f32_e32 v174, v160, v161
	v_cvt_pk_bf16_f32 v146, v146, v147
	v_cvt_pk_bf16_f32 v147, v148, v149
	v_lshl_add_u64 v[160:161], v[166:167], 1, s[14:15]
	global_store_dwordx2 v[160:161], v[146:147], off
	s_waitcnt vmcnt(4) lgkmcnt(0)
	v_pk_add_f32 v[144:145], v[144:145], v[184:185]
	v_pk_add_f32 v[142:143], v[142:143], v[182:183]
	v_mul_f32_e32 v147, v145, v145
	v_mul_f32_e32 v146, v143, v143
	global_store_dwordx4 v[158:159], v[142:145], off offset:64
	v_fmac_f32_e32 v146, v142, v142
	v_fmac_f32_e32 v147, v144, v144
	v_pk_mul_f32 v[144:145], v[96:97], v[144:145]
	v_pk_mul_f32 v[142:143], v[94:95], v[142:143]
	v_add_f32_e32 v146, v146, v147
	v_cvt_pk_bf16_f32 v142, v142, v143
	v_cvt_pk_bf16_f32 v143, v144, v145
	global_store_dwordx2 v[160:161], v[142:143], off offset:32
	v_add_f32_e32 v146, v174, v146
	s_waitcnt vmcnt(5) lgkmcnt(0)
	v_pk_add_f32 v[140:141], v[140:141], v[188:189]
	v_pk_add_f32 v[138:139], v[138:139], v[186:187]
	v_mul_f32_e32 v143, v141, v141
	v_mul_f32_e32 v142, v139, v139
	global_store_dwordx4 v[158:159], v[138:141], off offset:512
	v_fmac_f32_e32 v142, v138, v138
	v_fmac_f32_e32 v143, v140, v140
	v_pk_mul_f32 v[140:141], v[88:89], v[140:141]
	v_pk_mul_f32 v[138:139], v[86:87], v[138:139]
	v_add_f32_e32 v142, v142, v143
	v_cvt_pk_bf16_f32 v138, v138, v139
	v_cvt_pk_bf16_f32 v139, v140, v141
	global_store_dwordx2 v[160:161], v[138:139], off offset:256
	v_add_f32_e32 v142, v146, v142
	s_waitcnt vmcnt(6) lgkmcnt(0)
	v_pk_add_f32 v[136:137], v[136:137], v[192:193]
	v_pk_add_f32 v[134:135], v[134:135], v[190:191]
	global_store_dwordx4 v[158:159], v[134:137], off offset:576
	v_pk_mul_f32 v[140:141], v[78:79], v[134:135]
	v_pk_mul_f32 v[138:139], v[80:81], v[136:137]
	v_mul_f32_e32 v135, v135, v135
	v_fmac_f32_e32 v135, v134, v134
	v_mul_f32_e32 v134, v137, v137
	v_fmac_f32_e32 v134, v136, v136
	v_and_b32_e32 v136, 64, v218
	v_add_f32_e32 v134, v135, v134
	v_xor_b32_e32 v135, 16, v218
	v_add_u32_e32 v137, 64, v136
	v_cmp_lt_i32_e32 vcc, v135, v137
	v_add_f32_e32 v134, v142, v134
	v_cvt_pk_bf16_f32 v140, v140, v141
	v_cndmask_b32_e32 v135, v218, v135, vcc
	v_lshlrev_b32_e32 v136, 2, v135
	ds_bpermute_b32 v135, v136, v134
	v_cvt_pk_bf16_f32 v141, v138, v139
	global_store_dwordx2 v[160:161], v[140:141], off offset:288
	s_waitcnt lgkmcnt(0)
	v_add_f32_e32 v138, v134, v135
	v_xor_b32_e32 v134, 32, v218
	v_cmp_lt_i32_e32 vcc, v134, v137
	s_nop 1
	v_cndmask_b32_e32 v134, v218, v134, vcc
	v_lshlrev_b32_e32 v137, 2, v134
	ds_bpermute_b32 v139, v137, v138
	v_lshl_add_u64 v[134:135], v[170:171], 3, s[16:17]
	s_and_saveexec_b64 s[26:27], s[8:9]
	s_cbranch_execz .LBB0_908
	s_waitcnt lgkmcnt(0)
	v_add_f32_e32 v138, v138, v139
	v_mul_f32_e32 v138, 0x4b800000, v138
	v_trunc_f32_e32 v138, v138
	v_mul_f32_e32 v139, 0x2f800000, v138
	v_floor_f32_e32 v139, v139
	v_fmac_f32_e32 v138, 0xcf800000, v139
	v_cvt_u32_f32_e32 v138, v138
	v_cvt_u32_f32_e32 v139, v139
	global_atomic_add_x2 v[134:135], v[138:139], off

; #define PG8_STAGE(bufoff, gbase, voff) do { _Pragma("unroll") for (int _i = 0; _i < 2; ++_i) \
;         __builtin_amdgcn_global_load_lds((const unsigned*)((const char*)(gbase) + (voff)[_i]), (PG8_LAS unsigned*)(lds + (bufoff) + ldsw + _i * 8192), 16, 0, 0); } while (0)
; #define PG8_LDA(dst, b, h) do { _Pragma("unroll") for (int m = 0; m < 4; ++m) _Pragma("unroll") for (int k = 0; k < 2; ++k) dst[m][k] = *(const PG8_LAS bf16x8*)(lds + PG8_SA(b, h) + aoff + m * 2048 + k * 1024); } while (0)
; #define PG8_LDB(dst, b, h) do { _Pragma("unroll") for (int n = 0; n < 2; ++n) _Pragma("unroll") for (int k = 0; k < 2; ++k) dst[n][k] = *(const PG8_LAS bf16x8*)(lds + PG8_SB(b, h) + boff + n * 2048 + k * 1024); } while (0)
; #define PG8_MMA(ai, bj, At, Bt) do { __builtin_amdgcn_s_setprio(1); _Pragma("unroll") for (int m = 0; m < 4; ++m) _Pragma("unroll") for (int n = 0; n < 2; ++n) _Pragma("unroll") for (int k = 0; k < 2; ++k) \
;         acc[ai][bj][m][n] = __builtin_amdgcn_mfma_f32_16x16x32_bf16(Bt[n][k], At[m][k], acc[ai][bj][m][n], 0, 0, 0); __builtin_amdgcn_s_setprio(0); } while (0)
; #define PG8_WAIT_V(n) asm volatile("s_waitcnt vmcnt(" #n ")" ::: "memory")
; #define PG8_WAIT_L(n) asm volatile("s_waitcnt lgkmcnt(" #n ")" ::: "memory")
; #define PG8_BAR __builtin_amdgcn_s_barrier()
; #define PG8_SCHED __builtin_amdgcn_sched_barrier(0)
; template <class Epi, class Sched, bool ALIGN_EPI = false, bool SP2 = false>
; __device__ __forceinline__ void gemm_phase(PG8_LAS unsigned char* lds, const Gemm g, const Sched& S, const Epi& E) {
;     ...
;             const bool last = (t == nt - 2);
;             const char* a1 = cA + (size_t)(t + 1) * kstep;
;             const char* a2 = last ? nA : cA + (size_t)(t + 2) * kstep; const char* b2 = last ? nB : cB + (size_t)(t + 2) * kstep;
;             const char* a3 = a2 + kstep; const char* b3 = b2 + kstep;
;             if (last && has_next) S.a_ready(nxt);
;             if constexpr (SP2) {
;             PG8_LDB(B0, 0, 0); PG8_LDB(B1, 0, 1); PG8_SCHED; PG8_LDA(At, 0, 0); PG8_STAGE(PG8_SA(1, 1), a1 + hstep, voffA);
;             PG8_WAIT_V(8); PG8_WAIT_L(0); PG8_BAR; PG8_MMA(0, 0, At, B0); PG8_MMA(0, 1, At, B1); PG8_BAR; PG8_SCHED;
;             PG8_LDA(At, 0, 1); PG8_STAGE(PG8_SB(0, 0), b2, voffB); PG8_STAGE(PG8_SB(0, 1), b2 + hstep, voffB); PG8_STAGE(PG8_SA(0, 0), a2, voffA);
.LBB0_1016:
	s_add_u32 s24, s22, 0xfff80080
	s_addc_u32 s25, s23, -1
	s_add_i32 s67, 0, 0x10000
	s_cmp_eq_u32 s66, 28
	s_cselect_b32 s27, s17, s25
	s_cselect_b32 s26, s50, s24
	v_add_u32_e32 v158, s67, v152
	s_cselect_b32 s25, s15, s53
	s_cselect_b32 s24, s51, s52
	s_add_i32 s69, 0, 0x14000
	ds_read_b128 v[142:145], v158
	ds_read_b128 v[146:149], v158 offset:1024
	ds_read_b128 v[164:167], v158 offset:2048
	ds_read_b128 v[168:171], v158 offset:3072
	v_add_u32_e32 v158, s69, v152
	ds_read_b128 v[172:175], v158
	ds_read_b128 v[176:179], v158 offset:1024
	ds_read_b128 v[180:183], v158 offset:2048
	ds_read_b128 v[184:187], v158 offset:3072
	s_add_i32 m0, s41, 0xc000
	ds_read_b128 v[188:191], v163
	ds_read_b128 v[192:195], v163 offset:1024
	ds_read_b128 v[196:199], v163 offset:2048
	ds_read_b128 v[200:203], v163 offset:3072
	ds_read_b128 v[204:207], v163 offset:4096
	ds_read_b128 v[230:233], v163 offset:5120
	ds_read_b128 v[234:237], v163 offset:6144
	ds_read_b128 v[238:241], v163 offset:7168
	global_load_lds_dwordx4 v140, s[22:23]
	s_add_i32 m0, s41, 0xe000
	s_nop 0
	global_load_lds_dwordx4 v138, s[22:23]
	s_waitcnt vmcnt(8)
	s_waitcnt lgkmcnt(0)
	s_barrier
	s_setprio 1
	s_waitcnt lgkmcnt(0)
	v_mfma_f32_16x16x32_bf16 v[130:133], v[142:145], v[188:191], v[130:133]
	v_mfma_f32_16x16x32_bf16 v[126:129], v[164:167], v[188:191], v[126:129]
	v_mfma_f32_16x16x32_bf16 v[114:117], v[142:145], v[196:199], v[114:117]
	v_mfma_f32_16x16x32_bf16 v[110:113], v[164:167], v[196:199], v[110:113]
	v_mfma_f32_16x16x32_bf16 v[98:101], v[142:145], v[204:207], v[98:101]
	v_mfma_f32_16x16x32_bf16 v[94:97], v[164:167], v[204:207], v[94:97]
	v_mfma_f32_16x16x32_bf16 v[82:85], v[142:145], v[234:237], v[82:85]
	v_mfma_f32_16x16x32_bf16 v[78:81], v[164:167], v[234:237], v[78:81]
	v_mfma_f32_16x16x32_bf16 v[130:133], v[146:149], v[192:195], v[130:133]
	v_mfma_f32_16x16x32_bf16 v[126:129], v[168:171], v[192:195], v[126:129]
	v_mfma_f32_16x16x32_bf16 v[114:117], v[146:149], v[200:203], v[114:117]
	v_mfma_f32_16x16x32_bf16 v[110:113], v[168:171], v[200:203], v[110:113]
	v_mfma_f32_16x16x32_bf16 v[98:101], v[146:149], v[230:233], v[98:101]
	v_mfma_f32_16x16x32_bf16 v[94:97], v[168:171], v[230:233], v[94:97]
	v_mfma_f32_16x16x32_bf16 v[82:85], v[146:149], v[238:241], v[82:85]
	v_mfma_f32_16x16x32_bf16 v[78:81], v[168:171], v[238:241], v[78:81]
	s_setprio 0
	s_setprio 1
	v_mfma_f32_16x16x32_bf16 v[122:125], v[172:175], v[188:191], v[122:125]
	v_mfma_f32_16x16x32_bf16 v[118:121], v[180:183], v[188:191], v[118:121]
	v_mfma_f32_16x16x32_bf16 v[106:109], v[172:175], v[196:199], v[106:109]
	v_mfma_f32_16x16x32_bf16 v[102:105], v[180:183], v[196:199], v[102:105]
	v_mfma_f32_16x16x32_bf16 v[90:93], v[172:175], v[204:207], v[90:93]
	v_mfma_f32_16x16x32_bf16 v[86:89], v[180:183], v[204:207], v[86:89]
	v_mfma_f32_16x16x32_bf16 v[74:77], v[172:175], v[234:237], v[74:77]
	v_mfma_f32_16x16x32_bf16 v[70:73], v[180:183], v[234:237], v[70:73]
	v_mfma_f32_16x16x32_bf16 v[122:125], v[176:179], v[192:195], v[122:125]
	v_mfma_f32_16x16x32_bf16 v[118:121], v[184:187], v[192:195], v[118:121]
	v_mfma_f32_16x16x32_bf16 v[106:109], v[176:179], v[200:203], v[106:109]
	v_mfma_f32_16x16x32_bf16 v[102:105], v[184:187], v[200:203], v[102:105]
	v_mfma_f32_16x16x32_bf16 v[90:93], v[176:179], v[230:233], v[90:93]
	v_mfma_f32_16x16x32_bf16 v[86:89], v[184:187], v[230:233], v[86:89]
	v_mfma_f32_16x16x32_bf16 v[74:77], v[176:179], v[238:241], v[74:77]
	v_mfma_f32_16x16x32_bf16 v[70:73], v[184:187], v[238:241], v[70:73]
	s_setprio 0
	s_barrier
	s_add_i32 s67, s67, s30
	s_mov_b32 m0, s67
	ds_read_b128 v[188:191], v163 offset:16384
	ds_read_b128 v[192:195], v163 offset:17408
	ds_read_b128 v[196:199], v163 offset:18432
	ds_read_b128 v[200:203], v163 offset:19456
	ds_read_b128 v[204:207], v163 offset:20480
	ds_read_b128 v[230:233], v163 offset:21504
	ds_read_b128 v[234:237], v163 offset:22528
	ds_read_b128 v[238:241], v163 offset:23552
	global_load_lds_dwordx4 v2, s[24:25]
	s_add_i32 m0, s67, 0x2000
	s_add_u32 s70, s24, 0x80000
	s_addc_u32 s71, s25, 0
	s_add_i32 s67, s69, s30
	global_load_lds_dwordx4 v0, s[24:25]
	s_mov_b32 m0, s67
	v_lshl_add_u64 v[246:247], s[26:27], 0, v[134:135]
	global_load_lds_dwordx4 v2, s[70:71]
	s_add_i32 m0, s67, 0x2000
	s_nop 0
	global_load_lds_dwordx4 v0, s[70:71]
	v_lshl_add_u64 v[244:245], s[26:27], 0, v[136:137]
	s_mov_b32 m0, s41
	s_nop 0
	global_load_lds_dwordx4 v136, s[26:27]
	s_mov_b32 m0, s42
	s_nop 0
	global_load_lds_dwordx4 v134, s[26:27]
	s_waitcnt vmcnt(8)
	s_waitcnt lgkmcnt(0)
	s_barrier
; #define PG8_STAGE(bufoff, gbase, voff) do { _Pragma("unroll") for (int _i = 0; _i < 2; ++_i) \
;         __builtin_amdgcn_global_load_lds((const unsigned*)((const char*)(gbase) + (voff)[_i]), (PG8_LAS unsigned*)(lds + (bufoff) + ldsw + _i * 8192), 16, 0, 0); } while (0)
; #define PG8_LDA(dst, b, h) do { _Pragma("unroll") for (int m = 0; m < 4; ++m) _Pragma("unroll") for (int k = 0; k < 2; ++k) dst[m][k] = *(const PG8_LAS bf16x8*)(lds + PG8_SA(b, h) + aoff + m * 2048 + k * 1024); } while (0)
; #define PG8_LDB(dst, b, h) do { _Pragma("unroll") for (int n = 0; n < 2; ++n) _Pragma("unroll") for (int k = 0; k < 2; ++k) dst[n][k] = *(const PG8_LAS bf16x8*)(lds + PG8_SB(b, h) + boff + n * 2048 + k * 1024); } while (0)
; #define PG8_MMA(ai, bj, At, Bt) do { __builtin_amdgcn_s_setprio(1); _Pragma("unroll") for (int m = 0; m < 4; ++m) _Pragma("unroll") for (int n = 0; n < 2; ++n) _Pragma("unroll") for (int k = 0; k < 2; ++k) \
;         acc[ai][bj][m][n] = __builtin_amdgcn_mfma_f32_16x16x32_bf16(Bt[n][k], At[m][k], acc[ai][bj][m][n], 0, 0, 0); __builtin_amdgcn_s_setprio(0); } while (0)
; #define PG8_WAIT_V(n) asm volatile("s_waitcnt vmcnt(" #n ")" ::: "memory")
; #define PG8_WAIT_L(n) asm volatile("s_waitcnt lgkmcnt(" #n ")" ::: "memory")
; #define PG8_BAR __builtin_amdgcn_s_barrier()
; #define PG8_SCHED __builtin_amdgcn_sched_barrier(0)
; template <class Epi, class Sched, bool ALIGN_EPI = false, bool SP2 = false>
; __device__ __forceinline__ void gemm_phase(PG8_LAS unsigned char* lds, const Gemm g, const Sched& S, const Epi& E) {
;     ...
;             PG8_WAIT_V(8); PG8_WAIT_L(0); PG8_BAR; PG8_MMA(1, 0, At, B0); PG8_MMA(1, 1, At, B1); PG8_BAR; PG8_SCHED;
;             PG8_LDB(B0, 1, 0); PG8_LDB(B1, 1, 1); PG8_SCHED; PG8_LDA(At, 1, 0); PG8_STAGE(PG8_SA(0, 1), a2 + hstep, voffA);
;             PG8_WAIT_V(8); PG8_WAIT_L(0); PG8_BAR; PG8_MMA(0, 0, At, B0); PG8_MMA(0, 1, At, B1); PG8_BAR; PG8_SCHED;
	s_setprio 1
	s_waitcnt lgkmcnt(0)
	v_mfma_f32_16x16x32_bf16 v[66:69], v[142:145], v[188:191], v[66:69]
	v_mfma_f32_16x16x32_bf16 v[62:65], v[164:167], v[188:191], v[62:65]
	v_mfma_f32_16x16x32_bf16 v[50:53], v[142:145], v[196:199], v[50:53]
	v_mfma_f32_16x16x32_bf16 v[46:49], v[164:167], v[196:199], v[46:49]
	v_mfma_f32_16x16x32_bf16 v[34:37], v[142:145], v[204:207], v[34:37]
	v_mfma_f32_16x16x32_bf16 v[30:33], v[164:167], v[204:207], v[30:33]
	v_mfma_f32_16x16x32_bf16 v[18:21], v[142:145], v[234:237], v[18:21]
	v_mfma_f32_16x16x32_bf16 v[14:17], v[164:167], v[234:237], v[14:17]
	v_mfma_f32_16x16x32_bf16 v[66:69], v[146:149], v[192:195], v[66:69]
	v_mfma_f32_16x16x32_bf16 v[62:65], v[168:171], v[192:195], v[62:65]
	v_mfma_f32_16x16x32_bf16 v[50:53], v[146:149], v[200:203], v[50:53]
	v_mfma_f32_16x16x32_bf16 v[46:49], v[168:171], v[200:203], v[46:49]
	v_mfma_f32_16x16x32_bf16 v[34:37], v[146:149], v[230:233], v[34:37]
	v_mfma_f32_16x16x32_bf16 v[30:33], v[168:171], v[230:233], v[30:33]
	v_mfma_f32_16x16x32_bf16 v[18:21], v[146:149], v[238:241], v[18:21]
	v_mfma_f32_16x16x32_bf16 v[14:17], v[168:171], v[238:241], v[14:17]
	s_setprio 0
	s_setprio 1
	v_mfma_f32_16x16x32_bf16 v[58:61], v[172:175], v[188:191], v[58:61]
	v_mfma_f32_16x16x32_bf16 v[54:57], v[180:183], v[188:191], v[54:57]
	v_mfma_f32_16x16x32_bf16 v[42:45], v[172:175], v[196:199], v[42:45]
	v_mfma_f32_16x16x32_bf16 v[38:41], v[180:183], v[196:199], v[38:41]
	v_mfma_f32_16x16x32_bf16 v[26:29], v[172:175], v[204:207], v[26:29]
	v_mfma_f32_16x16x32_bf16 v[22:25], v[180:183], v[204:207], v[22:25]
	v_mfma_f32_16x16x32_bf16 v[10:13], v[172:175], v[234:237], v[10:13]
	v_mfma_f32_16x16x32_bf16 v[6:9], v[180:183], v[234:237], v[6:9]
	v_mfma_f32_16x16x32_bf16 v[58:61], v[176:179], v[192:195], v[58:61]
	v_mfma_f32_16x16x32_bf16 v[54:57], v[184:187], v[192:195], v[54:57]
	v_mfma_f32_16x16x32_bf16 v[42:45], v[176:179], v[200:203], v[42:45]
	v_mfma_f32_16x16x32_bf16 v[38:41], v[184:187], v[200:203], v[38:41]
	v_mfma_f32_16x16x32_bf16 v[26:29], v[176:179], v[230:233], v[26:29]
	v_mfma_f32_16x16x32_bf16 v[22:25], v[184:187], v[230:233], v[22:25]
	v_mfma_f32_16x16x32_bf16 v[10:13], v[176:179], v[238:241], v[10:13]
	v_mfma_f32_16x16x32_bf16 v[6:9], v[184:187], v[238:241], v[6:9]
	s_setprio 0
	s_barrier
	s_add_i32 s67, 0, 0x18000
	v_add_u32_e32 v160, s67, v152
	s_add_i32 s69, 0, 0x1c000
	ds_read_b128 v[142:145], v160
	ds_read_b128 v[146:149], v160 offset:1024
	ds_read_b128 v[164:167], v160 offset:2048
	ds_read_b128 v[168:171], v160 offset:3072
	v_add_u32_e32 v160, s69, v152
	ds_read_b128 v[172:175], v160
	ds_read_b128 v[176:179], v160 offset:1024
	ds_read_b128 v[180:183], v160 offset:2048
	ds_read_b128 v[184:187], v160 offset:3072
	s_add_u32 s26, s26, 0x80000
	s_addc_u32 s27, s27, 0
	s_mov_b32 m0, s43
	ds_read_b128 v[188:191], v163 offset:32768
	ds_read_b128 v[192:195], v163 offset:33792
	ds_read_b128 v[196:199], v163 offset:34816
	ds_read_b128 v[200:203], v163 offset:35840
	ds_read_b128 v[204:207], v163 offset:36864
	ds_read_b128 v[230:233], v163 offset:37888
	ds_read_b128 v[234:237], v163 offset:38912
	ds_read_b128 v[238:241], v163 offset:39936
	global_load_lds_dwordx4 v136, s[26:27]
	s_mov_b32 m0, s44
	s_nop 0
	global_load_lds_dwordx4 v134, s[26:27]
	s_waitcnt vmcnt(8)
	s_waitcnt lgkmcnt(0)
	s_barrier
	s_setprio 1
	s_waitcnt lgkmcnt(0)
	v_mfma_f32_16x16x32_bf16 v[130:133], v[142:145], v[188:191], v[130:133]
	v_mfma_f32_16x16x32_bf16 v[126:129], v[164:167], v[188:191], v[126:129]
	v_mfma_f32_16x16x32_bf16 v[114:117], v[142:145], v[196:199], v[114:117]
	v_mfma_f32_16x16x32_bf16 v[110:113], v[164:167], v[196:199], v[110:113]
	v_mfma_f32_16x16x32_bf16 v[98:101], v[142:145], v[204:207], v[98:101]
	v_mfma_f32_16x16x32_bf16 v[94:97], v[164:167], v[204:207], v[94:97]
	v_mfma_f32_16x16x32_bf16 v[82:85], v[142:145], v[234:237], v[82:85]
	v_mfma_f32_16x16x32_bf16 v[78:81], v[164:167], v[234:237], v[78:81]
	v_mfma_f32_16x16x32_bf16 v[130:133], v[146:149], v[192:195], v[130:133]
	v_mfma_f32_16x16x32_bf16 v[126:129], v[168:171], v[192:195], v[126:129]
	v_mfma_f32_16x16x32_bf16 v[114:117], v[146:149], v[200:203], v[114:117]
	v_mfma_f32_16x16x32_bf16 v[110:113], v[168:171], v[200:203], v[110:113]
	v_mfma_f32_16x16x32_bf16 v[98:101], v[146:149], v[230:233], v[98:101]
	v_mfma_f32_16x16x32_bf16 v[94:97], v[168:171], v[230:233], v[94:97]
	v_mfma_f32_16x16x32_bf16 v[82:85], v[146:149], v[238:241], v[82:85]
	v_mfma_f32_16x16x32_bf16 v[78:81], v[168:171], v[238:241], v[78:81]
	s_setprio 0
	s_setprio 1
	v_mfma_f32_16x16x32_bf16 v[122:125], v[172:175], v[188:191], v[122:125]
	v_mfma_f32_16x16x32_bf16 v[118:121], v[180:183], v[188:191], v[118:121]
	v_mfma_f32_16x16x32_bf16 v[106:109], v[172:175], v[196:199], v[106:109]
	v_mfma_f32_16x16x32_bf16 v[102:105], v[180:183], v[196:199], v[102:105]
	v_mfma_f32_16x16x32_bf16 v[90:93], v[172:175], v[204:207], v[90:93]
	v_mfma_f32_16x16x32_bf16 v[86:89], v[180:183], v[204:207], v[86:89]
	v_mfma_f32_16x16x32_bf16 v[74:77], v[172:175], v[234:237], v[74:77]
	v_mfma_f32_16x16x32_bf16 v[70:73], v[180:183], v[234:237], v[70:73]
	v_mfma_f32_16x16x32_bf16 v[122:125], v[176:179], v[192:195], v[122:125]
	v_mfma_f32_16x16x32_bf16 v[118:121], v[184:187], v[192:195], v[118:121]
	v_mfma_f32_16x16x32_bf16 v[106:109], v[176:179], v[200:203], v[106:109]
	v_mfma_f32_16x16x32_bf16 v[102:105], v[184:187], v[200:203], v[102:105]
	v_mfma_f32_16x16x32_bf16 v[90:93], v[176:179], v[230:233], v[90:93]
	v_mfma_f32_16x16x32_bf16 v[86:89], v[184:187], v[230:233], v[86:89]
	v_mfma_f32_16x16x32_bf16 v[74:77], v[176:179], v[238:241], v[74:77]
	v_mfma_f32_16x16x32_bf16 v[70:73], v[184:187], v[238:241], v[70:73]
	s_setprio 0
	s_barrier
; #define PG8_STAGE(bufoff, gbase, voff) do { _Pragma("unroll") for (int _i = 0; _i < 2; ++_i) \
;         __builtin_amdgcn_global_load_lds((const unsigned*)((const char*)(gbase) + (voff)[_i]), (PG8_LAS unsigned*)(lds + (bufoff) + ldsw + _i * 8192), 16, 0, 0); } while (0)
; #define PG8_LDA(dst, b, h) do { _Pragma("unroll") for (int m = 0; m < 4; ++m) _Pragma("unroll") for (int k = 0; k < 2; ++k) dst[m][k] = *(const PG8_LAS bf16x8*)(lds + PG8_SA(b, h) + aoff + m * 2048 + k * 1024); } while (0)
; #define PG8_MMA(ai, bj, At, Bt) do { __builtin_amdgcn_s_setprio(1); _Pragma("unroll") for (int m = 0; m < 4; ++m) _Pragma("unroll") for (int n = 0; n < 2; ++n) _Pragma("unroll") for (int k = 0; k < 2; ++k) \
;         acc[ai][bj][m][n] = __builtin_amdgcn_mfma_f32_16x16x32_bf16(Bt[n][k], At[m][k], acc[ai][bj][m][n], 0, 0, 0); __builtin_amdgcn_s_setprio(0); } while (0)
; #define PG8_WAIT_V(n) asm volatile("s_waitcnt vmcnt(" #n ")" ::: "memory")
; #define PG8_WAIT_L(n) asm volatile("s_waitcnt lgkmcnt(" #n ")" ::: "memory")
; #define PG8_BAR __builtin_amdgcn_s_barrier()
; #define PG8_SCHED __builtin_amdgcn_sched_barrier(0)
; template <class Epi, class Sched, bool ALIGN_EPI = false, bool SP2 = false>
; __device__ __forceinline__ void gemm_phase(PG8_LAS unsigned char* lds, const Gemm g, const Sched& S, const Epi& E) {
;     ...
;         for (int t = 0; t < nt; t += 2) {
;             const bool last = (t == nt - 2);
;             const char* a1 = cA + (size_t)(t + 1) * kstep;
;             const char* a2 = last ? nA : cA + (size_t)(t + 2) * kstep; const char* b2 = last ? nB : cB + (size_t)(t + 2) * kstep;
;     ...
;             PG8_LDA(At, 1, 1); PG8_STAGE(PG8_SB(1, 0), b3, voffB); PG8_STAGE(PG8_SB(1, 1), b3 + hstep, voffB); PG8_STAGE(PG8_SA(1, 0), a3, voffA);
;             PG8_WAIT_V(8); PG8_WAIT_L(0); PG8_BAR; PG8_MMA(1, 0, At, B0); PG8_MMA(1, 1, At, B1); PG8_BAR; PG8_SCHED;
	s_add_u32 vcc_lo, s24, s2
	s_addc_u32 vcc_hi, s25, s3
	s_add_i32 s26, s67, s30
	s_mov_b32 m0, s26
	ds_read_b128 v[188:191], v163 offset:49152
	ds_read_b128 v[192:195], v163 offset:50176
	ds_read_b128 v[196:199], v163 offset:51200
	ds_read_b128 v[200:203], v163 offset:52224
	ds_read_b128 v[204:207], v163 offset:53248
	ds_read_b128 v[230:233], v163 offset:54272
	ds_read_b128 v[234:237], v163 offset:55296
	ds_read_b128 v[238:241], v163 offset:56320
	global_load_lds_dwordx4 v2, vcc
	s_add_i32 m0, s26, 0x2000
	s_add_u32 s24, s24, 0x80080
	s_addc_u32 s25, s25, 0
	s_add_i32 s26, s69, s30
	global_load_lds_dwordx4 v0, vcc
	s_mov_b32 m0, s26
	s_nop 0
	global_load_lds_dwordx4 v2, s[24:25]
	s_add_i32 m0, s26, 0x2000
	s_nop 0
	global_load_lds_dwordx4 v0, s[24:25]
	v_lshl_add_u64 v[158:159], v[244:245], 0, s[2:3]
	s_mov_b32 m0, s45
	s_nop 0
	global_load_lds_dwordx4 v[158:159], off
	v_lshl_add_u64 v[158:159], v[246:247], 0, s[2:3]
	s_mov_b32 m0, s46
	s_nop 0
	global_load_lds_dwordx4 v[158:159], off
	s_waitcnt vmcnt(8)
	s_waitcnt lgkmcnt(0)
	s_barrier
	s_setprio 1
	s_waitcnt lgkmcnt(0)
	v_mfma_f32_16x16x32_bf16 v[66:69], v[142:145], v[188:191], v[66:69]
	v_mfma_f32_16x16x32_bf16 v[62:65], v[164:167], v[188:191], v[62:65]
	v_mfma_f32_16x16x32_bf16 v[50:53], v[142:145], v[196:199], v[50:53]
	v_mfma_f32_16x16x32_bf16 v[46:49], v[164:167], v[196:199], v[46:49]
	v_mfma_f32_16x16x32_bf16 v[34:37], v[142:145], v[204:207], v[34:37]
	v_mfma_f32_16x16x32_bf16 v[30:33], v[164:167], v[204:207], v[30:33]
	v_mfma_f32_16x16x32_bf16 v[18:21], v[142:145], v[234:237], v[18:21]
	v_mfma_f32_16x16x32_bf16 v[14:17], v[164:167], v[234:237], v[14:17]
	v_mfma_f32_16x16x32_bf16 v[66:69], v[146:149], v[192:195], v[66:69]
	v_mfma_f32_16x16x32_bf16 v[62:65], v[168:171], v[192:195], v[62:65]
	v_mfma_f32_16x16x32_bf16 v[50:53], v[146:149], v[200:203], v[50:53]
	v_mfma_f32_16x16x32_bf16 v[46:49], v[168:171], v[200:203], v[46:49]
	v_mfma_f32_16x16x32_bf16 v[34:37], v[146:149], v[230:233], v[34:37]
	v_mfma_f32_16x16x32_bf16 v[30:33], v[168:171], v[230:233], v[30:33]
	v_mfma_f32_16x16x32_bf16 v[18:21], v[146:149], v[238:241], v[18:21]
	v_mfma_f32_16x16x32_bf16 v[14:17], v[168:171], v[238:241], v[14:17]
	s_setprio 0
	s_setprio 1
	v_mfma_f32_16x16x32_bf16 v[58:61], v[172:175], v[188:191], v[58:61]
	v_mfma_f32_16x16x32_bf16 v[54:57], v[180:183], v[188:191], v[54:57]
	v_mfma_f32_16x16x32_bf16 v[42:45], v[172:175], v[196:199], v[42:45]
	v_mfma_f32_16x16x32_bf16 v[38:41], v[180:183], v[196:199], v[38:41]
	v_mfma_f32_16x16x32_bf16 v[26:29], v[172:175], v[204:207], v[26:29]
	v_mfma_f32_16x16x32_bf16 v[22:25], v[180:183], v[204:207], v[22:25]
	v_mfma_f32_16x16x32_bf16 v[10:13], v[172:175], v[234:237], v[10:13]
	v_mfma_f32_16x16x32_bf16 v[6:9], v[180:183], v[234:237], v[6:9]
	v_mfma_f32_16x16x32_bf16 v[58:61], v[176:179], v[192:195], v[58:61]
	v_mfma_f32_16x16x32_bf16 v[54:57], v[184:187], v[192:195], v[54:57]
	v_mfma_f32_16x16x32_bf16 v[42:45], v[176:179], v[200:203], v[42:45]
	v_mfma_f32_16x16x32_bf16 v[38:41], v[184:187], v[200:203], v[38:41]
	v_mfma_f32_16x16x32_bf16 v[26:29], v[176:179], v[230:233], v[26:29]
	v_mfma_f32_16x16x32_bf16 v[22:25], v[184:187], v[230:233], v[22:25]
	v_mfma_f32_16x16x32_bf16 v[10:13], v[176:179], v[238:241], v[10:13]
	v_mfma_f32_16x16x32_bf16 v[6:9], v[184:187], v[238:241], v[6:9]
	s_setprio 0
	s_barrier
	s_add_i32 s66, s66, 2
	s_add_u32 s52, s52, 0x100
	s_addc_u32 s53, s53, 0
	s_add_u32 s22, s22, 0x100
	s_addc_u32 s23, s23, 0
	s_cmp_gt_u32 s66, 29
	s_cbranch_scc0 .LBB0_1016
	s_and_b64 vcc, exec, s[12:13]
	s_cbranch_vccz .LBB0_1019
	s_barrier

; #define PG8_STAGE(bufoff, gbase, voff) do { _Pragma("unroll") for (int _i = 0; _i < 2; ++_i) \
;         __builtin_amdgcn_global_load_lds((const unsigned*)((const char*)(gbase) + (voff)[_i]), (PG8_LAS unsigned*)(lds + (bufoff) + ldsw + _i * 8192), 16, 0, 0); } while (0)
; #define PG8_LDA(dst, b, h) do { _Pragma("unroll") for (int m = 0; m < 4; ++m) _Pragma("unroll") for (int k = 0; k < 2; ++k) dst[m][k] = *(const PG8_LAS bf16x8*)(lds + PG8_SA(b, h) + aoff + m * 2048 + k * 1024); } while (0)
; #define PG8_LDB(dst, b, h) do { _Pragma("unroll") for (int n = 0; n < 2; ++n) _Pragma("unroll") for (int k = 0; k < 2; ++k) dst[n][k] = *(const PG8_LAS bf16x8*)(lds + PG8_SB(b, h) + boff + n * 2048 + k * 1024); } while (0)
; #define PG8_MMA(ai, bj, At, Bt) do { __builtin_amdgcn_s_setprio(1); _Pragma("unroll") for (int m = 0; m < 4; ++m) _Pragma("unroll") for (int n = 0; n < 2; ++n) _Pragma("unroll") for (int k = 0; k < 2; ++k) \
;         acc[ai][bj][m][n] = __builtin_amdgcn_mfma_f32_16x16x32_bf16(Bt[n][k], At[m][k], acc[ai][bj][m][n], 0, 0, 0); __builtin_amdgcn_s_setprio(0); } while (0)
; #define PG8_WAIT_V(n) asm volatile("s_waitcnt vmcnt(" #n ")" ::: "memory")
; #define PG8_WAIT_L(n) asm volatile("s_waitcnt lgkmcnt(" #n ")" ::: "memory")
; #define PG8_BAR __builtin_amdgcn_s_barrier()
; #define PG8_SCHED __builtin_amdgcn_sched_barrier(0)
; template <class Epi, class Sched, bool ALIGN_EPI = false, bool SP2 = false>
; __device__ __forceinline__ void gemm_phase(PG8_LAS unsigned char* lds, const Gemm g, const Sched& S, const Epi& E) {
;     ...
;             const bool last = (t == nt - 2);
;             const char* a1 = cA + (size_t)(t + 1) * kstep;
;             const char* a2 = last ? nA : cA + (size_t)(t + 2) * kstep; const char* b2 = last ? nB : cB + (size_t)(t + 2) * kstep;
;             const char* a3 = a2 + kstep; const char* b3 = b2 + kstep;
;             if (last && has_next) S.a_ready(nxt);
;             if constexpr (SP2) {
;             PG8_LDB(B0, 0, 0); PG8_LDB(B1, 0, 1); PG8_SCHED; PG8_LDA(At, 0, 0); PG8_STAGE(PG8_SA(1, 1), a1 + hstep, voffA);
;             PG8_WAIT_V(8); PG8_WAIT_L(0); PG8_BAR; PG8_MMA(0, 0, At, B0); PG8_MMA(0, 1, At, B1); PG8_BAR; PG8_SCHED;
;             PG8_LDA(At, 0, 1); PG8_STAGE(PG8_SB(0, 0), b2, voffB); PG8_STAGE(PG8_SB(0, 1), b2 + hstep, voffB); PG8_STAGE(PG8_SA(0, 0), a2, voffA);
.LBB0_1630:
	s_add_u32 s26, s24, 0x100
	s_addc_u32 s27, s25, 0
	s_add_i32 s78, 0, 0x10000
	s_cmp_eq_u32 s71, 28
	s_cselect_b32 s31, s19, s27
	s_cselect_b32 s30, s66, s26
	s_cselect_b32 s29, s17, s70
	s_cselect_b32 s28, s67, s69
	s_add_i32 s79, 0, 0x14000
	v_add_u32_e32 v98, s78, v152
	v_add_u32_e32 v158, s79, v152
	ds_read_b128 v[78:81], v98
	ds_read_b128 v[90:93], v98 offset:1024
	ds_read_b128 v[94:97], v98 offset:2048
	ds_read_b128 v[98:101], v98 offset:3072
	ds_read_b128 v[166:169], v158
	ds_read_b128 v[174:177], v158 offset:1024
	ds_read_b128 v[178:181], v158 offset:2048
	ds_read_b128 v[182:185], v158 offset:3072
	s_add_i32 m0, s45, 0xc000
	ds_read_b128 v[186:189], v173
	ds_read_b128 v[190:193], v173 offset:1024
	ds_read_b128 v[194:197], v173 offset:2048
	ds_read_b128 v[198:201], v173 offset:3072
	ds_read_b128 v[202:205], v173 offset:4096
	ds_read_b128 v[230:233], v173 offset:5120
	ds_read_b128 v[234:237], v173 offset:6144
	ds_read_b128 v[238:241], v173 offset:7168
	global_load_lds_dwordx4 v164, s[24:25]
	s_add_i32 m0, s45, 0xe000
	s_nop 0
	global_load_lds_dwordx4 v162, s[24:25]
	s_waitcnt vmcnt(8)
	s_waitcnt lgkmcnt(0)
	s_barrier
	s_setprio 1
	s_waitcnt lgkmcnt(0)
	v_mfma_f32_16x16x32_bf16 v[146:149], v[78:81], v[186:189], v[146:149]
	v_mfma_f32_16x16x32_bf16 v[142:145], v[94:97], v[186:189], v[142:145]
	v_mfma_f32_16x16x32_bf16 v[130:133], v[78:81], v[194:197], v[130:133]
	v_mfma_f32_16x16x32_bf16 v[126:129], v[94:97], v[194:197], v[126:129]
	v_mfma_f32_16x16x32_bf16 v[114:117], v[78:81], v[202:205], v[114:117]
	v_mfma_f32_16x16x32_bf16 v[110:113], v[94:97], v[202:205], v[110:113]
	v_mfma_f32_16x16x32_bf16 v[86:89], v[78:81], v[234:237], v[86:89]
	v_mfma_f32_16x16x32_bf16 v[82:85], v[94:97], v[234:237], v[82:85]
	v_mfma_f32_16x16x32_bf16 v[146:149], v[90:93], v[190:193], v[146:149]
	v_mfma_f32_16x16x32_bf16 v[142:145], v[98:101], v[190:193], v[142:145]
	v_mfma_f32_16x16x32_bf16 v[130:133], v[90:93], v[198:201], v[130:133]
	v_mfma_f32_16x16x32_bf16 v[126:129], v[98:101], v[198:201], v[126:129]
	v_mfma_f32_16x16x32_bf16 v[114:117], v[90:93], v[230:233], v[114:117]
	v_mfma_f32_16x16x32_bf16 v[110:113], v[98:101], v[230:233], v[110:113]
	v_mfma_f32_16x16x32_bf16 v[86:89], v[90:93], v[238:241], v[86:89]
	v_mfma_f32_16x16x32_bf16 v[82:85], v[98:101], v[238:241], v[82:85]
	s_setprio 0
	s_setprio 1
	v_mfma_f32_16x16x32_bf16 v[138:141], v[166:169], v[186:189], v[138:141]
	v_mfma_f32_16x16x32_bf16 v[134:137], v[178:181], v[186:189], v[134:137]
	v_mfma_f32_16x16x32_bf16 v[122:125], v[166:169], v[194:197], v[122:125]
	v_mfma_f32_16x16x32_bf16 v[118:121], v[178:181], v[194:197], v[118:121]
	v_mfma_f32_16x16x32_bf16 v[106:109], v[166:169], v[202:205], v[106:109]
	v_mfma_f32_16x16x32_bf16 v[102:105], v[178:181], v[202:205], v[102:105]
	v_mfma_f32_16x16x32_bf16 v[74:77], v[166:169], v[234:237], v[74:77]
	v_mfma_f32_16x16x32_bf16 v[70:73], v[178:181], v[234:237], v[70:73]
	v_mfma_f32_16x16x32_bf16 v[138:141], v[174:177], v[190:193], v[138:141]
	v_mfma_f32_16x16x32_bf16 v[134:137], v[182:185], v[190:193], v[134:137]
	v_mfma_f32_16x16x32_bf16 v[122:125], v[174:177], v[198:201], v[122:125]
	v_mfma_f32_16x16x32_bf16 v[118:121], v[182:185], v[198:201], v[118:121]
	v_mfma_f32_16x16x32_bf16 v[106:109], v[174:177], v[230:233], v[106:109]
	v_mfma_f32_16x16x32_bf16 v[102:105], v[182:185], v[230:233], v[102:105]
	v_mfma_f32_16x16x32_bf16 v[74:77], v[174:177], v[238:241], v[74:77]
	v_mfma_f32_16x16x32_bf16 v[70:73], v[182:185], v[238:241], v[70:73]
	s_setprio 0
	s_barrier
	s_add_i32 s24, s78, s44
	s_mov_b32 m0, s24
	ds_read_b128 v[186:189], v173 offset:16384
	ds_read_b128 v[190:193], v173 offset:17408
	ds_read_b128 v[194:197], v173 offset:18432
	ds_read_b128 v[198:201], v173 offset:19456
	ds_read_b128 v[202:205], v173 offset:20480
	ds_read_b128 v[230:233], v173 offset:21504
	ds_read_b128 v[234:237], v173 offset:22528
	ds_read_b128 v[238:241], v173 offset:23552
	global_load_lds_dwordx4 v2, s[28:29]
	s_add_i32 m0, s24, 0x2000
	s_add_u32 s24, s28, 0x80000
	s_addc_u32 s25, s29, 0
	s_add_i32 s78, s79, s44
	global_load_lds_dwordx4 v0, s[28:29]
	s_mov_b32 m0, s78
	s_nop 0
	global_load_lds_dwordx4 v2, s[24:25]
	s_add_i32 m0, s78, 0x2000
	s_nop 0
	global_load_lds_dwordx4 v0, s[24:25]
	s_mov_b32 m0, s45
	s_nop 0
	global_load_lds_dwordx4 v2, s[30:31]
	s_mov_b32 m0, s46
	s_nop 0
	global_load_lds_dwordx4 v0, s[30:31]
	s_waitcnt vmcnt(8)
	s_waitcnt lgkmcnt(0)
	s_barrier
	s_setprio 1
	s_waitcnt lgkmcnt(0)
	v_mfma_f32_16x16x32_bf16 v[66:69], v[78:81], v[186:189], v[66:69]
	v_mfma_f32_16x16x32_bf16 v[62:65], v[94:97], v[186:189], v[62:65]
	v_mfma_f32_16x16x32_bf16 v[50:53], v[78:81], v[194:197], v[50:53]
	v_mfma_f32_16x16x32_bf16 v[46:49], v[94:97], v[194:197], v[46:49]
	v_mfma_f32_16x16x32_bf16 v[34:37], v[78:81], v[202:205], v[34:37]
	v_mfma_f32_16x16x32_bf16 v[30:33], v[94:97], v[202:205], v[30:33]
	v_mfma_f32_16x16x32_bf16 v[18:21], v[78:81], v[234:237], v[18:21]
	v_mfma_f32_16x16x32_bf16 v[14:17], v[94:97], v[234:237], v[14:17]
	v_mfma_f32_16x16x32_bf16 v[66:69], v[90:93], v[190:193], v[66:69]
	v_mfma_f32_16x16x32_bf16 v[62:65], v[98:101], v[190:193], v[62:65]
	v_mfma_f32_16x16x32_bf16 v[50:53], v[90:93], v[198:201], v[50:53]
	v_mfma_f32_16x16x32_bf16 v[46:49], v[98:101], v[198:201], v[46:49]
	v_mfma_f32_16x16x32_bf16 v[34:37], v[90:93], v[230:233], v[34:37]
	v_mfma_f32_16x16x32_bf16 v[30:33], v[98:101], v[230:233], v[30:33]
	v_mfma_f32_16x16x32_bf16 v[18:21], v[90:93], v[238:241], v[18:21]
	v_mfma_f32_16x16x32_bf16 v[14:17], v[98:101], v[238:241], v[14:17]
	s_setprio 0
	s_setprio 1
	v_mfma_f32_16x16x32_bf16 v[58:61], v[166:169], v[186:189], v[58:61]
	v_mfma_f32_16x16x32_bf16 v[54:57], v[178:181], v[186:189], v[54:57]
	v_mfma_f32_16x16x32_bf16 v[42:45], v[166:169], v[194:197], v[42:45]
	v_mfma_f32_16x16x32_bf16 v[38:41], v[178:181], v[194:197], v[38:41]
	v_mfma_f32_16x16x32_bf16 v[26:29], v[166:169], v[202:205], v[26:29]
	v_mfma_f32_16x16x32_bf16 v[22:25], v[178:181], v[202:205], v[22:25]
	v_mfma_f32_16x16x32_bf16 v[10:13], v[166:169], v[234:237], v[10:13]
	v_mfma_f32_16x16x32_bf16 v[6:9], v[178:181], v[234:237], v[6:9]
	v_mfma_f32_16x16x32_bf16 v[58:61], v[174:177], v[190:193], v[58:61]
	v_mfma_f32_16x16x32_bf16 v[54:57], v[182:185], v[190:193], v[54:57]
	v_mfma_f32_16x16x32_bf16 v[42:45], v[174:177], v[198:201], v[42:45]
	v_mfma_f32_16x16x32_bf16 v[38:41], v[182:185], v[198:201], v[38:41]
	v_mfma_f32_16x16x32_bf16 v[26:29], v[174:177], v[230:233], v[26:29]
	v_mfma_f32_16x16x32_bf16 v[22:25], v[182:185], v[230:233], v[22:25]
	v_mfma_f32_16x16x32_bf16 v[10:13], v[174:177], v[238:241], v[10:13]
	v_mfma_f32_16x16x32_bf16 v[6:9], v[182:185], v[238:241], v[6:9]
	s_setprio 0
	s_barrier
; #define PG8_STAGE(bufoff, gbase, voff) do { _Pragma("unroll") for (int _i = 0; _i < 2; ++_i) \
;         __builtin_amdgcn_global_load_lds((const unsigned*)((const char*)(gbase) + (voff)[_i]), (PG8_LAS unsigned*)(lds + (bufoff) + ldsw + _i * 8192), 16, 0, 0); } while (0)
; #define PG8_LDA(dst, b, h) do { _Pragma("unroll") for (int m = 0; m < 4; ++m) _Pragma("unroll") for (int k = 0; k < 2; ++k) dst[m][k] = *(const PG8_LAS bf16x8*)(lds + PG8_SA(b, h) + aoff + m * 2048 + k * 1024); } while (0)
; #define PG8_LDB(dst, b, h) do { _Pragma("unroll") for (int n = 0; n < 2; ++n) _Pragma("unroll") for (int k = 0; k < 2; ++k) dst[n][k] = *(const PG8_LAS bf16x8*)(lds + PG8_SB(b, h) + boff + n * 2048 + k * 1024); } while (0)
; #define PG8_MMA(ai, bj, At, Bt) do { __builtin_amdgcn_s_setprio(1); _Pragma("unroll") for (int m = 0; m < 4; ++m) _Pragma("unroll") for (int n = 0; n < 2; ++n) _Pragma("unroll") for (int k = 0; k < 2; ++k) \
;         acc[ai][bj][m][n] = __builtin_amdgcn_mfma_f32_16x16x32_bf16(Bt[n][k], At[m][k], acc[ai][bj][m][n], 0, 0, 0); __builtin_amdgcn_s_setprio(0); } while (0)
; #define PG8_WAIT_V(n) asm volatile("s_waitcnt vmcnt(" #n ")" ::: "memory")
; #define PG8_WAIT_L(n) asm volatile("s_waitcnt lgkmcnt(" #n ")" ::: "memory")
; #define PG8_BAR __builtin_amdgcn_s_barrier()
; #define PG8_SCHED __builtin_amdgcn_sched_barrier(0)
; template <class Epi, class Sched, bool ALIGN_EPI = false, bool SP2 = false>
; __device__ __forceinline__ void gemm_phase(PG8_LAS unsigned char* lds, const Gemm g, const Sched& S, const Epi& E) {
;     ...
;             PG8_LDB(B0, 1, 0); PG8_LDB(B1, 1, 1); PG8_SCHED; PG8_LDA(At, 1, 0); PG8_STAGE(PG8_SA(0, 1), a2 + hstep, voffA);
;             PG8_WAIT_V(8); PG8_WAIT_L(0); PG8_BAR; PG8_MMA(0, 0, At, B0); PG8_MMA(0, 1, At, B1); PG8_BAR; PG8_SCHED;
;             PG8_LDA(At, 1, 1); PG8_STAGE(PG8_SB(1, 0), b3, voffB); PG8_STAGE(PG8_SB(1, 1), b3 + hstep, voffB); PG8_STAGE(PG8_SA(1, 0), a3, voffA);
;             PG8_WAIT_V(8); PG8_WAIT_L(0); PG8_BAR; PG8_MMA(1, 0, At, B0); PG8_MMA(1, 1, At, B1); PG8_BAR; PG8_SCHED;
	s_add_i32 s78, 0, 0x18000
	s_add_i32 s79, 0, 0x1c000
	v_add_u32_e32 v98, s78, v152
	v_add_u32_e32 v160, s79, v152
	ds_read_b128 v[78:81], v98
	ds_read_b128 v[90:93], v98 offset:1024
	ds_read_b128 v[94:97], v98 offset:2048
	ds_read_b128 v[98:101], v98 offset:3072
	ds_read_b128 v[166:169], v160
	ds_read_b128 v[174:177], v160 offset:1024
	ds_read_b128 v[178:181], v160 offset:2048
	ds_read_b128 v[182:185], v160 offset:3072
	s_add_u32 s24, s30, 0x80000
	s_addc_u32 s25, s31, 0
	s_mov_b32 m0, s47
	ds_read_b128 v[186:189], v173 offset:32768
	ds_read_b128 v[190:193], v173 offset:33792
	ds_read_b128 v[194:197], v173 offset:34816
	ds_read_b128 v[198:201], v173 offset:35840
	ds_read_b128 v[202:205], v173 offset:36864
	ds_read_b128 v[230:233], v173 offset:37888
	ds_read_b128 v[234:237], v173 offset:38912
	ds_read_b128 v[238:241], v173 offset:39936
	global_load_lds_dwordx4 v2, s[24:25]
	s_mov_b32 m0, s48
	s_nop 0
	global_load_lds_dwordx4 v0, s[24:25]
	s_waitcnt vmcnt(8)
	s_waitcnt lgkmcnt(0)
	s_barrier
	s_setprio 1
	s_waitcnt lgkmcnt(0)
	v_mfma_f32_16x16x32_bf16 v[146:149], v[78:81], v[186:189], v[146:149]
	v_mfma_f32_16x16x32_bf16 v[142:145], v[94:97], v[186:189], v[142:145]
	v_mfma_f32_16x16x32_bf16 v[130:133], v[78:81], v[194:197], v[130:133]
	v_mfma_f32_16x16x32_bf16 v[126:129], v[94:97], v[194:197], v[126:129]
	v_mfma_f32_16x16x32_bf16 v[114:117], v[78:81], v[202:205], v[114:117]
	v_mfma_f32_16x16x32_bf16 v[110:113], v[94:97], v[202:205], v[110:113]
	v_mfma_f32_16x16x32_bf16 v[86:89], v[78:81], v[234:237], v[86:89]
	v_mfma_f32_16x16x32_bf16 v[82:85], v[94:97], v[234:237], v[82:85]
	v_mfma_f32_16x16x32_bf16 v[146:149], v[90:93], v[190:193], v[146:149]
	v_mfma_f32_16x16x32_bf16 v[142:145], v[98:101], v[190:193], v[142:145]
	v_mfma_f32_16x16x32_bf16 v[130:133], v[90:93], v[198:201], v[130:133]
	v_mfma_f32_16x16x32_bf16 v[126:129], v[98:101], v[198:201], v[126:129]
	v_mfma_f32_16x16x32_bf16 v[114:117], v[90:93], v[230:233], v[114:117]
	v_mfma_f32_16x16x32_bf16 v[110:113], v[98:101], v[230:233], v[110:113]
	v_mfma_f32_16x16x32_bf16 v[86:89], v[90:93], v[238:241], v[86:89]
	v_mfma_f32_16x16x32_bf16 v[82:85], v[98:101], v[238:241], v[82:85]
	s_setprio 0
	s_setprio 1
	v_mfma_f32_16x16x32_bf16 v[138:141], v[166:169], v[186:189], v[138:141]
	v_mfma_f32_16x16x32_bf16 v[134:137], v[178:181], v[186:189], v[134:137]
	v_mfma_f32_16x16x32_bf16 v[122:125], v[166:169], v[194:197], v[122:125]
	v_mfma_f32_16x16x32_bf16 v[118:121], v[178:181], v[194:197], v[118:121]
	v_mfma_f32_16x16x32_bf16 v[106:109], v[166:169], v[202:205], v[106:109]
	v_mfma_f32_16x16x32_bf16 v[102:105], v[178:181], v[202:205], v[102:105]
	v_mfma_f32_16x16x32_bf16 v[74:77], v[166:169], v[234:237], v[74:77]
	v_mfma_f32_16x16x32_bf16 v[70:73], v[178:181], v[234:237], v[70:73]
	v_mfma_f32_16x16x32_bf16 v[138:141], v[174:177], v[190:193], v[138:141]
	v_mfma_f32_16x16x32_bf16 v[134:137], v[182:185], v[190:193], v[134:137]
	v_mfma_f32_16x16x32_bf16 v[122:125], v[174:177], v[198:201], v[122:125]
	v_mfma_f32_16x16x32_bf16 v[118:121], v[182:185], v[198:201], v[118:121]
	v_mfma_f32_16x16x32_bf16 v[106:109], v[174:177], v[230:233], v[106:109]
	v_mfma_f32_16x16x32_bf16 v[102:105], v[182:185], v[230:233], v[102:105]
	v_mfma_f32_16x16x32_bf16 v[74:77], v[174:177], v[238:241], v[74:77]
	v_mfma_f32_16x16x32_bf16 v[70:73], v[182:185], v[238:241], v[70:73]
	s_setprio 0
	s_barrier
	s_add_u32 vcc_lo, s28, s2
	s_addc_u32 vcc_hi, s29, s3
	s_add_i32 s24, s78, s44
	s_mov_b32 m0, s24
	ds_read_b128 v[186:189], v173 offset:49152
	ds_read_b128 v[190:193], v173 offset:50176
	ds_read_b128 v[194:197], v173 offset:51200
	ds_read_b128 v[198:201], v173 offset:52224
	ds_read_b128 v[202:205], v173 offset:53248
	ds_read_b128 v[230:233], v173 offset:54272
	ds_read_b128 v[234:237], v173 offset:55296
	ds_read_b128 v[238:241], v173 offset:56320
	global_load_lds_dwordx4 v2, vcc
	s_add_i32 m0, s24, 0x2000
	s_add_u32 s24, s28, 0x80080
	s_addc_u32 s25, s29, 0
	s_add_i32 s28, s79, s44
	global_load_lds_dwordx4 v0, vcc
	s_mov_b32 m0, s28
	s_nop 0
	global_load_lds_dwordx4 v2, s[24:25]
	s_add_i32 m0, s28, 0x2000
	s_nop 0
	global_load_lds_dwordx4 v0, s[24:25]
	s_add_u32 vcc_lo, s30, s2
	s_addc_u32 vcc_hi, s31, s3
	s_mov_b32 m0, s49
	s_nop 0
	global_load_lds_dwordx4 v2, vcc
	s_mov_b32 m0, s50
	s_nop 0
	global_load_lds_dwordx4 v0, vcc
	s_waitcnt vmcnt(8)
	s_waitcnt lgkmcnt(0)
	s_barrier
	s_setprio 1
	s_waitcnt lgkmcnt(0)
	v_mfma_f32_16x16x32_bf16 v[66:69], v[78:81], v[186:189], v[66:69]
	v_mfma_f32_16x16x32_bf16 v[62:65], v[94:97], v[186:189], v[62:65]
	v_mfma_f32_16x16x32_bf16 v[50:53], v[78:81], v[194:197], v[50:53]
	v_mfma_f32_16x16x32_bf16 v[46:49], v[94:97], v[194:197], v[46:49]
	v_mfma_f32_16x16x32_bf16 v[34:37], v[78:81], v[202:205], v[34:37]
	v_mfma_f32_16x16x32_bf16 v[30:33], v[94:97], v[202:205], v[30:33]
	v_mfma_f32_16x16x32_bf16 v[18:21], v[78:81], v[234:237], v[18:21]
	v_mfma_f32_16x16x32_bf16 v[14:17], v[94:97], v[234:237], v[14:17]
	v_mfma_f32_16x16x32_bf16 v[66:69], v[90:93], v[190:193], v[66:69]
	v_mfma_f32_16x16x32_bf16 v[62:65], v[98:101], v[190:193], v[62:65]
	v_mfma_f32_16x16x32_bf16 v[50:53], v[90:93], v[198:201], v[50:53]
	v_mfma_f32_16x16x32_bf16 v[46:49], v[98:101], v[198:201], v[46:49]
	v_mfma_f32_16x16x32_bf16 v[34:37], v[90:93], v[230:233], v[34:37]
	v_mfma_f32_16x16x32_bf16 v[30:33], v[98:101], v[230:233], v[30:33]
	v_mfma_f32_16x16x32_bf16 v[18:21], v[90:93], v[238:241], v[18:21]
	v_mfma_f32_16x16x32_bf16 v[14:17], v[98:101], v[238:241], v[14:17]
	s_setprio 0
	s_setprio 1
	v_mfma_f32_16x16x32_bf16 v[58:61], v[166:169], v[186:189], v[58:61]
	v_mfma_f32_16x16x32_bf16 v[54:57], v[178:181], v[186:189], v[54:57]
	v_mfma_f32_16x16x32_bf16 v[42:45], v[166:169], v[194:197], v[42:45]
	v_mfma_f32_16x16x32_bf16 v[38:41], v[178:181], v[194:197], v[38:41]
	v_mfma_f32_16x16x32_bf16 v[26:29], v[166:169], v[202:205], v[26:29]
	v_mfma_f32_16x16x32_bf16 v[22:25], v[178:181], v[202:205], v[22:25]
	v_mfma_f32_16x16x32_bf16 v[10:13], v[166:169], v[234:237], v[10:13]
	v_mfma_f32_16x16x32_bf16 v[6:9], v[178:181], v[234:237], v[6:9]
	v_mfma_f32_16x16x32_bf16 v[58:61], v[174:177], v[190:193], v[58:61]
	v_mfma_f32_16x16x32_bf16 v[54:57], v[182:185], v[190:193], v[54:57]
	v_mfma_f32_16x16x32_bf16 v[42:45], v[174:177], v[198:201], v[42:45]
	v_mfma_f32_16x16x32_bf16 v[38:41], v[182:185], v[198:201], v[38:41]
	v_mfma_f32_16x16x32_bf16 v[26:29], v[174:177], v[230:233], v[26:29]
	v_mfma_f32_16x16x32_bf16 v[22:25], v[182:185], v[230:233], v[22:25]
	v_mfma_f32_16x16x32_bf16 v[10:13], v[174:177], v[238:241], v[10:13]
	v_mfma_f32_16x16x32_bf16 v[6:9], v[182:185], v[238:241], v[6:9]
	s_setprio 0
	s_barrier
;     __device__ __forceinline__ void operator()(const f32x4 (&acc)[2][2][4][2], const Unit& u, int wr, int wc, int fr, int fq) const {
;         const int row0 = u.pm * BM + wr * 64 + fr; const int col0 = u.pn * BM + wc * 32 + 4 * fq;
;         f32x4 gv[2][2];
; #pragma unroll
;         for (int bj = 0; bj < 2; ++bj)
; #pragma unroll
;             for (int n = 0; n < 2; ++n) gv[bj][n] = xg ? *(const f32x4*)(gn + col0 + bj * HALF + n * 16) : (f32x4){0.f, 0.f, 0.f, 0.f};
; #pragma unroll
;         for (int ai = 0; ai < 2; ++ai)
; #pragma unroll
;             for (int m = 0; m < 4; ++m) { const size_t off = (size_t)(row0 + ai * HALF + m * 16) * ldc + col0; float ss = 0.f;
; #pragma unroll
;                 for (int bj = 0; bj < 2; ++bj)
; #pragma unroll
;                     for (int n = 0; n < 2; ++n) { const f32x4 bs = *(const f32x4*)(base + off + bj * HALF + n * 16); const f32x4 o = bs + acc[ai][bj][m][n] * scale;
;                         *(f32x4*)(out + off + bj * HALF + n * 16) = o;
;                         if (xg) { ss += (o[0] * o[0] + o[1] * o[1]) + (o[2] * o[2] + o[3] * o[3]); const f32x4 og = o * gv[bj][n];
;                             typedef unsigned u32x2v __attribute__((ext_vector_type(2))); u32x2v w; w.x = cvt_pk_bf16(og[0], og[1]); w.y = cvt_pk_bf16(og[2], og[3]); *(u32x2v*)(xg + off + bj * HALF + n * 16) = w; } }
;                 if (xg) { ss += __shfl_xor(ss, 16); ss += __shfl_xor(ss, 32); if (fq == 0) atomicAdd(rowss + row0 + ai * HALF + m * 16, (rowss_t)(ss * 16777216.0f)); } }
	s_add_i32 s71, s71, 2
	s_add_u32 s69, s69, 0x100
	s_addc_u32 s70, s70, 0
	s_cmp_gt_u32 s71, 29
	s_mov_b64 s[24:25], s[26:27]
	s_cbranch_scc0 .LBB0_1630
	v_lshl_add_u32 v170, s52, 8, v5
	v_lshl_or_b32 v168, s53, 8, v172
	v_ashrrev_i32_e32 v171, 31, v170
	v_ashrrev_i32_e32 v169, 31, v168
	v_readlane_b32 s72, v254, 12
	v_lshlrev_b64 v[158:159], 11, v[170:171]
	v_readlane_b32 s82, v254, 22
	v_readlane_b32 s83, v254, 23
	v_lshl_add_u64 v[166:167], v[158:159], 0, v[168:169]
	v_lshl_add_u64 v[158:159], v[166:167], 2, s[10:11]
	v_lshl_add_u64 v[78:79], v[168:169], 2, s[82:83]
	global_load_dwordx4 v[98:101], v[78:79], off
	global_load_dwordx4 v[94:97], v[78:79], off offset:64
	global_load_dwordx4 v[90:93], v[78:79], off offset:512
	s_nop 0
	global_load_dwordx4 v[78:81], v[78:79], off offset:576
	v_readlane_b32 s73, v254, 13
	global_load_dwordx4 v[174:177], v[158:159], off
	global_load_dwordx4 v[182:185], v[158:159], off offset:64
	global_load_dwordx4 v[186:189], v[158:159], off offset:512
	global_load_dwordx4 v[190:193], v[158:159], off offset:576
	v_readlane_b32 s74, v254, 14
	v_readlane_b32 s75, v254, 15
	v_readlane_b32 s76, v254, 16
	v_readlane_b32 s77, v254, 17
	v_readlane_b32 s78, v254, 18
	v_readlane_b32 s79, v254, 19
	v_readlane_b32 s80, v254, 20
	v_readlane_b32 s81, v254, 21
	v_readlane_b32 s84, v254, 24
	v_readlane_b32 s85, v254, 25
	v_readlane_b32 s86, v254, 26
	v_readlane_b32 s87, v254, 27
	s_waitcnt vmcnt(3) lgkmcnt(0)
	v_pk_add_f32 v[148:149], v[148:149], v[176:177]
	v_pk_add_f32 v[146:147], v[146:147], v[174:175]
	v_mul_f32_e32 v161, v149, v149
	v_mul_f32_e32 v160, v147, v147
	global_store_dwordx4 v[158:159], v[146:149], off
	v_fmac_f32_e32 v160, v146, v146
	v_fmac_f32_e32 v161, v148, v148
	v_pk_mul_f32 v[148:149], v[100:101], v[148:149]
	v_pk_mul_f32 v[146:147], v[98:99], v[146:147]
	v_lshl_add_u64 v[174:175], v[166:167], 1, s[12:13]
	v_cvt_pk_bf16_f32 v146, v146, v147
	v_cvt_pk_bf16_f32 v147, v148, v149
	global_store_dwordx2 v[174:175], v[146:147], off
	v_add_f32_e32 v160, v160, v161
	s_waitcnt vmcnt(4) lgkmcnt(0)
	v_pk_add_f32 v[144:145], v[144:145], v[184:185]
	v_pk_add_f32 v[142:143], v[142:143], v[182:183]
	v_mul_f32_e32 v147, v145, v145
	v_mul_f32_e32 v146, v143, v143
	global_store_dwordx4 v[158:159], v[142:145], off offset:64
	v_fmac_f32_e32 v146, v142, v142
	v_fmac_f32_e32 v147, v144, v144
	v_pk_mul_f32 v[144:145], v[96:97], v[144:145]
	v_pk_mul_f32 v[142:143], v[94:95], v[142:143]
	v_add_f32_e32 v146, v146, v147
	v_cvt_pk_bf16_f32 v142, v142, v143
	v_cvt_pk_bf16_f32 v143, v144, v145
	global_store_dwordx2 v[174:175], v[142:143], off offset:32
	v_add_f32_e32 v146, v160, v146
	s_waitcnt vmcnt(5) lgkmcnt(0)
	v_pk_add_f32 v[140:141], v[140:141], v[188:189]
	v_pk_add_f32 v[138:139], v[138:139], v[186:187]
	v_mul_f32_e32 v143, v141, v141
	v_mul_f32_e32 v142, v139, v139
	global_store_dwordx4 v[158:159], v[138:141], off offset:512
	v_fmac_f32_e32 v142, v138, v138
	v_fmac_f32_e32 v143, v140, v140
	v_pk_mul_f32 v[140:141], v[92:93], v[140:141]
	v_pk_mul_f32 v[138:139], v[90:91], v[138:139]
	v_add_f32_e32 v142, v142, v143
	v_cvt_pk_bf16_f32 v138, v138, v139
	v_cvt_pk_bf16_f32 v139, v140, v141
	global_store_dwordx2 v[174:175], v[138:139], off offset:256
	v_add_f32_e32 v142, v146, v142
	s_waitcnt vmcnt(6) lgkmcnt(0)
	v_pk_add_f32 v[136:137], v[136:137], v[192:193]
	v_pk_add_f32 v[134:135], v[134:135], v[190:191]
	global_store_dwordx4 v[158:159], v[134:137], off offset:576
	v_pk_mul_f32 v[140:141], v[78:79], v[134:135]
	v_pk_mul_f32 v[138:139], v[80:81], v[136:137]
	v_mul_f32_e32 v135, v135, v135
	v_fmac_f32_e32 v135, v134, v134
	v_mul_f32_e32 v134, v137, v137
	v_fmac_f32_e32 v134, v136, v136
	v_and_b32_e32 v136, 64, v218
	v_add_f32_e32 v134, v135, v134
	v_xor_b32_e32 v135, 16, v218
	v_add_u32_e32 v137, 64, v136
	v_cmp_lt_i32_e32 vcc, v135, v137
	v_add_f32_e32 v134, v142, v134
	v_cvt_pk_bf16_f32 v140, v140, v141
	v_cndmask_b32_e32 v135, v218, v135, vcc
	v_lshlrev_b32_e32 v136, 2, v135
	ds_bpermute_b32 v135, v136, v134
	v_cvt_pk_bf16_f32 v141, v138, v139
	global_store_dwordx2 v[174:175], v[140:141], off offset:288
	s_waitcnt lgkmcnt(0)
	v_add_f32_e32 v138, v134, v135
	v_xor_b32_e32 v134, 32, v218
	v_cmp_lt_i32_e32 vcc, v134, v137
	s_nop 1
	v_cndmask_b32_e32 v134, v218, v134, vcc
	v_lshlrev_b32_e32 v137, 2, v134
	ds_bpermute_b32 v139, v137, v138
	v_lshl_add_u64 v[134:135], v[170:171], 3, s[14:15]
	s_and_saveexec_b64 s[24:25], s[6:7]
	s_cbranch_execz .LBB0_1633
	s_waitcnt lgkmcnt(0)
	v_add_f32_e32 v138, v138, v139
	v_mul_f32_e32 v138, 0x4b800000, v138
	v_trunc_f32_e32 v138, v138
	v_mul_f32_e32 v139, 0x2f800000, v138
	v_floor_f32_e32 v139, v139
	v_fmac_f32_e32 v138, 0xcf800000, v139
	v_cvt_u32_f32_e32 v138, v138
	v_cvt_u32_f32_e32 v139, v139
	global_atomic_add_x2 v[134:135], v[138:139], off
